# GEMM K-loops: the two end-of-load-segment waits (vmcnt(8), lgkmcnt(0)) merged into one s_waitcnt
# speedup vs baseline: 1.0018x; 1.0014x over previous
; #define PG8_STAGE(bufoff, gbase, voff) do { _Pragma("unroll") for (int _i = 0; _i < 2; ++_i) \
;         __builtin_amdgcn_global_load_lds((const unsigned*)((const char*)(gbase) + (voff)[_i]), (LAS unsigned*)(lds + (bufoff) + ldsw + _i * 8192), 16, 0, 0); } while (0)
; #define PG8_LDA(dst, b, h) do { _Pragma("unroll") for (int m = 0; m < 4; ++m) _Pragma("unroll") for (int k = 0; k < 2; ++k) dst[m][k] = *(const LAS bf16x8*)(lds + PG8_SA(b, h) + aoff + m * 2048 + k * 1024); } while (0)
; #define PG8_LDB(dst, b, h) do { _Pragma("unroll") for (int n = 0; n < 2; ++n) _Pragma("unroll") for (int k = 0; k < 2; ++k) dst[n][k] = *(const LAS bf16x8*)(lds + PG8_SB(b, h) + boff + n * 2048 + k * 1024); } while (0)
; #define PG8_WAIT_V(n) asm volatile("s_waitcnt vmcnt(" #n ")" ::: "memory")
; #define PG8_WAIT_L(n) asm volatile("s_waitcnt lgkmcnt(" #n ")" ::: "memory")
; #define PG8_BAR __builtin_amdgcn_s_barrier()
; #define PG8_SCHED __builtin_amdgcn_sched_barrier(0)
; template <class Epi, class Sched, bool ALIGN_EPI, bool LAST_FUSED = false, bool PERM = false, bool CARRY = false>
; __device__ __forceinline__ void gemm_phase(LAS unsigned char* lds, const int tid, const int K, const int lda, const int ldb, const Sched& S, const Epi& E) {
;     ...
;         const bool has_next = S.next(KD_IDX(ui + 1), nxt);
;         const char* nA = has_next ? nxt.a : cA; const char* nB = has_next ? nxt.b : cB; const int nt = cur.nt;
; #pragma unroll 1
;         for (int t = 0; t < nt; t += 2) {
;             const bool last = (t == nt - 2);
;             const char* a1 = cA + (size_t)(t + 1) * kstep;
;             const char* a2 = last ? nA : cA + (size_t)(t + 2) * kstep; const char* b2 = last ? nB : cB + (size_t)(t + 2) * kstep;
;             const char* a3 = a2 + kstep; const char* b3 = b2 + kstep;
;             PG8_LDB(B0, 0, 0); PG8_LDB(B1, 0, 1); PG8_SCHED; PG8_LDA(At, 0, 0); PG8_STAGE(PG8_SA(1, 1), a1 + hstepA, voffA);
;             PG8_WAIT_V(8); PG8_WAIT_L(0); PG8_BAR; PG8_MMA(0, 0, At, B0); PG8_MMA(0, 1, At, B1); PG8_BAR; PG8_SCHED;
;             PG8_LDA(At, 0, 1); PG8_STAGE(PG8_SB(0, 0), b2, voffB); PG8_STAGE(PG8_SB(0, 1), b2 + hstepB, voffB); PG8_STAGE(PG8_SA(0, 0), a2, voffA);
;             PG8_WAIT_V(8); PG8_WAIT_L(0); PG8_BAR; PG8_MMA(1, 0, At, B0); PG8_MMA(1, 1, At, B1); PG8_BAR; PG8_SCHED;
.LBB0_279:
	s_add_u32 s4, s2, 0xfff80080
	s_addc_u32 s5, s3, -1
	s_add_i32 s28, 0, 0x10000
	s_cmp_eq_u32 s27, 28
	s_cselect_b32 s37, s43, s5
	s_cselect_b32 s36, s42, s4
	s_cselect_b32 s5, s71, s23
	s_cselect_b32 s4, s70, s22
	s_add_i32 s31, 0, 0x14000
	v_add_u32_e32 v154, s28, v144
	v_add_u32_e32 v170, s31, v144
	ds_read_b128 v[136:139], v154
	ds_read_b128 v[146:149], v154 offset:1024
	ds_read_b128 v[150:153], v154 offset:2048
	ds_read_b128 v[154:157], v154 offset:3072
	ds_read_b128 v[158:161], v170
	ds_read_b128 v[162:165], v170 offset:1024
	ds_read_b128 v[166:169], v170 offset:2048
	ds_read_b128 v[170:173], v170 offset:3072
	v_lshl_add_u64 v[206:207], s[2:3], 0, v[132:133]
	s_add_i32 m0, s52, 0xc000
	ds_read_b128 v[174:177], v145
	ds_read_b128 v[178:181], v145 offset:1024
	ds_read_b128 v[182:185], v145 offset:2048
	ds_read_b128 v[186:189], v145 offset:3072
	ds_read_b128 v[190:193], v145 offset:4096
	ds_read_b128 v[194:197], v145 offset:5120
	ds_read_b128 v[198:201], v145 offset:6144
	ds_read_b128 v[202:205], v145 offset:7168
	global_load_lds_dwordx4 v[206:207], off
	v_lshl_add_u64 v[206:207], s[2:3], 0, v[134:135]
	s_add_i32 m0, s52, 0xe000
	s_nop 0
	global_load_lds_dwordx4 v[206:207], off
	s_waitcnt vmcnt(8) lgkmcnt(0)
	s_barrier
	s_setprio 1
	v_mfma_f32_16x16x32_bf16 v[126:129], v[136:139], v[174:177], v[126:129]
	v_mfma_f32_16x16x32_bf16 v[122:125], v[150:153], v[174:177], v[122:125]
	v_mfma_f32_16x16x32_bf16 v[110:113], v[136:139], v[182:185], v[110:113]
	v_mfma_f32_16x16x32_bf16 v[106:109], v[150:153], v[182:185], v[106:109]
	v_mfma_f32_16x16x32_bf16 v[94:97], v[136:139], v[190:193], v[94:97]
	v_mfma_f32_16x16x32_bf16 v[90:93], v[150:153], v[190:193], v[90:93]
	v_mfma_f32_16x16x32_bf16 v[78:81], v[136:139], v[198:201], v[78:81]
	v_mfma_f32_16x16x32_bf16 v[74:77], v[150:153], v[198:201], v[74:77]
	v_mfma_f32_16x16x32_bf16 v[126:129], v[146:149], v[178:181], v[126:129]
	v_mfma_f32_16x16x32_bf16 v[122:125], v[154:157], v[178:181], v[122:125]
	v_mfma_f32_16x16x32_bf16 v[110:113], v[146:149], v[186:189], v[110:113]
	v_mfma_f32_16x16x32_bf16 v[106:109], v[154:157], v[186:189], v[106:109]
	v_mfma_f32_16x16x32_bf16 v[94:97], v[146:149], v[194:197], v[94:97]
	v_mfma_f32_16x16x32_bf16 v[90:93], v[154:157], v[194:197], v[90:93]
	v_mfma_f32_16x16x32_bf16 v[78:81], v[146:149], v[202:205], v[78:81]
	v_mfma_f32_16x16x32_bf16 v[74:77], v[154:157], v[202:205], v[74:77]
	s_setprio 0
	s_setprio 1
	v_mfma_f32_16x16x32_bf16 v[118:121], v[158:161], v[174:177], v[118:121]
	v_mfma_f32_16x16x32_bf16 v[114:117], v[166:169], v[174:177], v[114:117]
	v_mfma_f32_16x16x32_bf16 v[102:105], v[158:161], v[182:185], v[102:105]
	v_mfma_f32_16x16x32_bf16 v[98:101], v[166:169], v[182:185], v[98:101]
	v_mfma_f32_16x16x32_bf16 v[86:89], v[158:161], v[190:193], v[86:89]
	v_mfma_f32_16x16x32_bf16 v[82:85], v[166:169], v[190:193], v[82:85]
	v_mfma_f32_16x16x32_bf16 v[70:73], v[158:161], v[198:201], v[70:73]
	v_mfma_f32_16x16x32_bf16 v[66:69], v[166:169], v[198:201], v[66:69]
	v_mfma_f32_16x16x32_bf16 v[118:121], v[162:165], v[178:181], v[118:121]
	v_mfma_f32_16x16x32_bf16 v[114:117], v[170:173], v[178:181], v[114:117]
	v_mfma_f32_16x16x32_bf16 v[102:105], v[162:165], v[186:189], v[102:105]
	v_mfma_f32_16x16x32_bf16 v[98:101], v[170:173], v[186:189], v[98:101]
	v_mfma_f32_16x16x32_bf16 v[86:89], v[162:165], v[194:197], v[86:89]
	v_mfma_f32_16x16x32_bf16 v[82:85], v[170:173], v[194:197], v[82:85]
	v_mfma_f32_16x16x32_bf16 v[70:73], v[162:165], v[202:205], v[70:73]
	v_mfma_f32_16x16x32_bf16 v[66:69], v[170:173], v[202:205], v[66:69]
	s_barrier
	s_setprio 0
	s_add_i32 s28, s28, s51
	v_lshl_add_u64 v[206:207], s[4:5], 0, v[0:1]
	s_mov_b32 m0, s28
	ds_read_b128 v[174:177], v145 offset:16384
	ds_read_b128 v[178:181], v145 offset:17408
	ds_read_b128 v[182:185], v145 offset:18432
	ds_read_b128 v[186:189], v145 offset:19456
	ds_read_b128 v[190:193], v145 offset:20480
	ds_read_b128 v[194:197], v145 offset:21504
	ds_read_b128 v[198:201], v145 offset:22528
	ds_read_b128 v[202:205], v145 offset:23552
	global_load_lds_dwordx4 v[206:207], off
	s_add_i32 m0, s28, 0x2000
	s_add_u32 s28, s4, 0x80000
	v_lshl_add_u64 v[208:209], s[4:5], 0, v[130:131]
	s_addc_u32 s29, s5, 0
	s_add_i32 s31, s31, s51
	global_load_lds_dwordx4 v[208:209], off
	v_lshl_add_u64 v[210:211], s[28:29], 0, v[0:1]
	s_mov_b32 m0, s31
	v_lshl_add_u64 v[212:213], s[36:37], 0, v[130:131]
	global_load_lds_dwordx4 v[210:211], off
	v_lshl_add_u64 v[210:211], s[28:29], 0, v[130:131]
	s_add_i32 m0, s31, 0x2000
	s_nop 0
	global_load_lds_dwordx4 v[210:211], off
	v_lshl_add_u64 v[210:211], s[36:37], 0, v[0:1]
	s_mov_b32 m0, s52
	s_nop 0
	global_load_lds_dwordx4 v[210:211], off
	s_mov_b32 m0, s53
	s_nop 0
	global_load_lds_dwordx4 v[212:213], off
	s_waitcnt vmcnt(8) lgkmcnt(0)
	s_barrier
; #define PG8_STAGE(bufoff, gbase, voff) do { _Pragma("unroll") for (int _i = 0; _i < 2; ++_i) \
;         __builtin_amdgcn_global_load_lds((const unsigned*)((const char*)(gbase) + (voff)[_i]), (LAS unsigned*)(lds + (bufoff) + ldsw + _i * 8192), 16, 0, 0); } while (0)
; #define PG8_LDA(dst, b, h) do { _Pragma("unroll") for (int m = 0; m < 4; ++m) _Pragma("unroll") for (int k = 0; k < 2; ++k) dst[m][k] = *(const LAS bf16x8*)(lds + PG8_SA(b, h) + aoff + m * 2048 + k * 1024); } while (0)
; #define PG8_LDB(dst, b, h) do { _Pragma("unroll") for (int n = 0; n < 2; ++n) _Pragma("unroll") for (int k = 0; k < 2; ++k) dst[n][k] = *(const LAS bf16x8*)(lds + PG8_SB(b, h) + boff + n * 2048 + k * 1024); } while (0)
; #define PG8_MMA(ai, bj, At, Bt) do { __builtin_amdgcn_s_setprio(1); _Pragma("unroll") for (int m = 0; m < 4; ++m) _Pragma("unroll") for (int n = 0; n < 2; ++n) _Pragma("unroll") for (int k = 0; k < 2; ++k) \
;         acc[ai][bj][m][n] = __builtin_amdgcn_mfma_f32_16x16x32_bf16(Bt[n][k], At[m][k], acc[ai][bj][m][n], 0, 0, 0); __builtin_amdgcn_s_setprio(0); } while (0)
; #define PG8_WAIT_V(n) asm volatile("s_waitcnt vmcnt(" #n ")" ::: "memory")
; #define PG8_WAIT_L(n) asm volatile("s_waitcnt lgkmcnt(" #n ")" ::: "memory")
; #define PG8_BAR __builtin_amdgcn_s_barrier()
; #define PG8_SCHED __builtin_amdgcn_sched_barrier(0)
; template <class Epi, class Sched, bool ALIGN_EPI, bool LAST_FUSED = false, bool PERM = false, bool CARRY = false>
; __device__ __forceinline__ void gemm_phase(LAS unsigned char* lds, const int tid, const int K, const int lda, const int ldb, const Sched& S, const Epi& E) {
;     ...
;             PG8_WAIT_V(8); PG8_WAIT_L(0); PG8_BAR; PG8_MMA(1, 0, At, B0); PG8_MMA(1, 1, At, B1); PG8_BAR; PG8_SCHED;
;             PG8_LDB(B0, 1, 0); PG8_LDB(B1, 1, 1); PG8_SCHED; PG8_LDA(At, 1, 0); PG8_STAGE(PG8_SA(0, 1), a2 + hstepA, voffA);
;             PG8_WAIT_V(8); PG8_WAIT_L(0); PG8_BAR; PG8_MMA(0, 0, At, B0); PG8_MMA(0, 1, At, B1); PG8_BAR; PG8_SCHED;
	s_setprio 1
	v_mfma_f32_16x16x32_bf16 v[62:65], v[136:139], v[174:177], v[62:65]
	v_mfma_f32_16x16x32_bf16 v[58:61], v[150:153], v[174:177], v[58:61]
	v_mfma_f32_16x16x32_bf16 v[46:49], v[136:139], v[182:185], v[46:49]
	v_mfma_f32_16x16x32_bf16 v[42:45], v[150:153], v[182:185], v[42:45]
	v_mfma_f32_16x16x32_bf16 v[30:33], v[136:139], v[190:193], v[30:33]
	v_mfma_f32_16x16x32_bf16 v[26:29], v[150:153], v[190:193], v[26:29]
	v_mfma_f32_16x16x32_bf16 v[14:17], v[136:139], v[198:201], v[14:17]
	v_mfma_f32_16x16x32_bf16 v[10:13], v[150:153], v[198:201], v[10:13]
	v_mfma_f32_16x16x32_bf16 v[62:65], v[146:149], v[178:181], v[62:65]
	v_mfma_f32_16x16x32_bf16 v[58:61], v[154:157], v[178:181], v[58:61]
	v_mfma_f32_16x16x32_bf16 v[46:49], v[146:149], v[186:189], v[46:49]
	v_mfma_f32_16x16x32_bf16 v[42:45], v[154:157], v[186:189], v[42:45]
	v_mfma_f32_16x16x32_bf16 v[30:33], v[146:149], v[194:197], v[30:33]
	v_mfma_f32_16x16x32_bf16 v[26:29], v[154:157], v[194:197], v[26:29]
	v_mfma_f32_16x16x32_bf16 v[14:17], v[146:149], v[202:205], v[14:17]
	v_mfma_f32_16x16x32_bf16 v[10:13], v[154:157], v[202:205], v[10:13]
	s_setprio 0
	s_setprio 1
	v_mfma_f32_16x16x32_bf16 v[54:57], v[158:161], v[174:177], v[54:57]
	v_mfma_f32_16x16x32_bf16 v[50:53], v[166:169], v[174:177], v[50:53]
	v_mfma_f32_16x16x32_bf16 v[38:41], v[158:161], v[182:185], v[38:41]
	v_mfma_f32_16x16x32_bf16 v[34:37], v[166:169], v[182:185], v[34:37]
	v_mfma_f32_16x16x32_bf16 v[22:25], v[158:161], v[190:193], v[22:25]
	v_mfma_f32_16x16x32_bf16 v[18:21], v[166:169], v[190:193], v[18:21]
	v_mfma_f32_16x16x32_bf16 v[6:9], v[158:161], v[198:201], v[6:9]
	v_mfma_f32_16x16x32_bf16 v[2:5], v[166:169], v[198:201], v[2:5]
	v_mfma_f32_16x16x32_bf16 v[54:57], v[162:165], v[178:181], v[54:57]
	v_mfma_f32_16x16x32_bf16 v[50:53], v[170:173], v[178:181], v[50:53]
	v_mfma_f32_16x16x32_bf16 v[38:41], v[162:165], v[186:189], v[38:41]
	v_mfma_f32_16x16x32_bf16 v[34:37], v[170:173], v[186:189], v[34:37]
	v_mfma_f32_16x16x32_bf16 v[22:25], v[162:165], v[194:197], v[22:25]
	v_mfma_f32_16x16x32_bf16 v[18:21], v[170:173], v[194:197], v[18:21]
	v_mfma_f32_16x16x32_bf16 v[6:9], v[162:165], v[202:205], v[6:9]
	v_mfma_f32_16x16x32_bf16 v[2:5], v[170:173], v[202:205], v[2:5]
	s_barrier
	s_setprio 0
	s_add_i32 s31, 0, 0x18000
	s_add_i32 s35, 0, 0x1c000
	v_add_u32_e32 v154, s31, v144
	v_add_u32_e32 v170, s35, v144
	ds_read_b128 v[136:139], v154
	ds_read_b128 v[146:149], v154 offset:1024
	ds_read_b128 v[150:153], v154 offset:2048
	ds_read_b128 v[154:157], v154 offset:3072
	ds_read_b128 v[158:161], v170
	ds_read_b128 v[162:165], v170 offset:1024
	ds_read_b128 v[166:169], v170 offset:2048
	ds_read_b128 v[170:173], v170 offset:3072
	s_add_u32 s28, s36, 0x80000
	s_addc_u32 s29, s37, 0
	s_mov_b32 m0, s54
	v_lshl_add_u64 v[214:215], s[28:29], 0, v[0:1]
	ds_read_b128 v[174:177], v145 offset:32768
	ds_read_b128 v[178:181], v145 offset:33792
	ds_read_b128 v[182:185], v145 offset:34816
	ds_read_b128 v[186:189], v145 offset:35840
	ds_read_b128 v[190:193], v145 offset:36864
	ds_read_b128 v[194:197], v145 offset:37888
	ds_read_b128 v[198:201], v145 offset:38912
	ds_read_b128 v[202:205], v145 offset:39936
	global_load_lds_dwordx4 v[214:215], off
	v_lshl_add_u64 v[214:215], s[28:29], 0, v[130:131]
	s_mov_b32 m0, s55
	s_nop 0
	global_load_lds_dwordx4 v[214:215], off
	s_waitcnt vmcnt(8) lgkmcnt(0)
	s_barrier
	s_setprio 1
	v_mfma_f32_16x16x32_bf16 v[126:129], v[136:139], v[174:177], v[126:129]
	v_mfma_f32_16x16x32_bf16 v[122:125], v[150:153], v[174:177], v[122:125]
	v_mfma_f32_16x16x32_bf16 v[110:113], v[136:139], v[182:185], v[110:113]
	v_mfma_f32_16x16x32_bf16 v[106:109], v[150:153], v[182:185], v[106:109]
	v_mfma_f32_16x16x32_bf16 v[94:97], v[136:139], v[190:193], v[94:97]
	v_mfma_f32_16x16x32_bf16 v[90:93], v[150:153], v[190:193], v[90:93]
	v_mfma_f32_16x16x32_bf16 v[78:81], v[136:139], v[198:201], v[78:81]
	v_mfma_f32_16x16x32_bf16 v[74:77], v[150:153], v[198:201], v[74:77]
	v_mfma_f32_16x16x32_bf16 v[126:129], v[146:149], v[178:181], v[126:129]
	v_mfma_f32_16x16x32_bf16 v[122:125], v[154:157], v[178:181], v[122:125]
	v_mfma_f32_16x16x32_bf16 v[110:113], v[146:149], v[186:189], v[110:113]
	v_mfma_f32_16x16x32_bf16 v[106:109], v[154:157], v[186:189], v[106:109]
	v_mfma_f32_16x16x32_bf16 v[94:97], v[146:149], v[194:197], v[94:97]
	v_mfma_f32_16x16x32_bf16 v[90:93], v[154:157], v[194:197], v[90:93]
	v_mfma_f32_16x16x32_bf16 v[78:81], v[146:149], v[202:205], v[78:81]
	v_mfma_f32_16x16x32_bf16 v[74:77], v[154:157], v[202:205], v[74:77]
	s_setprio 0
	s_setprio 1
	v_mfma_f32_16x16x32_bf16 v[118:121], v[158:161], v[174:177], v[118:121]
	v_mfma_f32_16x16x32_bf16 v[114:117], v[166:169], v[174:177], v[114:117]
	v_mfma_f32_16x16x32_bf16 v[102:105], v[158:161], v[182:185], v[102:105]
	v_mfma_f32_16x16x32_bf16 v[98:101], v[166:169], v[182:185], v[98:101]
	v_mfma_f32_16x16x32_bf16 v[86:89], v[158:161], v[190:193], v[86:89]
	v_mfma_f32_16x16x32_bf16 v[82:85], v[166:169], v[190:193], v[82:85]
	v_mfma_f32_16x16x32_bf16 v[70:73], v[158:161], v[198:201], v[70:73]
	v_mfma_f32_16x16x32_bf16 v[66:69], v[166:169], v[198:201], v[66:69]
	v_mfma_f32_16x16x32_bf16 v[118:121], v[162:165], v[178:181], v[118:121]
	v_mfma_f32_16x16x32_bf16 v[114:117], v[170:173], v[178:181], v[114:117]
	v_mfma_f32_16x16x32_bf16 v[102:105], v[162:165], v[186:189], v[102:105]
	v_mfma_f32_16x16x32_bf16 v[98:101], v[170:173], v[186:189], v[98:101]
	v_mfma_f32_16x16x32_bf16 v[86:89], v[162:165], v[194:197], v[86:89]
	v_mfma_f32_16x16x32_bf16 v[82:85], v[170:173], v[194:197], v[82:85]
	v_mfma_f32_16x16x32_bf16 v[70:73], v[162:165], v[202:205], v[70:73]
	v_mfma_f32_16x16x32_bf16 v[66:69], v[170:173], v[202:205], v[66:69]
	s_barrier
; #define PG8_STAGE(bufoff, gbase, voff) do { _Pragma("unroll") for (int _i = 0; _i < 2; ++_i) \
;         __builtin_amdgcn_global_load_lds((const unsigned*)((const char*)(gbase) + (voff)[_i]), (LAS unsigned*)(lds + (bufoff) + ldsw + _i * 8192), 16, 0, 0); } while (0)
; #define PG8_LDA(dst, b, h) do { _Pragma("unroll") for (int m = 0; m < 4; ++m) _Pragma("unroll") for (int k = 0; k < 2; ++k) dst[m][k] = *(const LAS bf16x8*)(lds + PG8_SA(b, h) + aoff + m * 2048 + k * 1024); } while (0)
; #define PG8_MMA(ai, bj, At, Bt) do { __builtin_amdgcn_s_setprio(1); _Pragma("unroll") for (int m = 0; m < 4; ++m) _Pragma("unroll") for (int n = 0; n < 2; ++n) _Pragma("unroll") for (int k = 0; k < 2; ++k) \
;         acc[ai][bj][m][n] = __builtin_amdgcn_mfma_f32_16x16x32_bf16(Bt[n][k], At[m][k], acc[ai][bj][m][n], 0, 0, 0); __builtin_amdgcn_s_setprio(0); } while (0)
; #define PG8_WAIT_V(n) asm volatile("s_waitcnt vmcnt(" #n ")" ::: "memory")
; #define PG8_WAIT_L(n) asm volatile("s_waitcnt lgkmcnt(" #n ")" ::: "memory")
; #define PG8_BAR __builtin_amdgcn_s_barrier()
; #define PG8_SCHED __builtin_amdgcn_sched_barrier(0)
; template <class Epi, class Sched, bool ALIGN_EPI, bool LAST_FUSED = false, bool PERM = false, bool CARRY = false>
; __device__ __forceinline__ void gemm_phase(LAS unsigned char* lds, const int tid, const int K, const int lda, const int ldb, const Sched& S, const Epi& E) {
;     ...
;             PG8_LDA(At, 1, 1); PG8_STAGE(PG8_SB(1, 0), b3, voffB); PG8_STAGE(PG8_SB(1, 1), b3 + hstepB, voffB); PG8_STAGE(PG8_SA(1, 0), a3, voffA);
;             PG8_WAIT_V(8); PG8_WAIT_L(0); PG8_BAR; PG8_MMA(1, 0, At, B0); PG8_MMA(1, 1, At, B1); PG8_BAR; PG8_SCHED;
;         }
;         if constexpr (ALIGN_EPI) { if (wr == 0) PG8_BAR; }
	s_setprio 0
	s_add_i32 s28, s31, s51
	v_lshl_add_u64 v[206:207], v[206:207], 0, s[68:69]
	s_mov_b32 m0, s28
	ds_read_b128 v[174:177], v145 offset:49152
	ds_read_b128 v[178:181], v145 offset:50176
	ds_read_b128 v[182:185], v145 offset:51200
	ds_read_b128 v[186:189], v145 offset:52224
	ds_read_b128 v[190:193], v145 offset:53248
	ds_read_b128 v[194:197], v145 offset:54272
	ds_read_b128 v[198:201], v145 offset:55296
	ds_read_b128 v[202:205], v145 offset:56320
	global_load_lds_dwordx4 v[206:207], off
	s_add_i32 m0, s28, 0x2000
	s_add_u32 s4, s4, 0x80080
	v_lshl_add_u64 v[206:207], v[208:209], 0, s[68:69]
	s_addc_u32 s5, s5, 0
	s_add_i32 s28, s35, s51
	global_load_lds_dwordx4 v[206:207], off
	v_lshl_add_u64 v[206:207], s[4:5], 0, v[0:1]
	s_mov_b32 m0, s28
	s_nop 0
	global_load_lds_dwordx4 v[206:207], off
	v_lshl_add_u64 v[206:207], s[4:5], 0, v[130:131]
	s_add_i32 m0, s28, 0x2000
	s_nop 0
	global_load_lds_dwordx4 v[206:207], off
	v_lshl_add_u64 v[206:207], v[210:211], 0, s[68:69]
	s_mov_b32 m0, s57
	s_nop 0
	global_load_lds_dwordx4 v[206:207], off
	v_lshl_add_u64 v[206:207], v[212:213], 0, s[68:69]
	s_mov_b32 m0, s58
	s_nop 0
	global_load_lds_dwordx4 v[206:207], off
	s_waitcnt vmcnt(8) lgkmcnt(0)
	s_barrier
	s_setprio 1
	v_mfma_f32_16x16x32_bf16 v[62:65], v[136:139], v[174:177], v[62:65]
	v_mfma_f32_16x16x32_bf16 v[58:61], v[150:153], v[174:177], v[58:61]
	v_mfma_f32_16x16x32_bf16 v[46:49], v[136:139], v[182:185], v[46:49]
	v_mfma_f32_16x16x32_bf16 v[42:45], v[150:153], v[182:185], v[42:45]
	v_mfma_f32_16x16x32_bf16 v[30:33], v[136:139], v[190:193], v[30:33]
	v_mfma_f32_16x16x32_bf16 v[26:29], v[150:153], v[190:193], v[26:29]
	v_mfma_f32_16x16x32_bf16 v[14:17], v[136:139], v[198:201], v[14:17]
	v_mfma_f32_16x16x32_bf16 v[10:13], v[150:153], v[198:201], v[10:13]
	v_mfma_f32_16x16x32_bf16 v[62:65], v[146:149], v[178:181], v[62:65]
	v_mfma_f32_16x16x32_bf16 v[58:61], v[154:157], v[178:181], v[58:61]
	v_mfma_f32_16x16x32_bf16 v[46:49], v[146:149], v[186:189], v[46:49]
	v_mfma_f32_16x16x32_bf16 v[42:45], v[154:157], v[186:189], v[42:45]
	v_mfma_f32_16x16x32_bf16 v[30:33], v[146:149], v[194:197], v[30:33]
	v_mfma_f32_16x16x32_bf16 v[26:29], v[154:157], v[194:197], v[26:29]
	v_mfma_f32_16x16x32_bf16 v[14:17], v[146:149], v[202:205], v[14:17]
	v_mfma_f32_16x16x32_bf16 v[10:13], v[154:157], v[202:205], v[10:13]
	s_setprio 0
	s_setprio 1
	v_mfma_f32_16x16x32_bf16 v[54:57], v[158:161], v[174:177], v[54:57]
	v_mfma_f32_16x16x32_bf16 v[50:53], v[166:169], v[174:177], v[50:53]
	v_mfma_f32_16x16x32_bf16 v[38:41], v[158:161], v[182:185], v[38:41]
	v_mfma_f32_16x16x32_bf16 v[34:37], v[166:169], v[182:185], v[34:37]
	v_mfma_f32_16x16x32_bf16 v[22:25], v[158:161], v[190:193], v[22:25]
	v_mfma_f32_16x16x32_bf16 v[18:21], v[166:169], v[190:193], v[18:21]
	v_mfma_f32_16x16x32_bf16 v[6:9], v[158:161], v[198:201], v[6:9]
	v_mfma_f32_16x16x32_bf16 v[2:5], v[166:169], v[198:201], v[2:5]
	v_mfma_f32_16x16x32_bf16 v[54:57], v[162:165], v[178:181], v[54:57]
	v_mfma_f32_16x16x32_bf16 v[50:53], v[170:173], v[178:181], v[50:53]
	v_mfma_f32_16x16x32_bf16 v[38:41], v[162:165], v[186:189], v[38:41]
	v_mfma_f32_16x16x32_bf16 v[34:37], v[170:173], v[186:189], v[34:37]
	v_mfma_f32_16x16x32_bf16 v[22:25], v[162:165], v[194:197], v[22:25]
	v_mfma_f32_16x16x32_bf16 v[18:21], v[170:173], v[194:197], v[18:21]
	v_mfma_f32_16x16x32_bf16 v[6:9], v[162:165], v[202:205], v[6:9]
	v_mfma_f32_16x16x32_bf16 v[2:5], v[170:173], v[202:205], v[2:5]
	s_barrier
	s_setprio 0
	s_add_i32 s27, s27, 2
	s_add_u32 s2, s2, 0x100
	s_addc_u32 s3, s3, 0
	s_add_u32 s22, s22, 0x100
	s_addc_u32 s23, s23, 0
	s_cmp_gt_u32 s27, 29
	s_cbranch_scc0 .LBB0_279
	s_and_b64 vcc, exec, s[18:19]
	s_cbranch_vccz .LBB0_282
	s_barrier

; #define PG8_STAGE(bufoff, gbase, voff) do { _Pragma("unroll") for (int _i = 0; _i < 2; ++_i) \
;         __builtin_amdgcn_global_load_lds((const unsigned*)((const char*)(gbase) + (voff)[_i]), (LAS unsigned*)(lds + (bufoff) + ldsw + _i * 8192), 16, 0, 0); } while (0)
; #define PG8_LDA(dst, b, h) do { _Pragma("unroll") for (int m = 0; m < 4; ++m) _Pragma("unroll") for (int k = 0; k < 2; ++k) dst[m][k] = *(const LAS bf16x8*)(lds + PG8_SA(b, h) + aoff + m * 2048 + k * 1024); } while (0)
; #define PG8_LDB(dst, b, h) do { _Pragma("unroll") for (int n = 0; n < 2; ++n) _Pragma("unroll") for (int k = 0; k < 2; ++k) dst[n][k] = *(const LAS bf16x8*)(lds + PG8_SB(b, h) + boff + n * 2048 + k * 1024); } while (0)
; #define PG8_WAIT_V(n) asm volatile("s_waitcnt vmcnt(" #n ")" ::: "memory")
; #define PG8_WAIT_L(n) asm volatile("s_waitcnt lgkmcnt(" #n ")" ::: "memory")
; #define PG8_BAR __builtin_amdgcn_s_barrier()
; #define PG8_SCHED __builtin_amdgcn_sched_barrier(0)
; template <class Epi, class Sched, bool ALIGN_EPI, bool LAST_FUSED = false, bool PERM = false, bool CARRY = false>
; __device__ __forceinline__ void gemm_phase(LAS unsigned char* lds, const int tid, const int K, const int lda, const int ldb, const Sched& S, const Epi& E) {
;     ...
;         const bool has_next = S.next(KD_IDX(ui + 1), nxt);
;         const char* nA = has_next ? nxt.a : cA; const char* nB = has_next ? nxt.b : cB; const int nt = cur.nt;
; #pragma unroll 1
;         for (int t = 0; t < nt; t += 2) {
;             const bool last = (t == nt - 2);
;             const char* a1 = cA + (size_t)(t + 1) * kstep;
;             const char* a2 = last ? nA : cA + (size_t)(t + 2) * kstep; const char* b2 = last ? nB : cB + (size_t)(t + 2) * kstep;
;             const char* a3 = a2 + kstep; const char* b3 = b2 + kstep;
;             PG8_LDB(B0, 0, 0); PG8_LDB(B1, 0, 1); PG8_SCHED; PG8_LDA(At, 0, 0); PG8_STAGE(PG8_SA(1, 1), a1 + hstepA, voffA);
;             PG8_WAIT_V(8); PG8_WAIT_L(0); PG8_BAR; PG8_MMA(0, 0, At, B0); PG8_MMA(0, 1, At, B1); PG8_BAR; PG8_SCHED;
;             PG8_LDA(At, 0, 1); PG8_STAGE(PG8_SB(0, 0), b2, voffB); PG8_STAGE(PG8_SB(0, 1), b2 + hstepB, voffB); PG8_STAGE(PG8_SA(0, 0), a2, voffA);
;             PG8_WAIT_V(8); PG8_WAIT_L(0); PG8_BAR; PG8_MMA(1, 0, At, B0); PG8_MMA(1, 1, At, B1); PG8_BAR; PG8_SCHED;
.LBB0_512:
	s_add_u32 s28, s4, 0xfff80080
	s_addc_u32 s29, s5, -1
	s_add_i32 s31, 0, 0x10000
	s_cmp_eq_u32 s24, 28
	s_cselect_b32 s41, s87, s29
	s_cselect_b32 s40, s86, s28
	v_add_u32_e32 v148, s31, v160
	s_cselect_b32 s37, s39, s23
	s_cselect_b32 s36, s38, s22
	s_add_i32 s35, 0, 0x14000
	ds_read_b128 v[140:143], v148
	ds_read_b128 v[144:147], v148 offset:1024
	ds_read_b128 v[162:165], v148 offset:2048
	ds_read_b128 v[166:169], v148 offset:3072
	v_add_u32_e32 v148, s35, v160
	ds_read_b128 v[170:173], v148
	ds_read_b128 v[174:177], v148 offset:1024
	ds_read_b128 v[178:181], v148 offset:2048
	ds_read_b128 v[182:185], v148 offset:3072
	v_lshl_add_u64 v[148:149], s[4:5], 0, v[136:137]
	s_add_i32 m0, s54, 0xc000
	ds_read_b128 v[186:189], v161
	ds_read_b128 v[190:193], v161 offset:1024
	ds_read_b128 v[194:197], v161 offset:2048
	ds_read_b128 v[198:201], v161 offset:3072
	ds_read_b128 v[202:205], v161 offset:4096
	ds_read_b128 v[206:209], v161 offset:5120
	ds_read_b128 v[210:213], v161 offset:6144
	ds_read_b128 v[214:217], v161 offset:7168
	global_load_lds_dwordx4 v[148:149], off
	v_lshl_add_u64 v[148:149], s[4:5], 0, v[138:139]
	s_add_i32 m0, s54, 0xe000
	s_nop 0
	global_load_lds_dwordx4 v[148:149], off
	s_waitcnt vmcnt(8) lgkmcnt(0)
	s_barrier
	s_setprio 1
	v_mfma_f32_16x16x32_bf16 v[126:129], v[140:143], v[186:189], v[126:129]
	v_mfma_f32_16x16x32_bf16 v[122:125], v[162:165], v[186:189], v[122:125]
	v_mfma_f32_16x16x32_bf16 v[110:113], v[140:143], v[194:197], v[110:113]
	v_mfma_f32_16x16x32_bf16 v[106:109], v[162:165], v[194:197], v[106:109]
	v_mfma_f32_16x16x32_bf16 v[94:97], v[140:143], v[202:205], v[94:97]
	v_mfma_f32_16x16x32_bf16 v[90:93], v[162:165], v[202:205], v[90:93]
	v_mfma_f32_16x16x32_bf16 v[78:81], v[140:143], v[210:213], v[78:81]
	v_mfma_f32_16x16x32_bf16 v[74:77], v[162:165], v[210:213], v[74:77]
	v_mfma_f32_16x16x32_bf16 v[126:129], v[144:147], v[190:193], v[126:129]
	v_mfma_f32_16x16x32_bf16 v[122:125], v[166:169], v[190:193], v[122:125]
	v_mfma_f32_16x16x32_bf16 v[110:113], v[144:147], v[198:201], v[110:113]
	v_mfma_f32_16x16x32_bf16 v[106:109], v[166:169], v[198:201], v[106:109]
	v_mfma_f32_16x16x32_bf16 v[94:97], v[144:147], v[206:209], v[94:97]
	v_mfma_f32_16x16x32_bf16 v[90:93], v[166:169], v[206:209], v[90:93]
	v_mfma_f32_16x16x32_bf16 v[78:81], v[144:147], v[214:217], v[78:81]
	v_mfma_f32_16x16x32_bf16 v[74:77], v[166:169], v[214:217], v[74:77]
	s_setprio 0
	s_setprio 1
	v_mfma_f32_16x16x32_bf16 v[118:121], v[170:173], v[186:189], v[118:121]
	v_mfma_f32_16x16x32_bf16 v[114:117], v[178:181], v[186:189], v[114:117]
	v_mfma_f32_16x16x32_bf16 v[102:105], v[170:173], v[194:197], v[102:105]
	v_mfma_f32_16x16x32_bf16 v[98:101], v[178:181], v[194:197], v[98:101]
	v_mfma_f32_16x16x32_bf16 v[86:89], v[170:173], v[202:205], v[86:89]
	v_mfma_f32_16x16x32_bf16 v[82:85], v[178:181], v[202:205], v[82:85]
	v_mfma_f32_16x16x32_bf16 v[70:73], v[170:173], v[210:213], v[70:73]
	v_mfma_f32_16x16x32_bf16 v[66:69], v[178:181], v[210:213], v[66:69]
	v_mfma_f32_16x16x32_bf16 v[118:121], v[174:177], v[190:193], v[118:121]
	v_mfma_f32_16x16x32_bf16 v[114:117], v[182:185], v[190:193], v[114:117]
	v_mfma_f32_16x16x32_bf16 v[102:105], v[174:177], v[198:201], v[102:105]
	v_mfma_f32_16x16x32_bf16 v[98:101], v[182:185], v[198:201], v[98:101]
	v_mfma_f32_16x16x32_bf16 v[86:89], v[174:177], v[206:209], v[86:89]
	v_mfma_f32_16x16x32_bf16 v[82:85], v[182:185], v[206:209], v[82:85]
	v_mfma_f32_16x16x32_bf16 v[70:73], v[174:177], v[214:217], v[70:73]
	v_mfma_f32_16x16x32_bf16 v[66:69], v[182:185], v[214:217], v[66:69]
	s_barrier
	s_setprio 0
	s_add_i32 s28, s31, s52
	v_lshl_add_u64 v[148:149], s[36:37], 0, v[0:1]
	s_mov_b32 m0, s28
	ds_read_b128 v[186:189], v161 offset:16384
	ds_read_b128 v[190:193], v161 offset:17408
	ds_read_b128 v[194:197], v161 offset:18432
	ds_read_b128 v[198:201], v161 offset:19456
	ds_read_b128 v[202:205], v161 offset:20480
	ds_read_b128 v[206:209], v161 offset:21504
	ds_read_b128 v[210:213], v161 offset:22528
	ds_read_b128 v[214:217], v161 offset:23552
	global_load_lds_dwordx4 v[148:149], off
	s_add_i32 m0, s28, 0x2000
	s_add_u32 s28, s36, 0x80000
	v_lshl_add_u64 v[152:153], s[36:37], 0, v[130:131]
	s_addc_u32 s29, s37, 0
	s_add_i32 s31, s35, s52
	global_load_lds_dwordx4 v[152:153], off
	v_lshl_add_u64 v[156:157], s[28:29], 0, v[0:1]
	s_mov_b32 m0, s31
	v_lshl_add_u64 v[218:219], s[40:41], 0, v[132:133]
	global_load_lds_dwordx4 v[156:157], off
	v_lshl_add_u64 v[156:157], s[28:29], 0, v[130:131]
	s_add_i32 m0, s31, 0x2000
	s_nop 0
	global_load_lds_dwordx4 v[156:157], off
	v_lshl_add_u64 v[156:157], s[40:41], 0, v[134:135]
	s_mov_b32 m0, s54
	s_nop 0
	global_load_lds_dwordx4 v[156:157], off
	s_mov_b32 m0, s55
	s_nop 0
	global_load_lds_dwordx4 v[218:219], off
	s_waitcnt vmcnt(8) lgkmcnt(0)
	s_barrier
; #define PG8_STAGE(bufoff, gbase, voff) do { _Pragma("unroll") for (int _i = 0; _i < 2; ++_i) \
;         __builtin_amdgcn_global_load_lds((const unsigned*)((const char*)(gbase) + (voff)[_i]), (LAS unsigned*)(lds + (bufoff) + ldsw + _i * 8192), 16, 0, 0); } while (0)
; #define PG8_LDA(dst, b, h) do { _Pragma("unroll") for (int m = 0; m < 4; ++m) _Pragma("unroll") for (int k = 0; k < 2; ++k) dst[m][k] = *(const LAS bf16x8*)(lds + PG8_SA(b, h) + aoff + m * 2048 + k * 1024); } while (0)
; #define PG8_LDB(dst, b, h) do { _Pragma("unroll") for (int n = 0; n < 2; ++n) _Pragma("unroll") for (int k = 0; k < 2; ++k) dst[n][k] = *(const LAS bf16x8*)(lds + PG8_SB(b, h) + boff + n * 2048 + k * 1024); } while (0)
; #define PG8_MMA(ai, bj, At, Bt) do { __builtin_amdgcn_s_setprio(1); _Pragma("unroll") for (int m = 0; m < 4; ++m) _Pragma("unroll") for (int n = 0; n < 2; ++n) _Pragma("unroll") for (int k = 0; k < 2; ++k) \
;         acc[ai][bj][m][n] = __builtin_amdgcn_mfma_f32_16x16x32_bf16(Bt[n][k], At[m][k], acc[ai][bj][m][n], 0, 0, 0); __builtin_amdgcn_s_setprio(0); } while (0)
; #define PG8_WAIT_V(n) asm volatile("s_waitcnt vmcnt(" #n ")" ::: "memory")
; #define PG8_WAIT_L(n) asm volatile("s_waitcnt lgkmcnt(" #n ")" ::: "memory")
; #define PG8_BAR __builtin_amdgcn_s_barrier()
; #define PG8_SCHED __builtin_amdgcn_sched_barrier(0)
; template <class Epi, class Sched, bool ALIGN_EPI, bool LAST_FUSED = false, bool PERM = false, bool CARRY = false>
; __device__ __forceinline__ void gemm_phase(LAS unsigned char* lds, const int tid, const int K, const int lda, const int ldb, const Sched& S, const Epi& E) {
;     ...
;             PG8_WAIT_V(8); PG8_WAIT_L(0); PG8_BAR; PG8_MMA(1, 0, At, B0); PG8_MMA(1, 1, At, B1); PG8_BAR; PG8_SCHED;
;             PG8_LDB(B0, 1, 0); PG8_LDB(B1, 1, 1); PG8_SCHED; PG8_LDA(At, 1, 0); PG8_STAGE(PG8_SA(0, 1), a2 + hstepA, voffA);
;             PG8_WAIT_V(8); PG8_WAIT_L(0); PG8_BAR; PG8_MMA(0, 0, At, B0); PG8_MMA(0, 1, At, B1); PG8_BAR; PG8_SCHED;
	s_setprio 1
	v_mfma_f32_16x16x32_bf16 v[62:65], v[140:143], v[186:189], v[62:65]
	v_mfma_f32_16x16x32_bf16 v[58:61], v[162:165], v[186:189], v[58:61]
	v_mfma_f32_16x16x32_bf16 v[46:49], v[140:143], v[194:197], v[46:49]
	v_mfma_f32_16x16x32_bf16 v[42:45], v[162:165], v[194:197], v[42:45]
	v_mfma_f32_16x16x32_bf16 v[30:33], v[140:143], v[202:205], v[30:33]
	v_mfma_f32_16x16x32_bf16 v[26:29], v[162:165], v[202:205], v[26:29]
	v_mfma_f32_16x16x32_bf16 v[14:17], v[140:143], v[210:213], v[14:17]
	v_mfma_f32_16x16x32_bf16 v[10:13], v[162:165], v[210:213], v[10:13]
	v_mfma_f32_16x16x32_bf16 v[62:65], v[144:147], v[190:193], v[62:65]
	v_mfma_f32_16x16x32_bf16 v[58:61], v[166:169], v[190:193], v[58:61]
	v_mfma_f32_16x16x32_bf16 v[46:49], v[144:147], v[198:201], v[46:49]
	v_mfma_f32_16x16x32_bf16 v[42:45], v[166:169], v[198:201], v[42:45]
	v_mfma_f32_16x16x32_bf16 v[30:33], v[144:147], v[206:209], v[30:33]
	v_mfma_f32_16x16x32_bf16 v[26:29], v[166:169], v[206:209], v[26:29]
	v_mfma_f32_16x16x32_bf16 v[14:17], v[144:147], v[214:217], v[14:17]
	v_mfma_f32_16x16x32_bf16 v[10:13], v[166:169], v[214:217], v[10:13]
	s_setprio 0
	s_setprio 1
	v_mfma_f32_16x16x32_bf16 v[54:57], v[170:173], v[186:189], v[54:57]
	v_mfma_f32_16x16x32_bf16 v[50:53], v[178:181], v[186:189], v[50:53]
	v_mfma_f32_16x16x32_bf16 v[38:41], v[170:173], v[194:197], v[38:41]
	v_mfma_f32_16x16x32_bf16 v[34:37], v[178:181], v[194:197], v[34:37]
	v_mfma_f32_16x16x32_bf16 v[22:25], v[170:173], v[202:205], v[22:25]
	v_mfma_f32_16x16x32_bf16 v[18:21], v[178:181], v[202:205], v[18:21]
	v_mfma_f32_16x16x32_bf16 v[6:9], v[170:173], v[210:213], v[6:9]
	v_mfma_f32_16x16x32_bf16 v[2:5], v[178:181], v[210:213], v[2:5]
	v_mfma_f32_16x16x32_bf16 v[54:57], v[174:177], v[190:193], v[54:57]
	v_mfma_f32_16x16x32_bf16 v[50:53], v[182:185], v[190:193], v[50:53]
	v_mfma_f32_16x16x32_bf16 v[38:41], v[174:177], v[198:201], v[38:41]
	v_mfma_f32_16x16x32_bf16 v[34:37], v[182:185], v[198:201], v[34:37]
	v_mfma_f32_16x16x32_bf16 v[22:25], v[174:177], v[206:209], v[22:25]
	v_mfma_f32_16x16x32_bf16 v[18:21], v[182:185], v[206:209], v[18:21]
	v_mfma_f32_16x16x32_bf16 v[6:9], v[174:177], v[214:217], v[6:9]
	v_mfma_f32_16x16x32_bf16 v[2:5], v[182:185], v[214:217], v[2:5]
	s_barrier
	s_setprio 0
	s_add_i32 s31, 0, 0x18000
	v_add_u32_e32 v150, s31, v160
	s_add_i32 s35, 0, 0x1c000
	ds_read_b128 v[140:143], v150
	ds_read_b128 v[144:147], v150 offset:1024
	ds_read_b128 v[162:165], v150 offset:2048
	ds_read_b128 v[166:169], v150 offset:3072
	v_add_u32_e32 v150, s35, v160
	ds_read_b128 v[170:173], v150
	ds_read_b128 v[174:177], v150 offset:1024
	ds_read_b128 v[178:181], v150 offset:2048
	ds_read_b128 v[182:185], v150 offset:3072
	s_add_u32 s28, s40, 0x80000
	s_addc_u32 s29, s41, 0
	s_mov_b32 m0, s56
	v_lshl_add_u64 v[220:221], s[28:29], 0, v[134:135]
	ds_read_b128 v[186:189], v161 offset:32768
	ds_read_b128 v[190:193], v161 offset:33792
	ds_read_b128 v[194:197], v161 offset:34816
	ds_read_b128 v[198:201], v161 offset:35840
	ds_read_b128 v[202:205], v161 offset:36864
	ds_read_b128 v[206:209], v161 offset:37888
	ds_read_b128 v[210:213], v161 offset:38912
	ds_read_b128 v[214:217], v161 offset:39936
	global_load_lds_dwordx4 v[220:221], off
	v_lshl_add_u64 v[220:221], s[28:29], 0, v[132:133]
	s_mov_b32 m0, s57
	s_nop 0
	global_load_lds_dwordx4 v[220:221], off
	s_waitcnt vmcnt(8) lgkmcnt(0)
	s_barrier
	s_setprio 1
	v_mfma_f32_16x16x32_bf16 v[126:129], v[140:143], v[186:189], v[126:129]
	v_mfma_f32_16x16x32_bf16 v[122:125], v[162:165], v[186:189], v[122:125]
	v_mfma_f32_16x16x32_bf16 v[110:113], v[140:143], v[194:197], v[110:113]
	v_mfma_f32_16x16x32_bf16 v[106:109], v[162:165], v[194:197], v[106:109]
	v_mfma_f32_16x16x32_bf16 v[94:97], v[140:143], v[202:205], v[94:97]
	v_mfma_f32_16x16x32_bf16 v[90:93], v[162:165], v[202:205], v[90:93]
	v_mfma_f32_16x16x32_bf16 v[78:81], v[140:143], v[210:213], v[78:81]
	v_mfma_f32_16x16x32_bf16 v[74:77], v[162:165], v[210:213], v[74:77]
	v_mfma_f32_16x16x32_bf16 v[126:129], v[144:147], v[190:193], v[126:129]
	v_mfma_f32_16x16x32_bf16 v[122:125], v[166:169], v[190:193], v[122:125]
	v_mfma_f32_16x16x32_bf16 v[110:113], v[144:147], v[198:201], v[110:113]
	v_mfma_f32_16x16x32_bf16 v[106:109], v[166:169], v[198:201], v[106:109]
	v_mfma_f32_16x16x32_bf16 v[94:97], v[144:147], v[206:209], v[94:97]
	v_mfma_f32_16x16x32_bf16 v[90:93], v[166:169], v[206:209], v[90:93]
	v_mfma_f32_16x16x32_bf16 v[78:81], v[144:147], v[214:217], v[78:81]
	v_mfma_f32_16x16x32_bf16 v[74:77], v[166:169], v[214:217], v[74:77]
	s_setprio 0
	s_setprio 1
	v_mfma_f32_16x16x32_bf16 v[118:121], v[170:173], v[186:189], v[118:121]
	v_mfma_f32_16x16x32_bf16 v[114:117], v[178:181], v[186:189], v[114:117]
	v_mfma_f32_16x16x32_bf16 v[102:105], v[170:173], v[194:197], v[102:105]
	v_mfma_f32_16x16x32_bf16 v[98:101], v[178:181], v[194:197], v[98:101]
	v_mfma_f32_16x16x32_bf16 v[86:89], v[170:173], v[202:205], v[86:89]
	v_mfma_f32_16x16x32_bf16 v[82:85], v[178:181], v[202:205], v[82:85]
	v_mfma_f32_16x16x32_bf16 v[70:73], v[170:173], v[210:213], v[70:73]
	v_mfma_f32_16x16x32_bf16 v[66:69], v[178:181], v[210:213], v[66:69]
	v_mfma_f32_16x16x32_bf16 v[118:121], v[174:177], v[190:193], v[118:121]
	v_mfma_f32_16x16x32_bf16 v[114:117], v[182:185], v[190:193], v[114:117]
	v_mfma_f32_16x16x32_bf16 v[102:105], v[174:177], v[198:201], v[102:105]
	v_mfma_f32_16x16x32_bf16 v[98:101], v[182:185], v[198:201], v[98:101]
	v_mfma_f32_16x16x32_bf16 v[86:89], v[174:177], v[206:209], v[86:89]
	v_mfma_f32_16x16x32_bf16 v[82:85], v[182:185], v[206:209], v[82:85]
	v_mfma_f32_16x16x32_bf16 v[70:73], v[174:177], v[214:217], v[70:73]
	v_mfma_f32_16x16x32_bf16 v[66:69], v[182:185], v[214:217], v[66:69]
	s_barrier
; #define PG8_STAGE(bufoff, gbase, voff) do { _Pragma("unroll") for (int _i = 0; _i < 2; ++_i) \
;         __builtin_amdgcn_global_load_lds((const unsigned*)((const char*)(gbase) + (voff)[_i]), (LAS unsigned*)(lds + (bufoff) + ldsw + _i * 8192), 16, 0, 0); } while (0)
; #define PG8_LDA(dst, b, h) do { _Pragma("unroll") for (int m = 0; m < 4; ++m) _Pragma("unroll") for (int k = 0; k < 2; ++k) dst[m][k] = *(const LAS bf16x8*)(lds + PG8_SA(b, h) + aoff + m * 2048 + k * 1024); } while (0)
; #define PG8_MMA(ai, bj, At, Bt) do { __builtin_amdgcn_s_setprio(1); _Pragma("unroll") for (int m = 0; m < 4; ++m) _Pragma("unroll") for (int n = 0; n < 2; ++n) _Pragma("unroll") for (int k = 0; k < 2; ++k) \
;         acc[ai][bj][m][n] = __builtin_amdgcn_mfma_f32_16x16x32_bf16(Bt[n][k], At[m][k], acc[ai][bj][m][n], 0, 0, 0); __builtin_amdgcn_s_setprio(0); } while (0)
; #define PG8_WAIT_V(n) asm volatile("s_waitcnt vmcnt(" #n ")" ::: "memory")
; #define PG8_WAIT_L(n) asm volatile("s_waitcnt lgkmcnt(" #n ")" ::: "memory")
; #define PG8_BAR __builtin_amdgcn_s_barrier()
; #define PG8_SCHED __builtin_amdgcn_sched_barrier(0)
; template <class Epi, class Sched, bool ALIGN_EPI, bool LAST_FUSED = false, bool PERM = false, bool CARRY = false>
; __device__ __forceinline__ void gemm_phase(LAS unsigned char* lds, const int tid, const int K, const int lda, const int ldb, const Sched& S, const Epi& E) {
;     ...
;             PG8_LDA(At, 1, 1); PG8_STAGE(PG8_SB(1, 0), b3, voffB); PG8_STAGE(PG8_SB(1, 1), b3 + hstepB, voffB); PG8_STAGE(PG8_SA(1, 0), a3, voffA);
;             PG8_WAIT_V(8); PG8_WAIT_L(0); PG8_BAR; PG8_MMA(1, 0, At, B0); PG8_MMA(1, 1, At, B1); PG8_BAR; PG8_SCHED;
;         }
;         if constexpr (ALIGN_EPI) { if (wr == 0) PG8_BAR; }
	s_setprio 0
	s_add_i32 s28, s31, s52
	v_lshl_add_u64 v[148:149], v[148:149], 0, s[68:69]
	s_mov_b32 m0, s28
	ds_read_b128 v[186:189], v161 offset:49152
	ds_read_b128 v[190:193], v161 offset:50176
	ds_read_b128 v[194:197], v161 offset:51200
	ds_read_b128 v[198:201], v161 offset:52224
	ds_read_b128 v[202:205], v161 offset:53248
	ds_read_b128 v[206:209], v161 offset:54272
	ds_read_b128 v[210:213], v161 offset:55296
	ds_read_b128 v[214:217], v161 offset:56320
	global_load_lds_dwordx4 v[148:149], off
	s_add_i32 m0, s28, 0x2000
	s_add_u32 s28, s36, 0x80080
	v_lshl_add_u64 v[148:149], v[152:153], 0, s[68:69]
	s_addc_u32 s29, s37, 0
	s_add_i32 s31, s35, s52
	global_load_lds_dwordx4 v[148:149], off
	v_lshl_add_u64 v[148:149], s[28:29], 0, v[0:1]
	s_mov_b32 m0, s31
	s_nop 0
	global_load_lds_dwordx4 v[148:149], off
	v_lshl_add_u64 v[148:149], s[28:29], 0, v[130:131]
	s_add_i32 m0, s31, 0x2000
	s_nop 0
	global_load_lds_dwordx4 v[148:149], off
	v_lshl_add_u64 v[148:149], v[156:157], 0, s[68:69]
	s_mov_b32 m0, s59
	s_nop 0
	global_load_lds_dwordx4 v[148:149], off
	v_lshl_add_u64 v[148:149], v[218:219], 0, s[68:69]
	s_mov_b32 m0, s60
	s_nop 0
	global_load_lds_dwordx4 v[148:149], off
	s_waitcnt vmcnt(8) lgkmcnt(0)
	s_barrier
	s_setprio 1
	v_mfma_f32_16x16x32_bf16 v[62:65], v[140:143], v[186:189], v[62:65]
	v_mfma_f32_16x16x32_bf16 v[58:61], v[162:165], v[186:189], v[58:61]
	v_mfma_f32_16x16x32_bf16 v[46:49], v[140:143], v[194:197], v[46:49]
	v_mfma_f32_16x16x32_bf16 v[42:45], v[162:165], v[194:197], v[42:45]
	v_mfma_f32_16x16x32_bf16 v[30:33], v[140:143], v[202:205], v[30:33]
	v_mfma_f32_16x16x32_bf16 v[26:29], v[162:165], v[202:205], v[26:29]
	v_mfma_f32_16x16x32_bf16 v[14:17], v[140:143], v[210:213], v[14:17]
	v_mfma_f32_16x16x32_bf16 v[10:13], v[162:165], v[210:213], v[10:13]
	v_mfma_f32_16x16x32_bf16 v[62:65], v[144:147], v[190:193], v[62:65]
	v_mfma_f32_16x16x32_bf16 v[58:61], v[166:169], v[190:193], v[58:61]
	v_mfma_f32_16x16x32_bf16 v[46:49], v[144:147], v[198:201], v[46:49]
	v_mfma_f32_16x16x32_bf16 v[42:45], v[166:169], v[198:201], v[42:45]
	v_mfma_f32_16x16x32_bf16 v[30:33], v[144:147], v[206:209], v[30:33]
	v_mfma_f32_16x16x32_bf16 v[26:29], v[166:169], v[206:209], v[26:29]
	v_mfma_f32_16x16x32_bf16 v[14:17], v[144:147], v[214:217], v[14:17]
	v_mfma_f32_16x16x32_bf16 v[10:13], v[166:169], v[214:217], v[10:13]
	s_setprio 0
	s_setprio 1
	v_mfma_f32_16x16x32_bf16 v[54:57], v[170:173], v[186:189], v[54:57]
	v_mfma_f32_16x16x32_bf16 v[50:53], v[178:181], v[186:189], v[50:53]
	v_mfma_f32_16x16x32_bf16 v[38:41], v[170:173], v[194:197], v[38:41]
	v_mfma_f32_16x16x32_bf16 v[34:37], v[178:181], v[194:197], v[34:37]
	v_mfma_f32_16x16x32_bf16 v[22:25], v[170:173], v[202:205], v[22:25]
	v_mfma_f32_16x16x32_bf16 v[18:21], v[178:181], v[202:205], v[18:21]
	v_mfma_f32_16x16x32_bf16 v[6:9], v[170:173], v[210:213], v[6:9]
	v_mfma_f32_16x16x32_bf16 v[2:5], v[178:181], v[210:213], v[2:5]
	v_mfma_f32_16x16x32_bf16 v[54:57], v[174:177], v[190:193], v[54:57]
	v_mfma_f32_16x16x32_bf16 v[50:53], v[182:185], v[190:193], v[50:53]
	v_mfma_f32_16x16x32_bf16 v[38:41], v[174:177], v[198:201], v[38:41]
	v_mfma_f32_16x16x32_bf16 v[34:37], v[182:185], v[198:201], v[34:37]
	v_mfma_f32_16x16x32_bf16 v[22:25], v[174:177], v[206:209], v[22:25]
	v_mfma_f32_16x16x32_bf16 v[18:21], v[182:185], v[206:209], v[18:21]
	v_mfma_f32_16x16x32_bf16 v[6:9], v[174:177], v[214:217], v[6:9]
	v_mfma_f32_16x16x32_bf16 v[2:5], v[182:185], v[214:217], v[2:5]
	s_barrier
	s_setprio 0
	s_add_i32 s24, s24, 2
	s_add_u32 s4, s4, 0x100
	s_addc_u32 s5, s5, 0
	s_add_u32 s22, s22, 0x100
	s_addc_u32 s23, s23, 0
	s_cmp_gt_u32 s24, 29
	s_cbranch_scc0 .LBB0_512
	s_and_b64 vcc, exec, s[78:79]
	s_cbranch_vccz .LBB0_515
	s_barrier

; #define PG8_STAGE(bufoff, gbase, voff) do { _Pragma("unroll") for (int _i = 0; _i < 2; ++_i) \
;         __builtin_amdgcn_global_load_lds((const unsigned*)((const char*)(gbase) + (voff)[_i]), (LAS unsigned*)(lds + (bufoff) + ldsw + _i * 8192), 16, 0, 0); } while (0)
; #define PG8_LDA(dst, b, h) do { _Pragma("unroll") for (int m = 0; m < 4; ++m) _Pragma("unroll") for (int k = 0; k < 2; ++k) dst[m][k] = *(const LAS bf16x8*)(lds + PG8_SA(b, h) + aoff + m * 2048 + k * 1024); } while (0)
; #define PG8_LDB(dst, b, h) do { _Pragma("unroll") for (int n = 0; n < 2; ++n) _Pragma("unroll") for (int k = 0; k < 2; ++k) dst[n][k] = *(const LAS bf16x8*)(lds + PG8_SB(b, h) + boff + n * 2048 + k * 1024); } while (0)
; #define PG8_WAIT_V(n) asm volatile("s_waitcnt vmcnt(" #n ")" ::: "memory")
; #define PG8_WAIT_L(n) asm volatile("s_waitcnt lgkmcnt(" #n ")" ::: "memory")
; #define PG8_BAR __builtin_amdgcn_s_barrier()
; #define PG8_SCHED __builtin_amdgcn_sched_barrier(0)
; template <class Epi, class Sched, bool ALIGN_EPI, bool LAST_FUSED = false, bool PERM = false, bool CARRY = false>
; __device__ __forceinline__ void gemm_phase(LAS unsigned char* lds, const int tid, const int K, const int lda, const int ldb, const Sched& S, const Epi& E) {
;     ...
;         const bool has_next = S.next(KD_IDX(ui + 1), nxt);
;         const char* nA = has_next ? nxt.a : cA; const char* nB = has_next ? nxt.b : cB; const int nt = cur.nt;
; #pragma unroll 1
;         for (int t = 0; t < nt; t += 2) {
;             const bool last = (t == nt - 2);
;             const char* a1 = cA + (size_t)(t + 1) * kstep;
;             const char* a2 = last ? nA : cA + (size_t)(t + 2) * kstep; const char* b2 = last ? nB : cB + (size_t)(t + 2) * kstep;
;             const char* a3 = a2 + kstep; const char* b3 = b2 + kstep;
;             PG8_LDB(B0, 0, 0); PG8_LDB(B1, 0, 1); PG8_SCHED; PG8_LDA(At, 0, 0); PG8_STAGE(PG8_SA(1, 1), a1 + hstepA, voffA);
;             PG8_WAIT_V(8); PG8_WAIT_L(0); PG8_BAR; PG8_MMA(0, 0, At, B0); PG8_MMA(0, 1, At, B1); PG8_BAR; PG8_SCHED;
;             PG8_LDA(At, 0, 1); PG8_STAGE(PG8_SB(0, 0), b2, voffB); PG8_STAGE(PG8_SB(0, 1), b2 + hstepB, voffB); PG8_STAGE(PG8_SA(0, 0), a2, voffA);
;             PG8_WAIT_V(8); PG8_WAIT_L(0); PG8_BAR; PG8_MMA(1, 0, At, B0); PG8_MMA(1, 1, At, B1); PG8_BAR; PG8_SCHED;
.LBB0_601:
	s_add_u32 s23, s30, s15
	s_addc_u32 s27, s31, 0
	s_add_u32 s35, s23, 0x100
	s_addc_u32 s42, s27, 0
	s_and_b64 s[28:29], s[40:41], exec
	s_cselect_b32 s47, s17, s42
	s_cselect_b32 s46, s16, s35
	s_add_u32 s15, s36, s15
	s_addc_u32 s28, s37, 0
	s_add_u32 s15, s15, 0x100
	s_addc_u32 s35, s28, 0
	s_add_i32 s75, 0, 0x10000
	s_and_b64 s[28:29], s[40:41], exec
	s_cselect_b32 s49, s19, s35
	s_cselect_b32 s48, s18, s15
	s_add_i32 s41, 0, 0x14000
	s_add_u32 s52, s23, 0x80080
	s_addc_u32 s53, s27, 0
	s_add_i32 s45, s75, s59
	s_add_i32 m0, s60, 0xc000
	s_add_i32 s77, s60, 0xe000
	s_add_i32 s29, s45, 0x2000
	s_add_u32 s50, s48, 0x80000
	v_add_u32_e32 v154, s75, v144
	v_add_u32_e32 v170, s41, v144
	s_addc_u32 s51, s49, 0
	s_add_i32 s44, s41, s59
	ds_read_b128 v[136:139], v154
	ds_read_b128 v[146:149], v154 offset:1024
	ds_read_b128 v[150:153], v154 offset:2048
	ds_read_b128 v[154:157], v154 offset:3072
	ds_read_b128 v[158:161], v170
	ds_read_b128 v[162:165], v170 offset:1024
	ds_read_b128 v[166:169], v170 offset:2048
	ds_read_b128 v[170:173], v170 offset:3072
	s_add_i32 s35, s44, 0x2000
	s_add_i32 s28, 0, 0x18000
	s_add_i32 s27, 0, 0x1c000
	s_add_u32 s42, s46, 0x80000
	s_addc_u32 s43, s47, 0
	s_add_i32 s23, s28, s59
	s_add_i32 s15, s23, 0x2000
	s_add_u32 s40, s48, 0x80080
	s_addc_u32 s41, s49, 0
	s_add_i32 s76, s27, s59
	s_add_i32 s75, s76, 0x2000
	v_lshl_add_u64 v[206:207], s[52:53], 0, v[134:135]
	ds_read_b128 v[174:177], v145
	ds_read_b128 v[178:181], v145 offset:1024
	ds_read_b128 v[182:185], v145 offset:2048
	ds_read_b128 v[186:189], v145 offset:3072
	ds_read_b128 v[190:193], v145 offset:4096
	ds_read_b128 v[194:197], v145 offset:5120
	ds_read_b128 v[198:201], v145 offset:6144
	ds_read_b128 v[202:205], v145 offset:7168
	global_load_lds_dwordx4 v[206:207], off
	v_lshl_add_u64 v[206:207], s[52:53], 0, v[132:133]
	s_mov_b32 m0, s77
	s_nop 0
	global_load_lds_dwordx4 v[206:207], off
	s_waitcnt vmcnt(8) lgkmcnt(0)
	s_barrier
	s_setprio 1
	v_mfma_f32_16x16x32_bf16 v[126:129], v[136:139], v[174:177], v[126:129]
	v_mfma_f32_16x16x32_bf16 v[122:125], v[150:153], v[174:177], v[122:125]
	v_mfma_f32_16x16x32_bf16 v[110:113], v[136:139], v[182:185], v[110:113]
	v_mfma_f32_16x16x32_bf16 v[106:109], v[150:153], v[182:185], v[106:109]
	v_mfma_f32_16x16x32_bf16 v[94:97], v[136:139], v[190:193], v[94:97]
	v_mfma_f32_16x16x32_bf16 v[90:93], v[150:153], v[190:193], v[90:93]
	v_mfma_f32_16x16x32_bf16 v[78:81], v[136:139], v[198:201], v[78:81]
	v_mfma_f32_16x16x32_bf16 v[74:77], v[150:153], v[198:201], v[74:77]
	v_mfma_f32_16x16x32_bf16 v[126:129], v[146:149], v[178:181], v[126:129]
	v_mfma_f32_16x16x32_bf16 v[122:125], v[154:157], v[178:181], v[122:125]
	v_mfma_f32_16x16x32_bf16 v[110:113], v[146:149], v[186:189], v[110:113]
	v_mfma_f32_16x16x32_bf16 v[106:109], v[154:157], v[186:189], v[106:109]
	v_mfma_f32_16x16x32_bf16 v[94:97], v[146:149], v[194:197], v[94:97]
	v_mfma_f32_16x16x32_bf16 v[90:93], v[154:157], v[194:197], v[90:93]
	v_mfma_f32_16x16x32_bf16 v[78:81], v[146:149], v[202:205], v[78:81]
	v_mfma_f32_16x16x32_bf16 v[74:77], v[154:157], v[202:205], v[74:77]
	s_setprio 0
	s_setprio 1
	v_mfma_f32_16x16x32_bf16 v[118:121], v[158:161], v[174:177], v[118:121]
	v_mfma_f32_16x16x32_bf16 v[114:117], v[166:169], v[174:177], v[114:117]
	v_mfma_f32_16x16x32_bf16 v[102:105], v[158:161], v[182:185], v[102:105]
	v_mfma_f32_16x16x32_bf16 v[98:101], v[166:169], v[182:185], v[98:101]
	v_mfma_f32_16x16x32_bf16 v[86:89], v[158:161], v[190:193], v[86:89]
	v_mfma_f32_16x16x32_bf16 v[82:85], v[166:169], v[190:193], v[82:85]
	v_mfma_f32_16x16x32_bf16 v[70:73], v[158:161], v[198:201], v[70:73]
	v_mfma_f32_16x16x32_bf16 v[66:69], v[166:169], v[198:201], v[66:69]
	v_mfma_f32_16x16x32_bf16 v[118:121], v[162:165], v[178:181], v[118:121]
	v_mfma_f32_16x16x32_bf16 v[114:117], v[170:173], v[178:181], v[114:117]
	v_mfma_f32_16x16x32_bf16 v[102:105], v[162:165], v[186:189], v[102:105]
	v_mfma_f32_16x16x32_bf16 v[98:101], v[170:173], v[186:189], v[98:101]
	v_mfma_f32_16x16x32_bf16 v[86:89], v[162:165], v[194:197], v[86:89]
	v_mfma_f32_16x16x32_bf16 v[82:85], v[170:173], v[194:197], v[82:85]
	v_mfma_f32_16x16x32_bf16 v[70:73], v[162:165], v[202:205], v[70:73]
	v_mfma_f32_16x16x32_bf16 v[66:69], v[170:173], v[202:205], v[66:69]
	s_barrier
	s_setprio 0
	s_mov_b32 m0, s45
	v_lshl_add_u64 v[206:207], s[48:49], 0, v[0:1]
	ds_read_b128 v[174:177], v145 offset:16384
	ds_read_b128 v[178:181], v145 offset:17408
	ds_read_b128 v[182:185], v145 offset:18432
	ds_read_b128 v[186:189], v145 offset:19456
	ds_read_b128 v[190:193], v145 offset:20480
	ds_read_b128 v[194:197], v145 offset:21504
	ds_read_b128 v[198:201], v145 offset:22528
	ds_read_b128 v[202:205], v145 offset:23552
	global_load_lds_dwordx4 v[206:207], off
	v_lshl_add_u64 v[208:209], s[48:49], 0, v[130:131]
	s_mov_b32 m0, s29
	v_lshl_add_u64 v[210:211], s[50:51], 0, v[0:1]
	global_load_lds_dwordx4 v[208:209], off
	s_mov_b32 m0, s44
	v_lshl_add_u64 v[212:213], s[46:47], 0, v[132:133]
	global_load_lds_dwordx4 v[210:211], off
	v_lshl_add_u64 v[210:211], s[50:51], 0, v[130:131]
	s_mov_b32 m0, s35
	s_nop 0
	global_load_lds_dwordx4 v[210:211], off
	v_lshl_add_u64 v[210:211], s[46:47], 0, v[134:135]
	s_mov_b32 m0, s60
	s_nop 0
	global_load_lds_dwordx4 v[210:211], off
	s_mov_b32 m0, s61
	s_nop 0
	global_load_lds_dwordx4 v[212:213], off
	s_waitcnt vmcnt(8) lgkmcnt(0)
	s_barrier
; #define PG8_STAGE(bufoff, gbase, voff) do { _Pragma("unroll") for (int _i = 0; _i < 2; ++_i) \
;         __builtin_amdgcn_global_load_lds((const unsigned*)((const char*)(gbase) + (voff)[_i]), (LAS unsigned*)(lds + (bufoff) + ldsw + _i * 8192), 16, 0, 0); } while (0)
; #define PG8_LDA(dst, b, h) do { _Pragma("unroll") for (int m = 0; m < 4; ++m) _Pragma("unroll") for (int k = 0; k < 2; ++k) dst[m][k] = *(const LAS bf16x8*)(lds + PG8_SA(b, h) + aoff + m * 2048 + k * 1024); } while (0)
; #define PG8_LDB(dst, b, h) do { _Pragma("unroll") for (int n = 0; n < 2; ++n) _Pragma("unroll") for (int k = 0; k < 2; ++k) dst[n][k] = *(const LAS bf16x8*)(lds + PG8_SB(b, h) + boff + n * 2048 + k * 1024); } while (0)
; #define PG8_MMA(ai, bj, At, Bt) do { __builtin_amdgcn_s_setprio(1); _Pragma("unroll") for (int m = 0; m < 4; ++m) _Pragma("unroll") for (int n = 0; n < 2; ++n) _Pragma("unroll") for (int k = 0; k < 2; ++k) \
;         acc[ai][bj][m][n] = __builtin_amdgcn_mfma_f32_16x16x32_bf16(Bt[n][k], At[m][k], acc[ai][bj][m][n], 0, 0, 0); __builtin_amdgcn_s_setprio(0); } while (0)
; #define PG8_WAIT_V(n) asm volatile("s_waitcnt vmcnt(" #n ")" ::: "memory")
; #define PG8_WAIT_L(n) asm volatile("s_waitcnt lgkmcnt(" #n ")" ::: "memory")
; #define PG8_BAR __builtin_amdgcn_s_barrier()
; #define PG8_SCHED __builtin_amdgcn_sched_barrier(0)
; template <class Epi, class Sched, bool ALIGN_EPI, bool LAST_FUSED = false, bool PERM = false, bool CARRY = false>
; __device__ __forceinline__ void gemm_phase(LAS unsigned char* lds, const int tid, const int K, const int lda, const int ldb, const Sched& S, const Epi& E) {
;     ...
;             PG8_WAIT_V(8); PG8_WAIT_L(0); PG8_BAR; PG8_MMA(1, 0, At, B0); PG8_MMA(1, 1, At, B1); PG8_BAR; PG8_SCHED;
;             PG8_LDB(B0, 1, 0); PG8_LDB(B1, 1, 1); PG8_SCHED; PG8_LDA(At, 1, 0); PG8_STAGE(PG8_SA(0, 1), a2 + hstepA, voffA);
;             PG8_WAIT_V(8); PG8_WAIT_L(0); PG8_BAR; PG8_MMA(0, 0, At, B0); PG8_MMA(0, 1, At, B1); PG8_BAR; PG8_SCHED;
	s_setprio 1
	v_mfma_f32_16x16x32_bf16 v[62:65], v[136:139], v[174:177], v[62:65]
	v_mfma_f32_16x16x32_bf16 v[58:61], v[150:153], v[174:177], v[58:61]
	v_mfma_f32_16x16x32_bf16 v[46:49], v[136:139], v[182:185], v[46:49]
	v_mfma_f32_16x16x32_bf16 v[42:45], v[150:153], v[182:185], v[42:45]
	v_mfma_f32_16x16x32_bf16 v[30:33], v[136:139], v[190:193], v[30:33]
	v_mfma_f32_16x16x32_bf16 v[26:29], v[150:153], v[190:193], v[26:29]
	v_mfma_f32_16x16x32_bf16 v[14:17], v[136:139], v[198:201], v[14:17]
	v_mfma_f32_16x16x32_bf16 v[10:13], v[150:153], v[198:201], v[10:13]
	v_mfma_f32_16x16x32_bf16 v[62:65], v[146:149], v[178:181], v[62:65]
	v_mfma_f32_16x16x32_bf16 v[58:61], v[154:157], v[178:181], v[58:61]
	v_mfma_f32_16x16x32_bf16 v[46:49], v[146:149], v[186:189], v[46:49]
	v_mfma_f32_16x16x32_bf16 v[42:45], v[154:157], v[186:189], v[42:45]
	v_mfma_f32_16x16x32_bf16 v[30:33], v[146:149], v[194:197], v[30:33]
	v_mfma_f32_16x16x32_bf16 v[26:29], v[154:157], v[194:197], v[26:29]
	v_mfma_f32_16x16x32_bf16 v[14:17], v[146:149], v[202:205], v[14:17]
	v_mfma_f32_16x16x32_bf16 v[10:13], v[154:157], v[202:205], v[10:13]
	s_setprio 0
	s_setprio 1
	v_mfma_f32_16x16x32_bf16 v[54:57], v[158:161], v[174:177], v[54:57]
	v_mfma_f32_16x16x32_bf16 v[50:53], v[166:169], v[174:177], v[50:53]
	v_mfma_f32_16x16x32_bf16 v[38:41], v[158:161], v[182:185], v[38:41]
	v_mfma_f32_16x16x32_bf16 v[34:37], v[166:169], v[182:185], v[34:37]
	v_mfma_f32_16x16x32_bf16 v[22:25], v[158:161], v[190:193], v[22:25]
	v_mfma_f32_16x16x32_bf16 v[18:21], v[166:169], v[190:193], v[18:21]
	v_mfma_f32_16x16x32_bf16 v[6:9], v[158:161], v[198:201], v[6:9]
	v_mfma_f32_16x16x32_bf16 v[2:5], v[166:169], v[198:201], v[2:5]
	v_mfma_f32_16x16x32_bf16 v[54:57], v[162:165], v[178:181], v[54:57]
	v_mfma_f32_16x16x32_bf16 v[50:53], v[170:173], v[178:181], v[50:53]
	v_mfma_f32_16x16x32_bf16 v[38:41], v[162:165], v[186:189], v[38:41]
	v_mfma_f32_16x16x32_bf16 v[34:37], v[170:173], v[186:189], v[34:37]
	v_mfma_f32_16x16x32_bf16 v[22:25], v[162:165], v[194:197], v[22:25]
	v_mfma_f32_16x16x32_bf16 v[18:21], v[170:173], v[194:197], v[18:21]
	v_mfma_f32_16x16x32_bf16 v[6:9], v[162:165], v[202:205], v[6:9]
	v_mfma_f32_16x16x32_bf16 v[2:5], v[170:173], v[202:205], v[2:5]
	s_barrier
	s_setprio 0
	v_add_u32_e32 v154, s28, v144
	v_add_u32_e32 v170, s27, v144
	ds_read_b128 v[136:139], v154
	ds_read_b128 v[146:149], v154 offset:1024
	ds_read_b128 v[150:153], v154 offset:2048
	ds_read_b128 v[154:157], v154 offset:3072
	ds_read_b128 v[158:161], v170
	ds_read_b128 v[162:165], v170 offset:1024
	ds_read_b128 v[166:169], v170 offset:2048
	ds_read_b128 v[170:173], v170 offset:3072
	s_mov_b32 m0, s62
	v_lshl_add_u64 v[214:215], s[42:43], 0, v[134:135]
	ds_read_b128 v[174:177], v145 offset:32768
	ds_read_b128 v[178:181], v145 offset:33792
	ds_read_b128 v[182:185], v145 offset:34816
	ds_read_b128 v[186:189], v145 offset:35840
	ds_read_b128 v[190:193], v145 offset:36864
	ds_read_b128 v[194:197], v145 offset:37888
	ds_read_b128 v[198:201], v145 offset:38912
	ds_read_b128 v[202:205], v145 offset:39936
	global_load_lds_dwordx4 v[214:215], off
	v_lshl_add_u64 v[214:215], s[42:43], 0, v[132:133]
	s_mov_b32 m0, s63
	s_nop 0
	global_load_lds_dwordx4 v[214:215], off
	s_waitcnt vmcnt(8) lgkmcnt(0)
	s_barrier
	s_setprio 1
	v_mfma_f32_16x16x32_bf16 v[126:129], v[136:139], v[174:177], v[126:129]
	v_mfma_f32_16x16x32_bf16 v[122:125], v[150:153], v[174:177], v[122:125]
	v_mfma_f32_16x16x32_bf16 v[110:113], v[136:139], v[182:185], v[110:113]
	v_mfma_f32_16x16x32_bf16 v[106:109], v[150:153], v[182:185], v[106:109]
	v_mfma_f32_16x16x32_bf16 v[94:97], v[136:139], v[190:193], v[94:97]
	v_mfma_f32_16x16x32_bf16 v[90:93], v[150:153], v[190:193], v[90:93]
	v_mfma_f32_16x16x32_bf16 v[78:81], v[136:139], v[198:201], v[78:81]
	v_mfma_f32_16x16x32_bf16 v[74:77], v[150:153], v[198:201], v[74:77]
	v_mfma_f32_16x16x32_bf16 v[126:129], v[146:149], v[178:181], v[126:129]
	v_mfma_f32_16x16x32_bf16 v[122:125], v[154:157], v[178:181], v[122:125]
	v_mfma_f32_16x16x32_bf16 v[110:113], v[146:149], v[186:189], v[110:113]
	v_mfma_f32_16x16x32_bf16 v[106:109], v[154:157], v[186:189], v[106:109]
	v_mfma_f32_16x16x32_bf16 v[94:97], v[146:149], v[194:197], v[94:97]
	v_mfma_f32_16x16x32_bf16 v[90:93], v[154:157], v[194:197], v[90:93]
	v_mfma_f32_16x16x32_bf16 v[78:81], v[146:149], v[202:205], v[78:81]
	v_mfma_f32_16x16x32_bf16 v[74:77], v[154:157], v[202:205], v[74:77]
	s_setprio 0
	s_setprio 1
	v_mfma_f32_16x16x32_bf16 v[118:121], v[158:161], v[174:177], v[118:121]
	v_mfma_f32_16x16x32_bf16 v[114:117], v[166:169], v[174:177], v[114:117]
	v_mfma_f32_16x16x32_bf16 v[102:105], v[158:161], v[182:185], v[102:105]
	v_mfma_f32_16x16x32_bf16 v[98:101], v[166:169], v[182:185], v[98:101]
	v_mfma_f32_16x16x32_bf16 v[86:89], v[158:161], v[190:193], v[86:89]
	v_mfma_f32_16x16x32_bf16 v[82:85], v[166:169], v[190:193], v[82:85]
	v_mfma_f32_16x16x32_bf16 v[70:73], v[158:161], v[198:201], v[70:73]
	v_mfma_f32_16x16x32_bf16 v[66:69], v[166:169], v[198:201], v[66:69]
	v_mfma_f32_16x16x32_bf16 v[118:121], v[162:165], v[178:181], v[118:121]
	v_mfma_f32_16x16x32_bf16 v[114:117], v[170:173], v[178:181], v[114:117]
	v_mfma_f32_16x16x32_bf16 v[102:105], v[162:165], v[186:189], v[102:105]
	v_mfma_f32_16x16x32_bf16 v[98:101], v[170:173], v[186:189], v[98:101]
	v_mfma_f32_16x16x32_bf16 v[86:89], v[162:165], v[194:197], v[86:89]
	v_mfma_f32_16x16x32_bf16 v[82:85], v[170:173], v[194:197], v[82:85]
	v_mfma_f32_16x16x32_bf16 v[70:73], v[162:165], v[202:205], v[70:73]
	v_mfma_f32_16x16x32_bf16 v[66:69], v[170:173], v[202:205], v[66:69]
	s_barrier
; #define PG8_STAGE(bufoff, gbase, voff) do { _Pragma("unroll") for (int _i = 0; _i < 2; ++_i) \
;         __builtin_amdgcn_global_load_lds((const unsigned*)((const char*)(gbase) + (voff)[_i]), (LAS unsigned*)(lds + (bufoff) + ldsw + _i * 8192), 16, 0, 0); } while (0)
; #define PG8_LDA(dst, b, h) do { _Pragma("unroll") for (int m = 0; m < 4; ++m) _Pragma("unroll") for (int k = 0; k < 2; ++k) dst[m][k] = *(const LAS bf16x8*)(lds + PG8_SA(b, h) + aoff + m * 2048 + k * 1024); } while (0)
; #define PG8_MMA(ai, bj, At, Bt) do { __builtin_amdgcn_s_setprio(1); _Pragma("unroll") for (int m = 0; m < 4; ++m) _Pragma("unroll") for (int n = 0; n < 2; ++n) _Pragma("unroll") for (int k = 0; k < 2; ++k) \
;         acc[ai][bj][m][n] = __builtin_amdgcn_mfma_f32_16x16x32_bf16(Bt[n][k], At[m][k], acc[ai][bj][m][n], 0, 0, 0); __builtin_amdgcn_s_setprio(0); } while (0)
; #define PG8_WAIT_V(n) asm volatile("s_waitcnt vmcnt(" #n ")" ::: "memory")
; #define PG8_WAIT_L(n) asm volatile("s_waitcnt lgkmcnt(" #n ")" ::: "memory")
; #define PG8_BAR __builtin_amdgcn_s_barrier()
; #define PG8_SCHED __builtin_amdgcn_sched_barrier(0)
; template <class Epi, class Sched, bool ALIGN_EPI, bool LAST_FUSED = false, bool PERM = false, bool CARRY = false>
; __device__ __forceinline__ void gemm_phase(LAS unsigned char* lds, const int tid, const int K, const int lda, const int ldb, const Sched& S, const Epi& E) {
;     ...
;             PG8_LDA(At, 1, 1); PG8_STAGE(PG8_SB(1, 0), b3, voffB); PG8_STAGE(PG8_SB(1, 1), b3 + hstepB, voffB); PG8_STAGE(PG8_SA(1, 0), a3, voffA);
;             PG8_WAIT_V(8); PG8_WAIT_L(0); PG8_BAR; PG8_MMA(1, 0, At, B0); PG8_MMA(1, 1, At, B1); PG8_BAR; PG8_SCHED;
;         }
;         if constexpr (ALIGN_EPI) { if (wr == 0) PG8_BAR; }
	s_setprio 0
	s_mov_b32 m0, s23
	v_lshl_add_u64 v[206:207], v[206:207], 0, s[68:69]
	ds_read_b128 v[174:177], v145 offset:49152
	ds_read_b128 v[178:181], v145 offset:50176
	ds_read_b128 v[182:185], v145 offset:51200
	ds_read_b128 v[186:189], v145 offset:52224
	ds_read_b128 v[190:193], v145 offset:53248
	ds_read_b128 v[194:197], v145 offset:54272
	ds_read_b128 v[198:201], v145 offset:55296
	ds_read_b128 v[202:205], v145 offset:56320
	global_load_lds_dwordx4 v[206:207], off
	v_lshl_add_u64 v[206:207], v[208:209], 0, s[68:69]
	s_mov_b32 m0, s15
	s_nop 0
	global_load_lds_dwordx4 v[206:207], off
	v_lshl_add_u64 v[206:207], s[40:41], 0, v[0:1]
	s_mov_b32 m0, s76
	s_nop 0
	global_load_lds_dwordx4 v[206:207], off
	v_lshl_add_u64 v[206:207], s[40:41], 0, v[130:131]
	s_mov_b32 m0, s75
	s_nop 0
	global_load_lds_dwordx4 v[206:207], off
	v_lshl_add_u64 v[206:207], v[210:211], 0, s[68:69]
	s_mov_b32 m0, s66
	s_nop 0
	global_load_lds_dwordx4 v[206:207], off
	v_lshl_add_u64 v[206:207], v[212:213], 0, s[68:69]
	s_mov_b32 m0, s67
	s_nop 0
	global_load_lds_dwordx4 v[206:207], off
	s_waitcnt vmcnt(8) lgkmcnt(0)
	s_barrier
	s_setprio 1
	v_mfma_f32_16x16x32_bf16 v[62:65], v[136:139], v[174:177], v[62:65]
	v_mfma_f32_16x16x32_bf16 v[58:61], v[150:153], v[174:177], v[58:61]
	v_mfma_f32_16x16x32_bf16 v[46:49], v[136:139], v[182:185], v[46:49]
	v_mfma_f32_16x16x32_bf16 v[42:45], v[150:153], v[182:185], v[42:45]
	v_mfma_f32_16x16x32_bf16 v[30:33], v[136:139], v[190:193], v[30:33]
	v_mfma_f32_16x16x32_bf16 v[26:29], v[150:153], v[190:193], v[26:29]
	v_mfma_f32_16x16x32_bf16 v[14:17], v[136:139], v[198:201], v[14:17]
	v_mfma_f32_16x16x32_bf16 v[10:13], v[150:153], v[198:201], v[10:13]
	v_mfma_f32_16x16x32_bf16 v[62:65], v[146:149], v[178:181], v[62:65]
	v_mfma_f32_16x16x32_bf16 v[58:61], v[154:157], v[178:181], v[58:61]
	v_mfma_f32_16x16x32_bf16 v[46:49], v[146:149], v[186:189], v[46:49]
	v_mfma_f32_16x16x32_bf16 v[42:45], v[154:157], v[186:189], v[42:45]
	v_mfma_f32_16x16x32_bf16 v[30:33], v[146:149], v[194:197], v[30:33]
	v_mfma_f32_16x16x32_bf16 v[26:29], v[154:157], v[194:197], v[26:29]
	v_mfma_f32_16x16x32_bf16 v[14:17], v[146:149], v[202:205], v[14:17]
	v_mfma_f32_16x16x32_bf16 v[10:13], v[154:157], v[202:205], v[10:13]
	s_setprio 0
	s_setprio 1
	v_mfma_f32_16x16x32_bf16 v[54:57], v[158:161], v[174:177], v[54:57]
	v_mfma_f32_16x16x32_bf16 v[50:53], v[166:169], v[174:177], v[50:53]
	v_mfma_f32_16x16x32_bf16 v[38:41], v[158:161], v[182:185], v[38:41]
	v_mfma_f32_16x16x32_bf16 v[34:37], v[166:169], v[182:185], v[34:37]
	v_mfma_f32_16x16x32_bf16 v[22:25], v[158:161], v[190:193], v[22:25]
	v_mfma_f32_16x16x32_bf16 v[18:21], v[166:169], v[190:193], v[18:21]
	v_mfma_f32_16x16x32_bf16 v[6:9], v[158:161], v[198:201], v[6:9]
	v_mfma_f32_16x16x32_bf16 v[2:5], v[166:169], v[198:201], v[2:5]
	v_mfma_f32_16x16x32_bf16 v[54:57], v[162:165], v[178:181], v[54:57]
	v_mfma_f32_16x16x32_bf16 v[50:53], v[170:173], v[178:181], v[50:53]
	v_mfma_f32_16x16x32_bf16 v[38:41], v[162:165], v[186:189], v[38:41]
	v_mfma_f32_16x16x32_bf16 v[34:37], v[170:173], v[186:189], v[34:37]
	v_mfma_f32_16x16x32_bf16 v[22:25], v[162:165], v[194:197], v[22:25]
	v_mfma_f32_16x16x32_bf16 v[18:21], v[170:173], v[194:197], v[18:21]
	v_mfma_f32_16x16x32_bf16 v[6:9], v[162:165], v[202:205], v[6:9]
	v_mfma_f32_16x16x32_bf16 v[2:5], v[170:173], v[202:205], v[2:5]
	s_barrier
	s_setprio 0
	s_movk_i32 s15, 0x100
	s_andn2_b64 vcc, exec, s[38:39]
	s_mov_b64 s[40:41], -1
	s_mov_b64 s[38:39], 0
	s_cbranch_vccz .LBB0_601
	s_and_b64 vcc, exec, s[12:13]
	s_cbranch_vccz .LBB0_604
	s_barrier

; #define PG8_STAGE(bufoff, gbase, voff) do { _Pragma("unroll") for (int _i = 0; _i < 2; ++_i) \
;         __builtin_amdgcn_global_load_lds((const unsigned*)((const char*)(gbase) + (voff)[_i]), (LAS unsigned*)(lds + (bufoff) + ldsw + _i * 8192), 16, 0, 0); } while (0)
; #define PG8_LDA(dst, b, h) do { _Pragma("unroll") for (int m = 0; m < 4; ++m) _Pragma("unroll") for (int k = 0; k < 2; ++k) dst[m][k] = *(const LAS bf16x8*)(lds + PG8_SA(b, h) + aoff + m * 2048 + k * 1024); } while (0)
; #define PG8_LDB(dst, b, h) do { _Pragma("unroll") for (int n = 0; n < 2; ++n) _Pragma("unroll") for (int k = 0; k < 2; ++k) dst[n][k] = *(const LAS bf16x8*)(lds + PG8_SB(b, h) + boff + n * 2048 + k * 1024); } while (0)
; #define PG8_WAIT_V(n) asm volatile("s_waitcnt vmcnt(" #n ")" ::: "memory")
; #define PG8_WAIT_L(n) asm volatile("s_waitcnt lgkmcnt(" #n ")" ::: "memory")
; #define PG8_BAR __builtin_amdgcn_s_barrier()
; #define PG8_SCHED __builtin_amdgcn_sched_barrier(0)
; template <class Epi, class Sched, bool ALIGN_EPI, bool LAST_FUSED = false, bool PERM = false, bool CARRY = false>
; __device__ __forceinline__ void gemm_phase(LAS unsigned char* lds, const int tid, const int K, const int lda, const int ldb, const Sched& S, const Epi& E) {
;     ...
;         const bool has_next = S.next(KD_IDX(ui + 1), nxt);
;         const char* nA = has_next ? nxt.a : cA; const char* nB = has_next ? nxt.b : cB; const int nt = cur.nt;
; #pragma unroll 1
;         for (int t = 0; t < nt; t += 2) {
;             const bool last = (t == nt - 2);
;             const char* a1 = cA + (size_t)(t + 1) * kstep;
;             const char* a2 = last ? nA : cA + (size_t)(t + 2) * kstep; const char* b2 = last ? nB : cB + (size_t)(t + 2) * kstep;
;             const char* a3 = a2 + kstep; const char* b3 = b2 + kstep;
;             PG8_LDB(B0, 0, 0); PG8_LDB(B1, 0, 1); PG8_SCHED; PG8_LDA(At, 0, 0); PG8_STAGE(PG8_SA(1, 1), a1 + hstepA, voffA);
;             PG8_WAIT_V(8); PG8_WAIT_L(0); PG8_BAR; PG8_MMA(0, 0, At, B0); PG8_MMA(0, 1, At, B1); PG8_BAR; PG8_SCHED;
;             PG8_LDA(At, 0, 1); PG8_STAGE(PG8_SB(0, 0), b2, voffB); PG8_STAGE(PG8_SB(0, 1), b2 + hstepB, voffB); PG8_STAGE(PG8_SA(0, 0), a2, voffA);
;             PG8_WAIT_V(8); PG8_WAIT_L(0); PG8_BAR; PG8_MMA(1, 0, At, B0); PG8_MMA(1, 1, At, B1); PG8_BAR; PG8_SCHED;
.LBB0_622:
	s_add_u32 s48, s30, s24
	s_addc_u32 s49, s31, 0
	s_add_u32 s42, s48, 0x100
	s_addc_u32 s43, s49, 0
	s_and_b64 s[40:41], s[38:39], exec
	s_cselect_b32 s43, s15, s43
	s_cselect_b32 s42, s14, s42
	s_add_u32 s24, s26, s24
	s_addc_u32 s40, s27, 0
	s_add_u32 s24, s24, 0x100
	s_addc_u32 s40, s40, 0
	s_add_i32 s62, 0, 0x10000
	s_and_b64 s[38:39], s[38:39], exec
	s_cselect_b32 s47, s17, s40
	s_cselect_b32 s46, s16, s24
	s_add_i32 s39, 0, 0x14000
	s_add_u32 s64, s48, 0x30080
	s_addc_u32 s65, s49, 0
	s_add_i32 s67, s62, s29
	s_add_i32 m0, s45, 0xc000
	s_add_i32 s66, s45, 0xe000
	s_add_i32 s70, s67, 0x2000
	s_add_u32 s48, s46, 0x10000
	v_add_u32_e32 v152, s62, v140
	v_add_u32_e32 v168, s39, v140
	s_addc_u32 s49, s47, 0
	s_add_i32 s71, s39, s29
	ds_read_b128 v[136:139], v152
	ds_read_b128 v[144:147], v152 offset:1024
	ds_read_b128 v[148:151], v152 offset:2048
	ds_read_b128 v[152:155], v152 offset:3072
	ds_read_b128 v[156:159], v168
	ds_read_b128 v[160:163], v168 offset:1024
	ds_read_b128 v[164:167], v168 offset:2048
	ds_read_b128 v[168:171], v168 offset:3072
	s_add_i32 s74, s71, 0x2000
	s_add_i32 s75, 0, 0x18000
	s_add_i32 s76, 0, 0x1c000
	s_add_u32 s40, s42, 0x30000
	s_addc_u32 s41, s43, 0
	s_add_i32 s61, s75, s29
	s_add_i32 s24, s61, 0x2000
	s_add_u32 s38, s46, 0x10080
	s_addc_u32 s39, s47, 0
	s_add_i32 s63, s76, s29
	s_add_i32 s62, s63, 0x2000
	v_lshl_add_u64 v[204:205], s[64:65], 0, v[130:131]
	ds_read_b128 v[172:175], v143
	ds_read_b128 v[176:179], v143 offset:1024
	ds_read_b128 v[180:183], v143 offset:2048
	ds_read_b128 v[184:187], v143 offset:3072
	ds_read_b128 v[188:191], v143 offset:4096
	ds_read_b128 v[192:195], v143 offset:5120
	ds_read_b128 v[196:199], v143 offset:6144
	ds_read_b128 v[200:203], v143 offset:7168
	global_load_lds_dwordx4 v[204:205], off
	v_lshl_add_u64 v[204:205], s[64:65], 0, v[132:133]
	s_mov_b32 m0, s66
	s_nop 0
	global_load_lds_dwordx4 v[204:205], off
	s_waitcnt vmcnt(8) lgkmcnt(0)
	s_barrier
	s_setprio 1
	v_mfma_f32_16x16x32_bf16 v[126:129], v[136:139], v[172:175], v[126:129]
	v_mfma_f32_16x16x32_bf16 v[122:125], v[148:151], v[172:175], v[122:125]
	v_mfma_f32_16x16x32_bf16 v[118:121], v[136:139], v[180:183], v[118:121]
	v_mfma_f32_16x16x32_bf16 v[114:117], v[148:151], v[180:183], v[114:117]
	v_mfma_f32_16x16x32_bf16 v[110:113], v[136:139], v[188:191], v[110:113]
	v_mfma_f32_16x16x32_bf16 v[106:109], v[148:151], v[188:191], v[106:109]
	v_mfma_f32_16x16x32_bf16 v[102:105], v[136:139], v[196:199], v[102:105]
	v_mfma_f32_16x16x32_bf16 v[98:101], v[148:151], v[196:199], v[98:101]
	v_mfma_f32_16x16x32_bf16 v[126:129], v[144:147], v[176:179], v[126:129]
	v_mfma_f32_16x16x32_bf16 v[122:125], v[152:155], v[176:179], v[122:125]
	v_mfma_f32_16x16x32_bf16 v[118:121], v[144:147], v[184:187], v[118:121]
	v_mfma_f32_16x16x32_bf16 v[114:117], v[152:155], v[184:187], v[114:117]
	v_mfma_f32_16x16x32_bf16 v[110:113], v[144:147], v[192:195], v[110:113]
	v_mfma_f32_16x16x32_bf16 v[106:109], v[152:155], v[192:195], v[106:109]
	v_mfma_f32_16x16x32_bf16 v[102:105], v[144:147], v[200:203], v[102:105]
	v_mfma_f32_16x16x32_bf16 v[98:101], v[152:155], v[200:203], v[98:101]
	s_setprio 0
	s_setprio 1
	v_mfma_f32_16x16x32_bf16 v[94:97], v[156:159], v[172:175], v[94:97]
	v_mfma_f32_16x16x32_bf16 v[90:93], v[164:167], v[172:175], v[90:93]
	v_mfma_f32_16x16x32_bf16 v[86:89], v[156:159], v[180:183], v[86:89]
	v_mfma_f32_16x16x32_bf16 v[82:85], v[164:167], v[180:183], v[82:85]
	v_mfma_f32_16x16x32_bf16 v[78:81], v[156:159], v[188:191], v[78:81]
	v_mfma_f32_16x16x32_bf16 v[74:77], v[164:167], v[188:191], v[74:77]
	v_mfma_f32_16x16x32_bf16 v[70:73], v[156:159], v[196:199], v[70:73]
	v_mfma_f32_16x16x32_bf16 v[66:69], v[164:167], v[196:199], v[66:69]
	v_mfma_f32_16x16x32_bf16 v[94:97], v[160:163], v[176:179], v[94:97]
	v_mfma_f32_16x16x32_bf16 v[90:93], v[168:171], v[176:179], v[90:93]
	v_mfma_f32_16x16x32_bf16 v[86:89], v[160:163], v[184:187], v[86:89]
	v_mfma_f32_16x16x32_bf16 v[82:85], v[168:171], v[184:187], v[82:85]
	v_mfma_f32_16x16x32_bf16 v[78:81], v[160:163], v[192:195], v[78:81]
	v_mfma_f32_16x16x32_bf16 v[74:77], v[168:171], v[192:195], v[74:77]
	v_mfma_f32_16x16x32_bf16 v[70:73], v[160:163], v[200:203], v[70:73]
	v_mfma_f32_16x16x32_bf16 v[66:69], v[168:171], v[200:203], v[66:69]
	s_barrier
	s_setprio 0
	s_mov_b32 m0, s67
	v_lshl_add_u64 v[204:205], s[46:47], 0, v[0:1]
	ds_read_b128 v[172:175], v143 offset:16384
	ds_read_b128 v[176:179], v143 offset:17408
	ds_read_b128 v[180:183], v143 offset:18432
	ds_read_b128 v[184:187], v143 offset:19456
	ds_read_b128 v[188:191], v143 offset:20480
	ds_read_b128 v[192:195], v143 offset:21504
	ds_read_b128 v[196:199], v143 offset:22528
	ds_read_b128 v[200:203], v143 offset:23552
	global_load_lds_dwordx4 v[204:205], off
	v_lshl_add_u64 v[206:207], s[46:47], 0, v[134:135]
	s_mov_b32 m0, s70
	v_lshl_add_u64 v[208:209], s[48:49], 0, v[0:1]
	global_load_lds_dwordx4 v[206:207], off
	s_mov_b32 m0, s71
	v_lshl_add_u64 v[210:211], s[42:43], 0, v[132:133]
	global_load_lds_dwordx4 v[208:209], off
	v_lshl_add_u64 v[208:209], s[48:49], 0, v[134:135]
	s_mov_b32 m0, s74
	s_nop 0
	global_load_lds_dwordx4 v[208:209], off
	v_lshl_add_u64 v[208:209], s[42:43], 0, v[130:131]
	s_mov_b32 m0, s45
	s_nop 0
	global_load_lds_dwordx4 v[208:209], off
	s_mov_b32 m0, s50
	s_nop 0
	global_load_lds_dwordx4 v[210:211], off
	s_waitcnt vmcnt(8) lgkmcnt(0)
	s_barrier
; #define PG8_STAGE(bufoff, gbase, voff) do { _Pragma("unroll") for (int _i = 0; _i < 2; ++_i) \
;         __builtin_amdgcn_global_load_lds((const unsigned*)((const char*)(gbase) + (voff)[_i]), (LAS unsigned*)(lds + (bufoff) + ldsw + _i * 8192), 16, 0, 0); } while (0)
; #define PG8_LDA(dst, b, h) do { _Pragma("unroll") for (int m = 0; m < 4; ++m) _Pragma("unroll") for (int k = 0; k < 2; ++k) dst[m][k] = *(const LAS bf16x8*)(lds + PG8_SA(b, h) + aoff + m * 2048 + k * 1024); } while (0)
; #define PG8_LDB(dst, b, h) do { _Pragma("unroll") for (int n = 0; n < 2; ++n) _Pragma("unroll") for (int k = 0; k < 2; ++k) dst[n][k] = *(const LAS bf16x8*)(lds + PG8_SB(b, h) + boff + n * 2048 + k * 1024); } while (0)
; #define PG8_MMA(ai, bj, At, Bt) do { __builtin_amdgcn_s_setprio(1); _Pragma("unroll") for (int m = 0; m < 4; ++m) _Pragma("unroll") for (int n = 0; n < 2; ++n) _Pragma("unroll") for (int k = 0; k < 2; ++k) \
;         acc[ai][bj][m][n] = __builtin_amdgcn_mfma_f32_16x16x32_bf16(Bt[n][k], At[m][k], acc[ai][bj][m][n], 0, 0, 0); __builtin_amdgcn_s_setprio(0); } while (0)
; #define PG8_WAIT_V(n) asm volatile("s_waitcnt vmcnt(" #n ")" ::: "memory")
; #define PG8_WAIT_L(n) asm volatile("s_waitcnt lgkmcnt(" #n ")" ::: "memory")
; #define PG8_BAR __builtin_amdgcn_s_barrier()
; #define PG8_SCHED __builtin_amdgcn_sched_barrier(0)
; template <class Epi, class Sched, bool ALIGN_EPI, bool LAST_FUSED = false, bool PERM = false, bool CARRY = false>
; __device__ __forceinline__ void gemm_phase(LAS unsigned char* lds, const int tid, const int K, const int lda, const int ldb, const Sched& S, const Epi& E) {
;     ...
;             PG8_WAIT_V(8); PG8_WAIT_L(0); PG8_BAR; PG8_MMA(1, 0, At, B0); PG8_MMA(1, 1, At, B1); PG8_BAR; PG8_SCHED;
;             PG8_LDB(B0, 1, 0); PG8_LDB(B1, 1, 1); PG8_SCHED; PG8_LDA(At, 1, 0); PG8_STAGE(PG8_SA(0, 1), a2 + hstepA, voffA);
;             PG8_WAIT_V(8); PG8_WAIT_L(0); PG8_BAR; PG8_MMA(0, 0, At, B0); PG8_MMA(0, 1, At, B1); PG8_BAR; PG8_SCHED;
;             PG8_LDA(At, 1, 1); PG8_STAGE(PG8_SB(1, 0), b3, voffB); PG8_STAGE(PG8_SB(1, 1), b3 + hstepB, voffB); PG8_STAGE(PG8_SA(1, 0), a3, voffA);
;             PG8_WAIT_V(8); PG8_WAIT_L(0); PG8_BAR; PG8_MMA(1, 0, At, B0); PG8_MMA(1, 1, At, B1); PG8_BAR; PG8_SCHED;
	s_setprio 1
	v_mfma_f32_16x16x32_bf16 v[62:65], v[136:139], v[172:175], v[62:65]
	v_mfma_f32_16x16x32_bf16 v[58:61], v[148:151], v[172:175], v[58:61]
	v_mfma_f32_16x16x32_bf16 v[54:57], v[136:139], v[180:183], v[54:57]
	v_mfma_f32_16x16x32_bf16 v[50:53], v[148:151], v[180:183], v[50:53]
	v_mfma_f32_16x16x32_bf16 v[46:49], v[136:139], v[188:191], v[46:49]
	v_mfma_f32_16x16x32_bf16 v[42:45], v[148:151], v[188:191], v[42:45]
	v_mfma_f32_16x16x32_bf16 v[38:41], v[136:139], v[196:199], v[38:41]
	v_mfma_f32_16x16x32_bf16 v[34:37], v[148:151], v[196:199], v[34:37]
	v_mfma_f32_16x16x32_bf16 v[62:65], v[144:147], v[176:179], v[62:65]
	v_mfma_f32_16x16x32_bf16 v[58:61], v[152:155], v[176:179], v[58:61]
	v_mfma_f32_16x16x32_bf16 v[54:57], v[144:147], v[184:187], v[54:57]
	v_mfma_f32_16x16x32_bf16 v[50:53], v[152:155], v[184:187], v[50:53]
	v_mfma_f32_16x16x32_bf16 v[46:49], v[144:147], v[192:195], v[46:49]
	v_mfma_f32_16x16x32_bf16 v[42:45], v[152:155], v[192:195], v[42:45]
	v_mfma_f32_16x16x32_bf16 v[38:41], v[144:147], v[200:203], v[38:41]
	v_mfma_f32_16x16x32_bf16 v[34:37], v[152:155], v[200:203], v[34:37]
	s_setprio 0
	s_setprio 1
	v_mfma_f32_16x16x32_bf16 v[30:33], v[156:159], v[172:175], v[30:33]
	v_mfma_f32_16x16x32_bf16 v[26:29], v[164:167], v[172:175], v[26:29]
	v_mfma_f32_16x16x32_bf16 v[22:25], v[156:159], v[180:183], v[22:25]
	v_mfma_f32_16x16x32_bf16 v[18:21], v[164:167], v[180:183], v[18:21]
	v_mfma_f32_16x16x32_bf16 v[14:17], v[156:159], v[188:191], v[14:17]
	v_mfma_f32_16x16x32_bf16 v[10:13], v[164:167], v[188:191], v[10:13]
	v_mfma_f32_16x16x32_bf16 v[6:9], v[156:159], v[196:199], v[6:9]
	v_mfma_f32_16x16x32_bf16 v[2:5], v[164:167], v[196:199], v[2:5]
	v_mfma_f32_16x16x32_bf16 v[30:33], v[160:163], v[176:179], v[30:33]
	v_mfma_f32_16x16x32_bf16 v[26:29], v[168:171], v[176:179], v[26:29]
	v_mfma_f32_16x16x32_bf16 v[22:25], v[160:163], v[184:187], v[22:25]
	v_mfma_f32_16x16x32_bf16 v[18:21], v[168:171], v[184:187], v[18:21]
	v_mfma_f32_16x16x32_bf16 v[14:17], v[160:163], v[192:195], v[14:17]
	v_mfma_f32_16x16x32_bf16 v[10:13], v[168:171], v[192:195], v[10:13]
	v_mfma_f32_16x16x32_bf16 v[6:9], v[160:163], v[200:203], v[6:9]
	v_mfma_f32_16x16x32_bf16 v[2:5], v[168:171], v[200:203], v[2:5]
	s_barrier
	s_setprio 0
	v_add_u32_e32 v152, s75, v140
	v_add_u32_e32 v168, s76, v140
	ds_read_b128 v[136:139], v152
	ds_read_b128 v[144:147], v152 offset:1024
	ds_read_b128 v[148:151], v152 offset:2048
	ds_read_b128 v[152:155], v152 offset:3072
	ds_read_b128 v[156:159], v168
	ds_read_b128 v[160:163], v168 offset:1024
	ds_read_b128 v[164:167], v168 offset:2048
	ds_read_b128 v[168:171], v168 offset:3072
	s_mov_b32 m0, s51
	v_lshl_add_u64 v[212:213], s[40:41], 0, v[130:131]
	ds_read_b128 v[172:175], v143 offset:32768
	ds_read_b128 v[176:179], v143 offset:33792
	ds_read_b128 v[180:183], v143 offset:34816
	ds_read_b128 v[184:187], v143 offset:35840
	ds_read_b128 v[188:191], v143 offset:36864
	ds_read_b128 v[192:195], v143 offset:37888
	ds_read_b128 v[196:199], v143 offset:38912
	ds_read_b128 v[200:203], v143 offset:39936
	global_load_lds_dwordx4 v[212:213], off
	v_lshl_add_u64 v[212:213], s[40:41], 0, v[132:133]
	s_mov_b32 m0, s52
	s_nop 0
	global_load_lds_dwordx4 v[212:213], off
	s_waitcnt vmcnt(8) lgkmcnt(0)
	s_barrier
	s_setprio 1
	v_mfma_f32_16x16x32_bf16 v[126:129], v[136:139], v[172:175], v[126:129]
	v_mfma_f32_16x16x32_bf16 v[122:125], v[148:151], v[172:175], v[122:125]
	v_mfma_f32_16x16x32_bf16 v[118:121], v[136:139], v[180:183], v[118:121]
	v_mfma_f32_16x16x32_bf16 v[114:117], v[148:151], v[180:183], v[114:117]
	v_mfma_f32_16x16x32_bf16 v[110:113], v[136:139], v[188:191], v[110:113]
	v_mfma_f32_16x16x32_bf16 v[106:109], v[148:151], v[188:191], v[106:109]
	v_mfma_f32_16x16x32_bf16 v[102:105], v[136:139], v[196:199], v[102:105]
	v_mfma_f32_16x16x32_bf16 v[98:101], v[148:151], v[196:199], v[98:101]
	v_mfma_f32_16x16x32_bf16 v[126:129], v[144:147], v[176:179], v[126:129]
	v_mfma_f32_16x16x32_bf16 v[122:125], v[152:155], v[176:179], v[122:125]
	v_mfma_f32_16x16x32_bf16 v[118:121], v[144:147], v[184:187], v[118:121]
	v_mfma_f32_16x16x32_bf16 v[114:117], v[152:155], v[184:187], v[114:117]
	v_mfma_f32_16x16x32_bf16 v[110:113], v[144:147], v[192:195], v[110:113]
	v_mfma_f32_16x16x32_bf16 v[106:109], v[152:155], v[192:195], v[106:109]
	v_mfma_f32_16x16x32_bf16 v[102:105], v[144:147], v[200:203], v[102:105]
	v_mfma_f32_16x16x32_bf16 v[98:101], v[152:155], v[200:203], v[98:101]
	s_setprio 0
	s_setprio 1
	v_mfma_f32_16x16x32_bf16 v[94:97], v[156:159], v[172:175], v[94:97]
	v_mfma_f32_16x16x32_bf16 v[90:93], v[164:167], v[172:175], v[90:93]
	v_mfma_f32_16x16x32_bf16 v[86:89], v[156:159], v[180:183], v[86:89]
	v_mfma_f32_16x16x32_bf16 v[82:85], v[164:167], v[180:183], v[82:85]
	v_mfma_f32_16x16x32_bf16 v[78:81], v[156:159], v[188:191], v[78:81]
	v_mfma_f32_16x16x32_bf16 v[74:77], v[164:167], v[188:191], v[74:77]
	v_mfma_f32_16x16x32_bf16 v[70:73], v[156:159], v[196:199], v[70:73]
	v_mfma_f32_16x16x32_bf16 v[66:69], v[164:167], v[196:199], v[66:69]
	v_mfma_f32_16x16x32_bf16 v[94:97], v[160:163], v[176:179], v[94:97]
	v_mfma_f32_16x16x32_bf16 v[90:93], v[168:171], v[176:179], v[90:93]
	v_mfma_f32_16x16x32_bf16 v[86:89], v[160:163], v[184:187], v[86:89]
	v_mfma_f32_16x16x32_bf16 v[82:85], v[168:171], v[184:187], v[82:85]
	v_mfma_f32_16x16x32_bf16 v[78:81], v[160:163], v[192:195], v[78:81]
	v_mfma_f32_16x16x32_bf16 v[74:77], v[168:171], v[192:195], v[74:77]
	v_mfma_f32_16x16x32_bf16 v[70:73], v[160:163], v[200:203], v[70:73]
	v_mfma_f32_16x16x32_bf16 v[66:69], v[168:171], v[200:203], v[66:69]
	s_barrier
; #define PG8_STAGE(bufoff, gbase, voff) do { _Pragma("unroll") for (int _i = 0; _i < 2; ++_i) \
;         __builtin_amdgcn_global_load_lds((const unsigned*)((const char*)(gbase) + (voff)[_i]), (LAS unsigned*)(lds + (bufoff) + ldsw + _i * 8192), 16, 0, 0); } while (0)
; #define PG8_LDA(dst, b, h) do { _Pragma("unroll") for (int m = 0; m < 4; ++m) _Pragma("unroll") for (int k = 0; k < 2; ++k) dst[m][k] = *(const LAS bf16x8*)(lds + PG8_SA(b, h) + aoff + m * 2048 + k * 1024); } while (0)
; #define PG8_MMA(ai, bj, At, Bt) do { __builtin_amdgcn_s_setprio(1); _Pragma("unroll") for (int m = 0; m < 4; ++m) _Pragma("unroll") for (int n = 0; n < 2; ++n) _Pragma("unroll") for (int k = 0; k < 2; ++k) \
;         acc[ai][bj][m][n] = __builtin_amdgcn_mfma_f32_16x16x32_bf16(Bt[n][k], At[m][k], acc[ai][bj][m][n], 0, 0, 0); __builtin_amdgcn_s_setprio(0); } while (0)
; #define PG8_WAIT_V(n) asm volatile("s_waitcnt vmcnt(" #n ")" ::: "memory")
; #define PG8_WAIT_L(n) asm volatile("s_waitcnt lgkmcnt(" #n ")" ::: "memory")
; #define PG8_BAR __builtin_amdgcn_s_barrier()
; #define PG8_SCHED __builtin_amdgcn_sched_barrier(0)
; template <class Epi, class Sched, bool ALIGN_EPI, bool LAST_FUSED = false, bool PERM = false, bool CARRY = false>
; __device__ __forceinline__ void gemm_phase(LAS unsigned char* lds, const int tid, const int K, const int lda, const int ldb, const Sched& S, const Epi& E) {
;     ...
;             PG8_LDA(At, 1, 1); PG8_STAGE(PG8_SB(1, 0), b3, voffB); PG8_STAGE(PG8_SB(1, 1), b3 + hstepB, voffB); PG8_STAGE(PG8_SA(1, 0), a3, voffA);
;             PG8_WAIT_V(8); PG8_WAIT_L(0); PG8_BAR; PG8_MMA(1, 0, At, B0); PG8_MMA(1, 1, At, B1); PG8_BAR; PG8_SCHED;
;         }
;         if constexpr (ALIGN_EPI) { if (wr == 0) PG8_BAR; }
	s_setprio 0
	s_mov_b32 m0, s61
	v_lshl_add_u64 v[204:205], v[204:205], 0, s[68:69]
	ds_read_b128 v[172:175], v143 offset:49152
	ds_read_b128 v[176:179], v143 offset:50176
	ds_read_b128 v[180:183], v143 offset:51200
	ds_read_b128 v[184:187], v143 offset:52224
	ds_read_b128 v[188:191], v143 offset:53248
	ds_read_b128 v[192:195], v143 offset:54272
	ds_read_b128 v[196:199], v143 offset:55296
	ds_read_b128 v[200:203], v143 offset:56320
	global_load_lds_dwordx4 v[204:205], off
	v_lshl_add_u64 v[204:205], v[206:207], 0, s[68:69]
	s_mov_b32 m0, s24
	s_nop 0
	global_load_lds_dwordx4 v[204:205], off
	v_lshl_add_u64 v[204:205], s[38:39], 0, v[0:1]
	s_mov_b32 m0, s63
	s_nop 0
	global_load_lds_dwordx4 v[204:205], off
	v_lshl_add_u64 v[204:205], s[38:39], 0, v[134:135]
	s_mov_b32 m0, s62
	s_nop 0
	global_load_lds_dwordx4 v[204:205], off
	v_lshl_add_u64 v[204:205], v[208:209], 0, s[68:69]
	s_mov_b32 m0, s55
	s_nop 0
	global_load_lds_dwordx4 v[204:205], off
	v_lshl_add_u64 v[204:205], v[210:211], 0, s[68:69]
	s_mov_b32 m0, s56
	s_nop 0
	global_load_lds_dwordx4 v[204:205], off
	s_waitcnt vmcnt(8) lgkmcnt(0)
	s_barrier
	s_setprio 1
	v_mfma_f32_16x16x32_bf16 v[62:65], v[136:139], v[172:175], v[62:65]
	v_mfma_f32_16x16x32_bf16 v[58:61], v[148:151], v[172:175], v[58:61]
	v_mfma_f32_16x16x32_bf16 v[54:57], v[136:139], v[180:183], v[54:57]
	v_mfma_f32_16x16x32_bf16 v[50:53], v[148:151], v[180:183], v[50:53]
	v_mfma_f32_16x16x32_bf16 v[46:49], v[136:139], v[188:191], v[46:49]
	v_mfma_f32_16x16x32_bf16 v[42:45], v[148:151], v[188:191], v[42:45]
	v_mfma_f32_16x16x32_bf16 v[38:41], v[136:139], v[196:199], v[38:41]
	v_mfma_f32_16x16x32_bf16 v[34:37], v[148:151], v[196:199], v[34:37]
	v_mfma_f32_16x16x32_bf16 v[62:65], v[144:147], v[176:179], v[62:65]
	v_mfma_f32_16x16x32_bf16 v[58:61], v[152:155], v[176:179], v[58:61]
	v_mfma_f32_16x16x32_bf16 v[54:57], v[144:147], v[184:187], v[54:57]
	v_mfma_f32_16x16x32_bf16 v[50:53], v[152:155], v[184:187], v[50:53]
	v_mfma_f32_16x16x32_bf16 v[46:49], v[144:147], v[192:195], v[46:49]
	v_mfma_f32_16x16x32_bf16 v[42:45], v[152:155], v[192:195], v[42:45]
	v_mfma_f32_16x16x32_bf16 v[38:41], v[144:147], v[200:203], v[38:41]
	v_mfma_f32_16x16x32_bf16 v[34:37], v[152:155], v[200:203], v[34:37]
	s_setprio 0
	s_setprio 1
	v_mfma_f32_16x16x32_bf16 v[30:33], v[156:159], v[172:175], v[30:33]
	v_mfma_f32_16x16x32_bf16 v[26:29], v[164:167], v[172:175], v[26:29]
	v_mfma_f32_16x16x32_bf16 v[22:25], v[156:159], v[180:183], v[22:25]
	v_mfma_f32_16x16x32_bf16 v[18:21], v[164:167], v[180:183], v[18:21]
	v_mfma_f32_16x16x32_bf16 v[14:17], v[156:159], v[188:191], v[14:17]
	v_mfma_f32_16x16x32_bf16 v[10:13], v[164:167], v[188:191], v[10:13]
	v_mfma_f32_16x16x32_bf16 v[6:9], v[156:159], v[196:199], v[6:9]
	v_mfma_f32_16x16x32_bf16 v[2:5], v[164:167], v[196:199], v[2:5]
	v_mfma_f32_16x16x32_bf16 v[30:33], v[160:163], v[176:179], v[30:33]
	v_mfma_f32_16x16x32_bf16 v[26:29], v[168:171], v[176:179], v[26:29]
	v_mfma_f32_16x16x32_bf16 v[22:25], v[160:163], v[184:187], v[22:25]
	v_mfma_f32_16x16x32_bf16 v[18:21], v[168:171], v[184:187], v[18:21]
	v_mfma_f32_16x16x32_bf16 v[14:17], v[160:163], v[192:195], v[14:17]
	v_mfma_f32_16x16x32_bf16 v[10:13], v[168:171], v[192:195], v[10:13]
	v_mfma_f32_16x16x32_bf16 v[6:9], v[160:163], v[200:203], v[6:9]
	v_mfma_f32_16x16x32_bf16 v[2:5], v[168:171], v[200:203], v[2:5]
	s_barrier
	s_setprio 0
	s_movk_i32 s24, 0x100
	s_andn2_b64 vcc, exec, s[36:37]
	s_mov_b64 s[38:39], -1
	s_mov_b64 s[36:37], 0
	s_cbranch_vccz .LBB0_622
	s_and_b64 vcc, exec, s[10:11]
	s_cbranch_vccz .LBB0_625
	s_barrier

; #define PG8_STAGE(bufoff, gbase, voff) do { _Pragma("unroll") for (int _i = 0; _i < 2; ++_i) \
;         __builtin_amdgcn_global_load_lds((const unsigned*)((const char*)(gbase) + (voff)[_i]), (LAS unsigned*)(lds + (bufoff) + ldsw + _i * 8192), 16, 0, 0); } while (0)
; #define PG8_LDA(dst, b, h) do { _Pragma("unroll") for (int m = 0; m < 4; ++m) _Pragma("unroll") for (int k = 0; k < 2; ++k) dst[m][k] = *(const LAS bf16x8*)(lds + PG8_SA(b, h) + aoff + m * 2048 + k * 1024); } while (0)
; #define PG8_LDB(dst, b, h) do { _Pragma("unroll") for (int n = 0; n < 2; ++n) _Pragma("unroll") for (int k = 0; k < 2; ++k) dst[n][k] = *(const LAS bf16x8*)(lds + PG8_SB(b, h) + boff + n * 2048 + k * 1024); } while (0)
; #define PG8_MMA(ai, bj, At, Bt) do { __builtin_amdgcn_s_setprio(1); _Pragma("unroll") for (int m = 0; m < 4; ++m) _Pragma("unroll") for (int n = 0; n < 2; ++n) _Pragma("unroll") for (int k = 0; k < 2; ++k) \
;         acc[ai][bj][m][n] = __builtin_amdgcn_mfma_f32_16x16x32_bf16(Bt[n][k], At[m][k], acc[ai][bj][m][n], 0, 0, 0); __builtin_amdgcn_s_setprio(0); } while (0)
; #define PG8_WAIT_V(n) asm volatile("s_waitcnt vmcnt(" #n ")" ::: "memory")
; #define PG8_WAIT_L(n) asm volatile("s_waitcnt lgkmcnt(" #n ")" ::: "memory")
; template <class Epi, class Sched, bool ALIGN_EPI, bool LAST_FUSED = false, bool PERM = false, bool CARRY = false>
; __device__ __forceinline__ void gemm_phase(LAS unsigned char* lds, const int tid, const int K, const int lda, const int ldb, const Sched& S, const Epi& E) {
;     ...
;         for (int t = 0; t < nt; t += 2) {
;             const bool last = (t == nt - 2);
;             const char* a1 = cA + (size_t)(t + 1) * kstep;
;             const char* a2 = last ? nA : cA + (size_t)(t + 2) * kstep; const char* b2 = last ? nB : cB + (size_t)(t + 2) * kstep;
;             const char* a3 = a2 + kstep; const char* b3 = b2 + kstep;
;             PG8_LDB(B0, 0, 0); PG8_LDB(B1, 0, 1); PG8_SCHED; PG8_LDA(At, 0, 0); PG8_STAGE(PG8_SA(1, 1), a1 + hstepA, voffA);
;             PG8_WAIT_V(8); PG8_WAIT_L(0); PG8_BAR; PG8_MMA(0, 0, At, B0); PG8_MMA(0, 1, At, B1); PG8_BAR; PG8_SCHED;
;             PG8_LDA(At, 0, 1); PG8_STAGE(PG8_SB(0, 0), b2, voffB); PG8_STAGE(PG8_SB(0, 1), b2 + hstepB, voffB); PG8_STAGE(PG8_SA(0, 0), a2, voffA);
;             PG8_WAIT_V(8); PG8_WAIT_L(0); PG8_BAR; PG8_MMA(1, 0, At, B0); PG8_MMA(1, 1, At, B1); PG8_BAR; PG8_SCHED;
.LBB0_705:
	s_add_u32 s30, s26, 0x100
	s_addc_u32 s31, s27, 0
	s_add_i32 s54, 0, 0x10000
	s_cmp_eq_u32 s53, 8
	s_cselect_b32 s39, s15, s31
	s_cselect_b32 s38, s14, s30
	v_add_u32_e32 v140, s54, v144
	s_cselect_b32 s37, s17, s52
	s_cselect_b32 s36, s16, s13
	s_add_i32 s55, 0, 0x14000
	ds_read_b128 v[146:149], v140
	ds_read_b128 v[150:153], v140 offset:1024
	ds_read_b128 v[154:157], v140 offset:2048
	ds_read_b128 v[158:161], v140 offset:3072
	v_add_u32_e32 v140, s55, v144
	ds_read_b128 v[162:165], v140
	ds_read_b128 v[166:169], v140 offset:1024
	ds_read_b128 v[170:173], v140 offset:2048
	ds_read_b128 v[174:177], v140 offset:3072
	v_lshl_add_u64 v[140:141], s[26:27], 0, v[136:137]
	s_add_i32 m0, s19, 0xc000
	ds_read_b128 v[178:181], v145
	ds_read_b128 v[182:185], v145 offset:1024
	ds_read_b128 v[186:189], v145 offset:2048
	ds_read_b128 v[190:193], v145 offset:3072
	ds_read_b128 v[194:197], v145 offset:4096
	ds_read_b128 v[198:201], v145 offset:5120
	ds_read_b128 v[202:205], v145 offset:6144
	ds_read_b128 v[206:209], v145 offset:7168
	global_load_lds_dwordx4 v[140:141], off
	v_lshl_add_u64 v[140:141], s[26:27], 0, v[138:139]
	s_add_i32 m0, s19, 0xe000
	s_nop 0
	global_load_lds_dwordx4 v[140:141], off
	s_waitcnt vmcnt(8) lgkmcnt(0)
	s_barrier
	s_setprio 1
	v_mfma_f32_16x16x32_bf16 v[126:129], v[146:149], v[178:181], v[126:129]
	v_mfma_f32_16x16x32_bf16 v[122:125], v[154:157], v[178:181], v[122:125]
	v_mfma_f32_16x16x32_bf16 v[118:121], v[146:149], v[186:189], v[118:121]
	v_mfma_f32_16x16x32_bf16 v[110:113], v[154:157], v[186:189], v[110:113]
	v_mfma_f32_16x16x32_bf16 v[102:105], v[146:149], v[194:197], v[102:105]
	v_mfma_f32_16x16x32_bf16 v[94:97], v[154:157], v[194:197], v[94:97]
	v_mfma_f32_16x16x32_bf16 v[86:89], v[146:149], v[202:205], v[86:89]
	v_mfma_f32_16x16x32_bf16 v[78:81], v[154:157], v[202:205], v[78:81]
	v_mfma_f32_16x16x32_bf16 v[126:129], v[150:153], v[182:185], v[126:129]
	v_mfma_f32_16x16x32_bf16 v[122:125], v[158:161], v[182:185], v[122:125]
	v_mfma_f32_16x16x32_bf16 v[118:121], v[150:153], v[190:193], v[118:121]
	v_mfma_f32_16x16x32_bf16 v[110:113], v[158:161], v[190:193], v[110:113]
	v_mfma_f32_16x16x32_bf16 v[102:105], v[150:153], v[198:201], v[102:105]
	v_mfma_f32_16x16x32_bf16 v[94:97], v[158:161], v[198:201], v[94:97]
	v_mfma_f32_16x16x32_bf16 v[86:89], v[150:153], v[206:209], v[86:89]
	v_mfma_f32_16x16x32_bf16 v[78:81], v[158:161], v[206:209], v[78:81]
	s_setprio 0
	s_setprio 1
	v_mfma_f32_16x16x32_bf16 v[114:117], v[162:165], v[178:181], v[114:117]
	v_mfma_f32_16x16x32_bf16 v[106:109], v[170:173], v[178:181], v[106:109]
	v_mfma_f32_16x16x32_bf16 v[98:101], v[162:165], v[186:189], v[98:101]
	v_mfma_f32_16x16x32_bf16 v[90:93], v[170:173], v[186:189], v[90:93]
	v_mfma_f32_16x16x32_bf16 v[82:85], v[162:165], v[194:197], v[82:85]
	v_mfma_f32_16x16x32_bf16 v[74:77], v[170:173], v[194:197], v[74:77]
	v_mfma_f32_16x16x32_bf16 v[70:73], v[162:165], v[202:205], v[70:73]
	v_mfma_f32_16x16x32_bf16 v[66:69], v[170:173], v[202:205], v[66:69]
	v_mfma_f32_16x16x32_bf16 v[114:117], v[166:169], v[182:185], v[114:117]
	v_mfma_f32_16x16x32_bf16 v[106:109], v[174:177], v[182:185], v[106:109]
	v_mfma_f32_16x16x32_bf16 v[98:101], v[166:169], v[190:193], v[98:101]
	v_mfma_f32_16x16x32_bf16 v[90:93], v[174:177], v[190:193], v[90:93]
	v_mfma_f32_16x16x32_bf16 v[82:85], v[166:169], v[198:201], v[82:85]
	v_mfma_f32_16x16x32_bf16 v[74:77], v[174:177], v[198:201], v[74:77]
	v_mfma_f32_16x16x32_bf16 v[70:73], v[166:169], v[206:209], v[70:73]
	v_mfma_f32_16x16x32_bf16 v[66:69], v[174:177], v[206:209], v[66:69]
	s_barrier
	s_setprio 0
	s_add_i32 s26, s54, s40
	v_lshl_add_u64 v[140:141], s[36:37], 0, v[0:1]
	s_mov_b32 m0, s26
	ds_read_b128 v[178:181], v145 offset:16384
	ds_read_b128 v[182:185], v145 offset:17408
	ds_read_b128 v[186:189], v145 offset:18432
	ds_read_b128 v[190:193], v145 offset:19456
	ds_read_b128 v[194:197], v145 offset:20480
	ds_read_b128 v[198:201], v145 offset:21504
	ds_read_b128 v[202:205], v145 offset:22528
	ds_read_b128 v[206:209], v145 offset:23552
	global_load_lds_dwordx4 v[140:141], off
	s_add_i32 m0, s26, 0x2000
	s_add_u32 s26, s36, 0x30000
	v_lshl_add_u64 v[210:211], s[36:37], 0, v[130:131]
	s_addc_u32 s27, s37, 0
	s_add_i32 s54, s55, s40
	global_load_lds_dwordx4 v[210:211], off
	v_lshl_add_u64 v[212:213], s[26:27], 0, v[0:1]
	s_mov_b32 m0, s54
	v_lshl_add_u64 v[214:215], s[38:39], 0, v[132:133]
	global_load_lds_dwordx4 v[212:213], off
	v_lshl_add_u64 v[212:213], s[26:27], 0, v[130:131]
	s_add_i32 m0, s54, 0x2000
	s_nop 0
	global_load_lds_dwordx4 v[212:213], off
	v_lshl_add_u64 v[212:213], s[38:39], 0, v[134:135]
	s_mov_b32 m0, s19
	s_nop 0
	global_load_lds_dwordx4 v[212:213], off
	s_mov_b32 m0, s42
	s_nop 0
	global_load_lds_dwordx4 v[214:215], off
	s_waitcnt vmcnt(8) lgkmcnt(0)
	s_barrier
; #define PG8_STAGE(bufoff, gbase, voff) do { _Pragma("unroll") for (int _i = 0; _i < 2; ++_i) \
;         __builtin_amdgcn_global_load_lds((const unsigned*)((const char*)(gbase) + (voff)[_i]), (LAS unsigned*)(lds + (bufoff) + ldsw + _i * 8192), 16, 0, 0); } while (0)
; #define PG8_LDA(dst, b, h) do { _Pragma("unroll") for (int m = 0; m < 4; ++m) _Pragma("unroll") for (int k = 0; k < 2; ++k) dst[m][k] = *(const LAS bf16x8*)(lds + PG8_SA(b, h) + aoff + m * 2048 + k * 1024); } while (0)
; #define PG8_LDB(dst, b, h) do { _Pragma("unroll") for (int n = 0; n < 2; ++n) _Pragma("unroll") for (int k = 0; k < 2; ++k) dst[n][k] = *(const LAS bf16x8*)(lds + PG8_SB(b, h) + boff + n * 2048 + k * 1024); } while (0)
; #define PG8_MMA(ai, bj, At, Bt) do { __builtin_amdgcn_s_setprio(1); _Pragma("unroll") for (int m = 0; m < 4; ++m) _Pragma("unroll") for (int n = 0; n < 2; ++n) _Pragma("unroll") for (int k = 0; k < 2; ++k) \
;         acc[ai][bj][m][n] = __builtin_amdgcn_mfma_f32_16x16x32_bf16(Bt[n][k], At[m][k], acc[ai][bj][m][n], 0, 0, 0); __builtin_amdgcn_s_setprio(0); } while (0)
; #define PG8_WAIT_V(n) asm volatile("s_waitcnt vmcnt(" #n ")" ::: "memory")
; #define PG8_WAIT_L(n) asm volatile("s_waitcnt lgkmcnt(" #n ")" ::: "memory")
; #define PG8_BAR __builtin_amdgcn_s_barrier()
; #define PG8_SCHED __builtin_amdgcn_sched_barrier(0)
; template <class Epi, class Sched, bool ALIGN_EPI, bool LAST_FUSED = false, bool PERM = false, bool CARRY = false>
; __device__ __forceinline__ void gemm_phase(LAS unsigned char* lds, const int tid, const int K, const int lda, const int ldb, const Sched& S, const Epi& E) {
;     ...
;             PG8_WAIT_V(8); PG8_WAIT_L(0); PG8_BAR; PG8_MMA(1, 0, At, B0); PG8_MMA(1, 1, At, B1); PG8_BAR; PG8_SCHED;
;             PG8_LDB(B0, 1, 0); PG8_LDB(B1, 1, 1); PG8_SCHED; PG8_LDA(At, 1, 0); PG8_STAGE(PG8_SA(0, 1), a2 + hstepA, voffA);
;             PG8_WAIT_V(8); PG8_WAIT_L(0); PG8_BAR; PG8_MMA(0, 0, At, B0); PG8_MMA(0, 1, At, B1); PG8_BAR; PG8_SCHED;
;             PG8_LDA(At, 1, 1); PG8_STAGE(PG8_SB(1, 0), b3, voffB); PG8_STAGE(PG8_SB(1, 1), b3 + hstepB, voffB); PG8_STAGE(PG8_SA(1, 0), a3, voffA);
;             PG8_WAIT_V(8); PG8_WAIT_L(0); PG8_BAR; PG8_MMA(1, 0, At, B0); PG8_MMA(1, 1, At, B1); PG8_BAR; PG8_SCHED;
	s_setprio 1
	v_mfma_f32_16x16x32_bf16 v[62:65], v[146:149], v[178:181], v[62:65]
	v_mfma_f32_16x16x32_bf16 v[58:61], v[154:157], v[178:181], v[58:61]
	v_mfma_f32_16x16x32_bf16 v[54:57], v[146:149], v[186:189], v[54:57]
	v_mfma_f32_16x16x32_bf16 v[46:49], v[154:157], v[186:189], v[46:49]
	v_mfma_f32_16x16x32_bf16 v[38:41], v[146:149], v[194:197], v[38:41]
	v_mfma_f32_16x16x32_bf16 v[30:33], v[154:157], v[194:197], v[30:33]
	v_mfma_f32_16x16x32_bf16 v[22:25], v[146:149], v[202:205], v[22:25]
	v_mfma_f32_16x16x32_bf16 v[14:17], v[154:157], v[202:205], v[14:17]
	v_mfma_f32_16x16x32_bf16 v[62:65], v[150:153], v[182:185], v[62:65]
	v_mfma_f32_16x16x32_bf16 v[58:61], v[158:161], v[182:185], v[58:61]
	v_mfma_f32_16x16x32_bf16 v[54:57], v[150:153], v[190:193], v[54:57]
	v_mfma_f32_16x16x32_bf16 v[46:49], v[158:161], v[190:193], v[46:49]
	v_mfma_f32_16x16x32_bf16 v[38:41], v[150:153], v[198:201], v[38:41]
	v_mfma_f32_16x16x32_bf16 v[30:33], v[158:161], v[198:201], v[30:33]
	v_mfma_f32_16x16x32_bf16 v[22:25], v[150:153], v[206:209], v[22:25]
	v_mfma_f32_16x16x32_bf16 v[14:17], v[158:161], v[206:209], v[14:17]
	s_setprio 0
	s_setprio 1
	v_mfma_f32_16x16x32_bf16 v[50:53], v[162:165], v[178:181], v[50:53]
	v_mfma_f32_16x16x32_bf16 v[42:45], v[170:173], v[178:181], v[42:45]
	v_mfma_f32_16x16x32_bf16 v[34:37], v[162:165], v[186:189], v[34:37]
	v_mfma_f32_16x16x32_bf16 v[26:29], v[170:173], v[186:189], v[26:29]
	v_mfma_f32_16x16x32_bf16 v[18:21], v[162:165], v[194:197], v[18:21]
	v_mfma_f32_16x16x32_bf16 v[10:13], v[170:173], v[194:197], v[10:13]
	v_mfma_f32_16x16x32_bf16 v[6:9], v[162:165], v[202:205], v[6:9]
	v_mfma_f32_16x16x32_bf16 v[2:5], v[170:173], v[202:205], v[2:5]
	v_mfma_f32_16x16x32_bf16 v[50:53], v[166:169], v[182:185], v[50:53]
	v_mfma_f32_16x16x32_bf16 v[42:45], v[174:177], v[182:185], v[42:45]
	v_mfma_f32_16x16x32_bf16 v[34:37], v[166:169], v[190:193], v[34:37]
	v_mfma_f32_16x16x32_bf16 v[26:29], v[174:177], v[190:193], v[26:29]
	v_mfma_f32_16x16x32_bf16 v[18:21], v[166:169], v[198:201], v[18:21]
	v_mfma_f32_16x16x32_bf16 v[10:13], v[174:177], v[198:201], v[10:13]
	v_mfma_f32_16x16x32_bf16 v[6:9], v[166:169], v[206:209], v[6:9]
	v_mfma_f32_16x16x32_bf16 v[2:5], v[174:177], v[206:209], v[2:5]
	s_barrier
	s_setprio 0
	s_add_i32 s54, 0, 0x18000
	s_add_i32 s55, 0, 0x1c000
	v_add_u32_e32 v158, s54, v144
	v_add_u32_e32 v174, s55, v144
	ds_read_b128 v[146:149], v158
	ds_read_b128 v[150:153], v158 offset:1024
	ds_read_b128 v[154:157], v158 offset:2048
	ds_read_b128 v[158:161], v158 offset:3072
	ds_read_b128 v[162:165], v174
	ds_read_b128 v[166:169], v174 offset:1024
	ds_read_b128 v[170:173], v174 offset:2048
	ds_read_b128 v[174:177], v174 offset:3072
	s_add_u32 s26, s38, 0x180000
	s_addc_u32 s27, s39, 0
	s_mov_b32 m0, s43
	v_lshl_add_u64 v[216:217], s[26:27], 0, v[134:135]
	ds_read_b128 v[178:181], v145 offset:32768
	ds_read_b128 v[182:185], v145 offset:33792
	ds_read_b128 v[186:189], v145 offset:34816
	ds_read_b128 v[190:193], v145 offset:35840
	ds_read_b128 v[194:197], v145 offset:36864
	ds_read_b128 v[198:201], v145 offset:37888
	ds_read_b128 v[202:205], v145 offset:38912
	ds_read_b128 v[206:209], v145 offset:39936
	global_load_lds_dwordx4 v[216:217], off
	v_lshl_add_u64 v[216:217], s[26:27], 0, v[132:133]
	s_mov_b32 m0, s44
	s_nop 0
	global_load_lds_dwordx4 v[216:217], off
	s_waitcnt vmcnt(8) lgkmcnt(0)
	s_barrier
	s_setprio 1
	v_mfma_f32_16x16x32_bf16 v[126:129], v[146:149], v[178:181], v[126:129]
	v_mfma_f32_16x16x32_bf16 v[122:125], v[154:157], v[178:181], v[122:125]
	v_mfma_f32_16x16x32_bf16 v[118:121], v[146:149], v[186:189], v[118:121]
	v_mfma_f32_16x16x32_bf16 v[110:113], v[154:157], v[186:189], v[110:113]
	v_mfma_f32_16x16x32_bf16 v[102:105], v[146:149], v[194:197], v[102:105]
	v_mfma_f32_16x16x32_bf16 v[94:97], v[154:157], v[194:197], v[94:97]
	v_mfma_f32_16x16x32_bf16 v[86:89], v[146:149], v[202:205], v[86:89]
	v_mfma_f32_16x16x32_bf16 v[78:81], v[154:157], v[202:205], v[78:81]
	v_mfma_f32_16x16x32_bf16 v[126:129], v[150:153], v[182:185], v[126:129]
	v_mfma_f32_16x16x32_bf16 v[122:125], v[158:161], v[182:185], v[122:125]
	v_mfma_f32_16x16x32_bf16 v[118:121], v[150:153], v[190:193], v[118:121]
	v_mfma_f32_16x16x32_bf16 v[110:113], v[158:161], v[190:193], v[110:113]
	v_mfma_f32_16x16x32_bf16 v[102:105], v[150:153], v[198:201], v[102:105]
	v_mfma_f32_16x16x32_bf16 v[94:97], v[158:161], v[198:201], v[94:97]
	v_mfma_f32_16x16x32_bf16 v[86:89], v[150:153], v[206:209], v[86:89]
	v_mfma_f32_16x16x32_bf16 v[78:81], v[158:161], v[206:209], v[78:81]
	s_setprio 0
	s_setprio 1
	v_mfma_f32_16x16x32_bf16 v[114:117], v[162:165], v[178:181], v[114:117]
	v_mfma_f32_16x16x32_bf16 v[106:109], v[170:173], v[178:181], v[106:109]
	v_mfma_f32_16x16x32_bf16 v[98:101], v[162:165], v[186:189], v[98:101]
	v_mfma_f32_16x16x32_bf16 v[90:93], v[170:173], v[186:189], v[90:93]
	v_mfma_f32_16x16x32_bf16 v[82:85], v[162:165], v[194:197], v[82:85]
	v_mfma_f32_16x16x32_bf16 v[74:77], v[170:173], v[194:197], v[74:77]
	v_mfma_f32_16x16x32_bf16 v[70:73], v[162:165], v[202:205], v[70:73]
	v_mfma_f32_16x16x32_bf16 v[66:69], v[170:173], v[202:205], v[66:69]
	v_mfma_f32_16x16x32_bf16 v[114:117], v[166:169], v[182:185], v[114:117]
	v_mfma_f32_16x16x32_bf16 v[106:109], v[174:177], v[182:185], v[106:109]
	v_mfma_f32_16x16x32_bf16 v[98:101], v[166:169], v[190:193], v[98:101]
	v_mfma_f32_16x16x32_bf16 v[90:93], v[174:177], v[190:193], v[90:93]
	v_mfma_f32_16x16x32_bf16 v[82:85], v[166:169], v[198:201], v[82:85]
	v_mfma_f32_16x16x32_bf16 v[74:77], v[174:177], v[198:201], v[74:77]
	v_mfma_f32_16x16x32_bf16 v[70:73], v[166:169], v[206:209], v[70:73]
	v_mfma_f32_16x16x32_bf16 v[66:69], v[174:177], v[206:209], v[66:69]
	s_barrier
; #define PG8_STAGE(bufoff, gbase, voff) do { _Pragma("unroll") for (int _i = 0; _i < 2; ++_i) \
;         __builtin_amdgcn_global_load_lds((const unsigned*)((const char*)(gbase) + (voff)[_i]), (LAS unsigned*)(lds + (bufoff) + ldsw + _i * 8192), 16, 0, 0); } while (0)
; #define PG8_LDA(dst, b, h) do { _Pragma("unroll") for (int m = 0; m < 4; ++m) _Pragma("unroll") for (int k = 0; k < 2; ++k) dst[m][k] = *(const LAS bf16x8*)(lds + PG8_SA(b, h) + aoff + m * 2048 + k * 1024); } while (0)
; #define PG8_MMA(ai, bj, At, Bt) do { __builtin_amdgcn_s_setprio(1); _Pragma("unroll") for (int m = 0; m < 4; ++m) _Pragma("unroll") for (int n = 0; n < 2; ++n) _Pragma("unroll") for (int k = 0; k < 2; ++k) \
;         acc[ai][bj][m][n] = __builtin_amdgcn_mfma_f32_16x16x32_bf16(Bt[n][k], At[m][k], acc[ai][bj][m][n], 0, 0, 0); __builtin_amdgcn_s_setprio(0); } while (0)
; #define PG8_WAIT_V(n) asm volatile("s_waitcnt vmcnt(" #n ")" ::: "memory")
; #define PG8_WAIT_L(n) asm volatile("s_waitcnt lgkmcnt(" #n ")" ::: "memory")
; #define PG8_BAR __builtin_amdgcn_s_barrier()
; #define PG8_SCHED __builtin_amdgcn_sched_barrier(0)
; template <class Epi, class Sched, bool ALIGN_EPI, bool LAST_FUSED = false, bool PERM = false, bool CARRY = false>
; __device__ __forceinline__ void gemm_phase(LAS unsigned char* lds, const int tid, const int K, const int lda, const int ldb, const Sched& S, const Epi& E) {
;     ...
;             PG8_LDA(At, 1, 1); PG8_STAGE(PG8_SB(1, 0), b3, voffB); PG8_STAGE(PG8_SB(1, 1), b3 + hstepB, voffB); PG8_STAGE(PG8_SA(1, 0), a3, voffA);
;             PG8_WAIT_V(8); PG8_WAIT_L(0); PG8_BAR; PG8_MMA(1, 0, At, B0); PG8_MMA(1, 1, At, B1); PG8_BAR; PG8_SCHED;
;         }
;         if constexpr (ALIGN_EPI) { if (wr == 0) PG8_BAR; }
	s_setprio 0
	s_add_i32 s26, s54, s40
	v_lshl_add_u64 v[140:141], v[140:141], 0, s[68:69]
	s_mov_b32 m0, s26
	ds_read_b128 v[178:181], v145 offset:49152
	ds_read_b128 v[182:185], v145 offset:50176
	ds_read_b128 v[186:189], v145 offset:51200
	ds_read_b128 v[190:193], v145 offset:52224
	ds_read_b128 v[194:197], v145 offset:53248
	ds_read_b128 v[198:201], v145 offset:54272
	ds_read_b128 v[202:205], v145 offset:55296
	ds_read_b128 v[206:209], v145 offset:56320
	global_load_lds_dwordx4 v[140:141], off
	s_add_i32 m0, s26, 0x2000
	s_add_u32 s26, s36, 0x30080
	v_lshl_add_u64 v[140:141], v[210:211], 0, s[68:69]
	s_addc_u32 s27, s37, 0
	s_add_i32 s36, s55, s40
	global_load_lds_dwordx4 v[140:141], off
	v_lshl_add_u64 v[140:141], s[26:27], 0, v[0:1]
	s_mov_b32 m0, s36
	s_nop 0
	global_load_lds_dwordx4 v[140:141], off
	v_lshl_add_u64 v[140:141], s[26:27], 0, v[130:131]
	s_add_i32 m0, s36, 0x2000
	s_nop 0
	global_load_lds_dwordx4 v[140:141], off
	v_lshl_add_u64 v[140:141], v[212:213], 0, s[68:69]
	s_mov_b32 m0, s46
	s_nop 0
	global_load_lds_dwordx4 v[140:141], off
	v_lshl_add_u64 v[140:141], v[214:215], 0, s[68:69]
	s_mov_b32 m0, s47
	s_nop 0
	global_load_lds_dwordx4 v[140:141], off
	s_waitcnt vmcnt(8) lgkmcnt(0)
	s_barrier
	s_setprio 1
	v_mfma_f32_16x16x32_bf16 v[62:65], v[146:149], v[178:181], v[62:65]
	v_mfma_f32_16x16x32_bf16 v[58:61], v[154:157], v[178:181], v[58:61]
	v_mfma_f32_16x16x32_bf16 v[54:57], v[146:149], v[186:189], v[54:57]
	v_mfma_f32_16x16x32_bf16 v[46:49], v[154:157], v[186:189], v[46:49]
	v_mfma_f32_16x16x32_bf16 v[38:41], v[146:149], v[194:197], v[38:41]
	v_mfma_f32_16x16x32_bf16 v[30:33], v[154:157], v[194:197], v[30:33]
	v_mfma_f32_16x16x32_bf16 v[22:25], v[146:149], v[202:205], v[22:25]
	v_mfma_f32_16x16x32_bf16 v[14:17], v[154:157], v[202:205], v[14:17]
	v_mfma_f32_16x16x32_bf16 v[62:65], v[150:153], v[182:185], v[62:65]
	v_mfma_f32_16x16x32_bf16 v[58:61], v[158:161], v[182:185], v[58:61]
	v_mfma_f32_16x16x32_bf16 v[54:57], v[150:153], v[190:193], v[54:57]
	v_mfma_f32_16x16x32_bf16 v[46:49], v[158:161], v[190:193], v[46:49]
	v_mfma_f32_16x16x32_bf16 v[38:41], v[150:153], v[198:201], v[38:41]
	v_mfma_f32_16x16x32_bf16 v[30:33], v[158:161], v[198:201], v[30:33]
	v_mfma_f32_16x16x32_bf16 v[22:25], v[150:153], v[206:209], v[22:25]
	v_mfma_f32_16x16x32_bf16 v[14:17], v[158:161], v[206:209], v[14:17]
	s_setprio 0
	s_setprio 1
	v_mfma_f32_16x16x32_bf16 v[50:53], v[162:165], v[178:181], v[50:53]
	v_mfma_f32_16x16x32_bf16 v[42:45], v[170:173], v[178:181], v[42:45]
	v_mfma_f32_16x16x32_bf16 v[34:37], v[162:165], v[186:189], v[34:37]
	v_mfma_f32_16x16x32_bf16 v[26:29], v[170:173], v[186:189], v[26:29]
	v_mfma_f32_16x16x32_bf16 v[18:21], v[162:165], v[194:197], v[18:21]
	v_mfma_f32_16x16x32_bf16 v[10:13], v[170:173], v[194:197], v[10:13]
	v_mfma_f32_16x16x32_bf16 v[6:9], v[162:165], v[202:205], v[6:9]
	v_mfma_f32_16x16x32_bf16 v[2:5], v[170:173], v[202:205], v[2:5]
	v_mfma_f32_16x16x32_bf16 v[50:53], v[166:169], v[182:185], v[50:53]
	v_mfma_f32_16x16x32_bf16 v[42:45], v[174:177], v[182:185], v[42:45]
	v_mfma_f32_16x16x32_bf16 v[34:37], v[166:169], v[190:193], v[34:37]
	v_mfma_f32_16x16x32_bf16 v[26:29], v[174:177], v[190:193], v[26:29]
	v_mfma_f32_16x16x32_bf16 v[18:21], v[166:169], v[198:201], v[18:21]
	v_mfma_f32_16x16x32_bf16 v[10:13], v[174:177], v[198:201], v[10:13]
	v_mfma_f32_16x16x32_bf16 v[6:9], v[166:169], v[206:209], v[6:9]
	v_mfma_f32_16x16x32_bf16 v[2:5], v[174:177], v[206:209], v[2:5]
	s_barrier
	s_setprio 0
	s_add_i32 s53, s53, 2
	s_add_u32 s13, s13, 0x100
	s_addc_u32 s52, s52, 0
	s_cmp_gt_u32 s53, 9
	s_mov_b64 s[26:27], s[30:31]
	s_cbranch_scc0 .LBB0_705
	s_and_b64 vcc, exec, s[10:11]
	s_cbranch_vccz .LBB0_708
	s_barrier

; #define PG8_STAGE(bufoff, gbase, voff) do { _Pragma("unroll") for (int _i = 0; _i < 2; ++_i) \
;         __builtin_amdgcn_global_load_lds((const unsigned*)((const char*)(gbase) + (voff)[_i]), (LAS unsigned*)(lds + (bufoff) + ldsw + _i * 8192), 16, 0, 0); } while (0)
; #define PG8_LDA(dst, b, h) do { _Pragma("unroll") for (int m = 0; m < 4; ++m) _Pragma("unroll") for (int k = 0; k < 2; ++k) dst[m][k] = *(const LAS bf16x8*)(lds + PG8_SA(b, h) + aoff + m * 2048 + k * 1024); } while (0)
; #define PG8_LDB(dst, b, h) do { _Pragma("unroll") for (int n = 0; n < 2; ++n) _Pragma("unroll") for (int k = 0; k < 2; ++k) dst[n][k] = *(const LAS bf16x8*)(lds + PG8_SB(b, h) + boff + n * 2048 + k * 1024); } while (0)
; #define PG8_MMA(ai, bj, At, Bt) do { __builtin_amdgcn_s_setprio(1); _Pragma("unroll") for (int m = 0; m < 4; ++m) _Pragma("unroll") for (int n = 0; n < 2; ++n) _Pragma("unroll") for (int k = 0; k < 2; ++k) \
;         acc[ai][bj][m][n] = __builtin_amdgcn_mfma_f32_16x16x32_bf16(Bt[n][k], At[m][k], acc[ai][bj][m][n], 0, 0, 0); __builtin_amdgcn_s_setprio(0); } while (0)
; #define PG8_WAIT_V(n) asm volatile("s_waitcnt vmcnt(" #n ")" ::: "memory")
; #define PG8_WAIT_L(n) asm volatile("s_waitcnt lgkmcnt(" #n ")" ::: "memory")
; template <class Epi, class Sched, bool ALIGN_EPI, bool LAST_FUSED = false, bool PERM = false, bool CARRY = false>
; __device__ __forceinline__ void gemm_phase(LAS unsigned char* lds, const int tid, const int K, const int lda, const int ldb, const Sched& S, const Epi& E) {
;     ...
;         for (int t = 0; t < nt; t += 2) {
;             const bool last = (t == nt - 2);
;             const char* a1 = cA + (size_t)(t + 1) * kstep;
;             const char* a2 = last ? nA : cA + (size_t)(t + 2) * kstep; const char* b2 = last ? nB : cB + (size_t)(t + 2) * kstep;
;             const char* a3 = a2 + kstep; const char* b3 = b2 + kstep;
;             PG8_LDB(B0, 0, 0); PG8_LDB(B1, 0, 1); PG8_SCHED; PG8_LDA(At, 0, 0); PG8_STAGE(PG8_SA(1, 1), a1 + hstepA, voffA);
;             PG8_WAIT_V(8); PG8_WAIT_L(0); PG8_BAR; PG8_MMA(0, 0, At, B0); PG8_MMA(0, 1, At, B1); PG8_BAR; PG8_SCHED;
;             PG8_LDA(At, 0, 1); PG8_STAGE(PG8_SB(0, 0), b2, voffB); PG8_STAGE(PG8_SB(0, 1), b2 + hstepB, voffB); PG8_STAGE(PG8_SA(0, 0), a2, voffA);
;             PG8_WAIT_V(8); PG8_WAIT_L(0); PG8_BAR; PG8_MMA(1, 0, At, B0); PG8_MMA(1, 1, At, B1); PG8_BAR; PG8_SCHED;
.LBB0_838:
	s_add_u32 s6, s4, 0xfff80080
	s_addc_u32 s7, s5, -1
	s_add_i32 s29, 0, 0x10000
	s_cmp_eq_u32 s28, 28
	s_cselect_b32 s37, s43, s7
	s_cselect_b32 s36, s42, s6
	v_add_u32_e32 v140, s29, v146
	s_cselect_b32 s7, s71, s23
	s_cselect_b32 s6, s70, s22
	s_add_i32 s31, 0, 0x14000
	ds_read_b128 v[136:139], v140
	ds_read_b128 v[148:151], v140 offset:1024
	ds_read_b128 v[152:155], v140 offset:2048
	ds_read_b128 v[156:159], v140 offset:3072
	v_add_u32_e32 v140, s31, v146
	ds_read_b128 v[160:163], v140
	ds_read_b128 v[164:167], v140 offset:1024
	ds_read_b128 v[168:171], v140 offset:2048
	ds_read_b128 v[172:175], v140 offset:3072
	v_lshl_add_u64 v[140:141], s[4:5], 0, v[132:133]
	s_add_i32 m0, s50, 0xc000
	ds_read_b128 v[176:179], v147
	ds_read_b128 v[180:183], v147 offset:1024
	ds_read_b128 v[184:187], v147 offset:2048
	ds_read_b128 v[188:191], v147 offset:3072
	ds_read_b128 v[192:195], v147 offset:4096
	ds_read_b128 v[196:199], v147 offset:5120
	ds_read_b128 v[200:203], v147 offset:6144
	ds_read_b128 v[204:207], v147 offset:7168
	global_load_lds_dwordx4 v[140:141], off
	v_lshl_add_u64 v[140:141], s[4:5], 0, v[134:135]
	s_add_i32 m0, s50, 0xe000
	s_nop 0
	global_load_lds_dwordx4 v[140:141], off
	s_waitcnt vmcnt(8) lgkmcnt(0)
	s_barrier
	s_setprio 1
	v_mfma_f32_16x16x32_bf16 v[126:129], v[136:139], v[176:179], v[126:129]
	v_mfma_f32_16x16x32_bf16 v[122:125], v[152:155], v[176:179], v[122:125]
	v_mfma_f32_16x16x32_bf16 v[110:113], v[136:139], v[184:187], v[110:113]
	v_mfma_f32_16x16x32_bf16 v[106:109], v[152:155], v[184:187], v[106:109]
	v_mfma_f32_16x16x32_bf16 v[94:97], v[136:139], v[192:195], v[94:97]
	v_mfma_f32_16x16x32_bf16 v[90:93], v[152:155], v[192:195], v[90:93]
	v_mfma_f32_16x16x32_bf16 v[78:81], v[136:139], v[200:203], v[78:81]
	v_mfma_f32_16x16x32_bf16 v[74:77], v[152:155], v[200:203], v[74:77]
	v_mfma_f32_16x16x32_bf16 v[126:129], v[148:151], v[180:183], v[126:129]
	v_mfma_f32_16x16x32_bf16 v[122:125], v[156:159], v[180:183], v[122:125]
	v_mfma_f32_16x16x32_bf16 v[110:113], v[148:151], v[188:191], v[110:113]
	v_mfma_f32_16x16x32_bf16 v[106:109], v[156:159], v[188:191], v[106:109]
	v_mfma_f32_16x16x32_bf16 v[94:97], v[148:151], v[196:199], v[94:97]
	v_mfma_f32_16x16x32_bf16 v[90:93], v[156:159], v[196:199], v[90:93]
	v_mfma_f32_16x16x32_bf16 v[78:81], v[148:151], v[204:207], v[78:81]
	v_mfma_f32_16x16x32_bf16 v[74:77], v[156:159], v[204:207], v[74:77]
	s_setprio 0
	s_setprio 1
	v_mfma_f32_16x16x32_bf16 v[118:121], v[160:163], v[176:179], v[118:121]
	v_mfma_f32_16x16x32_bf16 v[114:117], v[168:171], v[176:179], v[114:117]
	v_mfma_f32_16x16x32_bf16 v[102:105], v[160:163], v[184:187], v[102:105]
	v_mfma_f32_16x16x32_bf16 v[98:101], v[168:171], v[184:187], v[98:101]
	v_mfma_f32_16x16x32_bf16 v[86:89], v[160:163], v[192:195], v[86:89]
	v_mfma_f32_16x16x32_bf16 v[82:85], v[168:171], v[192:195], v[82:85]
	v_mfma_f32_16x16x32_bf16 v[70:73], v[160:163], v[200:203], v[70:73]
	v_mfma_f32_16x16x32_bf16 v[66:69], v[168:171], v[200:203], v[66:69]
	v_mfma_f32_16x16x32_bf16 v[118:121], v[164:167], v[180:183], v[118:121]
	v_mfma_f32_16x16x32_bf16 v[114:117], v[172:175], v[180:183], v[114:117]
	v_mfma_f32_16x16x32_bf16 v[102:105], v[164:167], v[188:191], v[102:105]
	v_mfma_f32_16x16x32_bf16 v[98:101], v[172:175], v[188:191], v[98:101]
	v_mfma_f32_16x16x32_bf16 v[86:89], v[164:167], v[196:199], v[86:89]
	v_mfma_f32_16x16x32_bf16 v[82:85], v[172:175], v[196:199], v[82:85]
	v_mfma_f32_16x16x32_bf16 v[70:73], v[164:167], v[204:207], v[70:73]
	v_mfma_f32_16x16x32_bf16 v[66:69], v[172:175], v[204:207], v[66:69]
	s_barrier
	s_setprio 0
	s_add_i32 s29, s29, s49
	v_lshl_add_u64 v[140:141], s[6:7], 0, v[0:1]
	s_mov_b32 m0, s29
	ds_read_b128 v[176:179], v147 offset:16384
	ds_read_b128 v[180:183], v147 offset:17408
	ds_read_b128 v[184:187], v147 offset:18432
	ds_read_b128 v[188:191], v147 offset:19456
	ds_read_b128 v[192:195], v147 offset:20480
	ds_read_b128 v[196:199], v147 offset:21504
	ds_read_b128 v[200:203], v147 offset:22528
	ds_read_b128 v[204:207], v147 offset:23552
	global_load_lds_dwordx4 v[140:141], off
	s_add_i32 m0, s29, 0x2000
	s_add_u32 s44, s6, 0x80000
	v_lshl_add_u64 v[208:209], s[6:7], 0, v[130:131]
	s_addc_u32 s45, s7, 0
	s_add_i32 s29, s31, s49
	global_load_lds_dwordx4 v[208:209], off
	v_lshl_add_u64 v[210:211], s[44:45], 0, v[0:1]
	s_mov_b32 m0, s29
	v_lshl_add_u64 v[212:213], s[36:37], 0, v[130:131]
	global_load_lds_dwordx4 v[210:211], off
	v_lshl_add_u64 v[210:211], s[44:45], 0, v[130:131]
	s_add_i32 m0, s29, 0x2000
	s_nop 0
	global_load_lds_dwordx4 v[210:211], off
	v_lshl_add_u64 v[210:211], s[36:37], 0, v[0:1]
	s_mov_b32 m0, s50
	s_nop 0
	global_load_lds_dwordx4 v[210:211], off
	s_mov_b32 m0, s51
	s_nop 0
	global_load_lds_dwordx4 v[212:213], off
	s_waitcnt vmcnt(8) lgkmcnt(0)
	s_barrier
; #define PG8_STAGE(bufoff, gbase, voff) do { _Pragma("unroll") for (int _i = 0; _i < 2; ++_i) \
;         __builtin_amdgcn_global_load_lds((const unsigned*)((const char*)(gbase) + (voff)[_i]), (LAS unsigned*)(lds + (bufoff) + ldsw + _i * 8192), 16, 0, 0); } while (0)
; #define PG8_LDA(dst, b, h) do { _Pragma("unroll") for (int m = 0; m < 4; ++m) _Pragma("unroll") for (int k = 0; k < 2; ++k) dst[m][k] = *(const LAS bf16x8*)(lds + PG8_SA(b, h) + aoff + m * 2048 + k * 1024); } while (0)
; #define PG8_LDB(dst, b, h) do { _Pragma("unroll") for (int n = 0; n < 2; ++n) _Pragma("unroll") for (int k = 0; k < 2; ++k) dst[n][k] = *(const LAS bf16x8*)(lds + PG8_SB(b, h) + boff + n * 2048 + k * 1024); } while (0)
; #define PG8_MMA(ai, bj, At, Bt) do { __builtin_amdgcn_s_setprio(1); _Pragma("unroll") for (int m = 0; m < 4; ++m) _Pragma("unroll") for (int n = 0; n < 2; ++n) _Pragma("unroll") for (int k = 0; k < 2; ++k) \
;         acc[ai][bj][m][n] = __builtin_amdgcn_mfma_f32_16x16x32_bf16(Bt[n][k], At[m][k], acc[ai][bj][m][n], 0, 0, 0); __builtin_amdgcn_s_setprio(0); } while (0)
; #define PG8_WAIT_V(n) asm volatile("s_waitcnt vmcnt(" #n ")" ::: "memory")
; #define PG8_WAIT_L(n) asm volatile("s_waitcnt lgkmcnt(" #n ")" ::: "memory")
; #define PG8_BAR __builtin_amdgcn_s_barrier()
; #define PG8_SCHED __builtin_amdgcn_sched_barrier(0)
; template <class Epi, class Sched, bool ALIGN_EPI, bool LAST_FUSED = false, bool PERM = false, bool CARRY = false>
; __device__ __forceinline__ void gemm_phase(LAS unsigned char* lds, const int tid, const int K, const int lda, const int ldb, const Sched& S, const Epi& E) {
;     ...
;             PG8_WAIT_V(8); PG8_WAIT_L(0); PG8_BAR; PG8_MMA(1, 0, At, B0); PG8_MMA(1, 1, At, B1); PG8_BAR; PG8_SCHED;
;             PG8_LDB(B0, 1, 0); PG8_LDB(B1, 1, 1); PG8_SCHED; PG8_LDA(At, 1, 0); PG8_STAGE(PG8_SA(0, 1), a2 + hstepA, voffA);
;             PG8_WAIT_V(8); PG8_WAIT_L(0); PG8_BAR; PG8_MMA(0, 0, At, B0); PG8_MMA(0, 1, At, B1); PG8_BAR; PG8_SCHED;
;             PG8_LDA(At, 1, 1); PG8_STAGE(PG8_SB(1, 0), b3, voffB); PG8_STAGE(PG8_SB(1, 1), b3 + hstepB, voffB); PG8_STAGE(PG8_SA(1, 0), a3, voffA);
;             PG8_WAIT_V(8); PG8_WAIT_L(0); PG8_BAR; PG8_MMA(1, 0, At, B0); PG8_MMA(1, 1, At, B1); PG8_BAR; PG8_SCHED;
	s_setprio 1
	v_mfma_f32_16x16x32_bf16 v[62:65], v[136:139], v[176:179], v[62:65]
	v_mfma_f32_16x16x32_bf16 v[58:61], v[152:155], v[176:179], v[58:61]
	v_mfma_f32_16x16x32_bf16 v[46:49], v[136:139], v[184:187], v[46:49]
	v_mfma_f32_16x16x32_bf16 v[42:45], v[152:155], v[184:187], v[42:45]
	v_mfma_f32_16x16x32_bf16 v[30:33], v[136:139], v[192:195], v[30:33]
	v_mfma_f32_16x16x32_bf16 v[26:29], v[152:155], v[192:195], v[26:29]
	v_mfma_f32_16x16x32_bf16 v[14:17], v[136:139], v[200:203], v[14:17]
	v_mfma_f32_16x16x32_bf16 v[10:13], v[152:155], v[200:203], v[10:13]
	v_mfma_f32_16x16x32_bf16 v[62:65], v[148:151], v[180:183], v[62:65]
	v_mfma_f32_16x16x32_bf16 v[58:61], v[156:159], v[180:183], v[58:61]
	v_mfma_f32_16x16x32_bf16 v[46:49], v[148:151], v[188:191], v[46:49]
	v_mfma_f32_16x16x32_bf16 v[42:45], v[156:159], v[188:191], v[42:45]
	v_mfma_f32_16x16x32_bf16 v[30:33], v[148:151], v[196:199], v[30:33]
	v_mfma_f32_16x16x32_bf16 v[26:29], v[156:159], v[196:199], v[26:29]
	v_mfma_f32_16x16x32_bf16 v[14:17], v[148:151], v[204:207], v[14:17]
	v_mfma_f32_16x16x32_bf16 v[10:13], v[156:159], v[204:207], v[10:13]
	s_setprio 0
	s_setprio 1
	v_mfma_f32_16x16x32_bf16 v[54:57], v[160:163], v[176:179], v[54:57]
	v_mfma_f32_16x16x32_bf16 v[50:53], v[168:171], v[176:179], v[50:53]
	v_mfma_f32_16x16x32_bf16 v[38:41], v[160:163], v[184:187], v[38:41]
	v_mfma_f32_16x16x32_bf16 v[34:37], v[168:171], v[184:187], v[34:37]
	v_mfma_f32_16x16x32_bf16 v[22:25], v[160:163], v[192:195], v[22:25]
	v_mfma_f32_16x16x32_bf16 v[18:21], v[168:171], v[192:195], v[18:21]
	v_mfma_f32_16x16x32_bf16 v[6:9], v[160:163], v[200:203], v[6:9]
	v_mfma_f32_16x16x32_bf16 v[2:5], v[168:171], v[200:203], v[2:5]
	v_mfma_f32_16x16x32_bf16 v[54:57], v[164:167], v[180:183], v[54:57]
	v_mfma_f32_16x16x32_bf16 v[50:53], v[172:175], v[180:183], v[50:53]
	v_mfma_f32_16x16x32_bf16 v[38:41], v[164:167], v[188:191], v[38:41]
	v_mfma_f32_16x16x32_bf16 v[34:37], v[172:175], v[188:191], v[34:37]
	v_mfma_f32_16x16x32_bf16 v[22:25], v[164:167], v[196:199], v[22:25]
	v_mfma_f32_16x16x32_bf16 v[18:21], v[172:175], v[196:199], v[18:21]
	v_mfma_f32_16x16x32_bf16 v[6:9], v[164:167], v[204:207], v[6:9]
	v_mfma_f32_16x16x32_bf16 v[2:5], v[172:175], v[204:207], v[2:5]
	s_barrier
	s_setprio 0
	s_add_i32 s29, 0, 0x18000
	s_add_i32 s31, 0, 0x1c000
	v_add_u32_e32 v156, s29, v146
	v_add_u32_e32 v172, s31, v146
	ds_read_b128 v[136:139], v156
	ds_read_b128 v[148:151], v156 offset:1024
	ds_read_b128 v[152:155], v156 offset:2048
	ds_read_b128 v[156:159], v156 offset:3072
	ds_read_b128 v[160:163], v172
	ds_read_b128 v[164:167], v172 offset:1024
	ds_read_b128 v[168:171], v172 offset:2048
	ds_read_b128 v[172:175], v172 offset:3072
	s_add_u32 s36, s36, 0x80000
	s_addc_u32 s37, s37, 0
	s_mov_b32 m0, s52
	v_lshl_add_u64 v[214:215], s[36:37], 0, v[0:1]
	ds_read_b128 v[176:179], v147 offset:32768
	ds_read_b128 v[180:183], v147 offset:33792
	ds_read_b128 v[184:187], v147 offset:34816
	ds_read_b128 v[188:191], v147 offset:35840
	ds_read_b128 v[192:195], v147 offset:36864
	ds_read_b128 v[196:199], v147 offset:37888
	ds_read_b128 v[200:203], v147 offset:38912
	ds_read_b128 v[204:207], v147 offset:39936
	global_load_lds_dwordx4 v[214:215], off
	v_lshl_add_u64 v[214:215], s[36:37], 0, v[130:131]
	s_mov_b32 m0, s53
	s_nop 0
	global_load_lds_dwordx4 v[214:215], off
	s_waitcnt vmcnt(8) lgkmcnt(0)
	s_barrier
	s_setprio 1
	v_mfma_f32_16x16x32_bf16 v[126:129], v[136:139], v[176:179], v[126:129]
	v_mfma_f32_16x16x32_bf16 v[122:125], v[152:155], v[176:179], v[122:125]
	v_mfma_f32_16x16x32_bf16 v[110:113], v[136:139], v[184:187], v[110:113]
	v_mfma_f32_16x16x32_bf16 v[106:109], v[152:155], v[184:187], v[106:109]
	v_mfma_f32_16x16x32_bf16 v[94:97], v[136:139], v[192:195], v[94:97]
	v_mfma_f32_16x16x32_bf16 v[90:93], v[152:155], v[192:195], v[90:93]
	v_mfma_f32_16x16x32_bf16 v[78:81], v[136:139], v[200:203], v[78:81]
	v_mfma_f32_16x16x32_bf16 v[74:77], v[152:155], v[200:203], v[74:77]
	v_mfma_f32_16x16x32_bf16 v[126:129], v[148:151], v[180:183], v[126:129]
	v_mfma_f32_16x16x32_bf16 v[122:125], v[156:159], v[180:183], v[122:125]
	v_mfma_f32_16x16x32_bf16 v[110:113], v[148:151], v[188:191], v[110:113]
	v_mfma_f32_16x16x32_bf16 v[106:109], v[156:159], v[188:191], v[106:109]
	v_mfma_f32_16x16x32_bf16 v[94:97], v[148:151], v[196:199], v[94:97]
	v_mfma_f32_16x16x32_bf16 v[90:93], v[156:159], v[196:199], v[90:93]
	v_mfma_f32_16x16x32_bf16 v[78:81], v[148:151], v[204:207], v[78:81]
	v_mfma_f32_16x16x32_bf16 v[74:77], v[156:159], v[204:207], v[74:77]
	s_setprio 0
	s_setprio 1
	v_mfma_f32_16x16x32_bf16 v[118:121], v[160:163], v[176:179], v[118:121]
	v_mfma_f32_16x16x32_bf16 v[114:117], v[168:171], v[176:179], v[114:117]
	v_mfma_f32_16x16x32_bf16 v[102:105], v[160:163], v[184:187], v[102:105]
	v_mfma_f32_16x16x32_bf16 v[98:101], v[168:171], v[184:187], v[98:101]
	v_mfma_f32_16x16x32_bf16 v[86:89], v[160:163], v[192:195], v[86:89]
	v_mfma_f32_16x16x32_bf16 v[82:85], v[168:171], v[192:195], v[82:85]
	v_mfma_f32_16x16x32_bf16 v[70:73], v[160:163], v[200:203], v[70:73]
	v_mfma_f32_16x16x32_bf16 v[66:69], v[168:171], v[200:203], v[66:69]
	v_mfma_f32_16x16x32_bf16 v[118:121], v[164:167], v[180:183], v[118:121]
	v_mfma_f32_16x16x32_bf16 v[114:117], v[172:175], v[180:183], v[114:117]
	v_mfma_f32_16x16x32_bf16 v[102:105], v[164:167], v[188:191], v[102:105]
	v_mfma_f32_16x16x32_bf16 v[98:101], v[172:175], v[188:191], v[98:101]
	v_mfma_f32_16x16x32_bf16 v[86:89], v[164:167], v[196:199], v[86:89]
	v_mfma_f32_16x16x32_bf16 v[82:85], v[172:175], v[196:199], v[82:85]
	v_mfma_f32_16x16x32_bf16 v[70:73], v[164:167], v[204:207], v[70:73]
	v_mfma_f32_16x16x32_bf16 v[66:69], v[172:175], v[204:207], v[66:69]
	s_barrier
; #define PG8_STAGE(bufoff, gbase, voff) do { _Pragma("unroll") for (int _i = 0; _i < 2; ++_i) \
;         __builtin_amdgcn_global_load_lds((const unsigned*)((const char*)(gbase) + (voff)[_i]), (LAS unsigned*)(lds + (bufoff) + ldsw + _i * 8192), 16, 0, 0); } while (0)
; #define PG8_LDA(dst, b, h) do { _Pragma("unroll") for (int m = 0; m < 4; ++m) _Pragma("unroll") for (int k = 0; k < 2; ++k) dst[m][k] = *(const LAS bf16x8*)(lds + PG8_SA(b, h) + aoff + m * 2048 + k * 1024); } while (0)
; #define PG8_MMA(ai, bj, At, Bt) do { __builtin_amdgcn_s_setprio(1); _Pragma("unroll") for (int m = 0; m < 4; ++m) _Pragma("unroll") for (int n = 0; n < 2; ++n) _Pragma("unroll") for (int k = 0; k < 2; ++k) \
;         acc[ai][bj][m][n] = __builtin_amdgcn_mfma_f32_16x16x32_bf16(Bt[n][k], At[m][k], acc[ai][bj][m][n], 0, 0, 0); __builtin_amdgcn_s_setprio(0); } while (0)
; #define PG8_WAIT_V(n) asm volatile("s_waitcnt vmcnt(" #n ")" ::: "memory")
; #define PG8_WAIT_L(n) asm volatile("s_waitcnt lgkmcnt(" #n ")" ::: "memory")
; #define PG8_BAR __builtin_amdgcn_s_barrier()
; #define PG8_SCHED __builtin_amdgcn_sched_barrier(0)
; template <class Epi, class Sched, bool ALIGN_EPI, bool LAST_FUSED = false, bool PERM = false, bool CARRY = false>
; __device__ __forceinline__ void gemm_phase(LAS unsigned char* lds, const int tid, const int K, const int lda, const int ldb, const Sched& S, const Epi& E) {
;     ...
;             PG8_LDA(At, 1, 1); PG8_STAGE(PG8_SB(1, 0), b3, voffB); PG8_STAGE(PG8_SB(1, 1), b3 + hstepB, voffB); PG8_STAGE(PG8_SA(1, 0), a3, voffA);
;             PG8_WAIT_V(8); PG8_WAIT_L(0); PG8_BAR; PG8_MMA(1, 0, At, B0); PG8_MMA(1, 1, At, B1); PG8_BAR; PG8_SCHED;
;         }
;         if constexpr (ALIGN_EPI) { if (wr == 0) PG8_BAR; }
	s_setprio 0
	s_add_i32 s29, s29, s49
	v_lshl_add_u64 v[140:141], v[140:141], 0, s[68:69]
	s_mov_b32 m0, s29
	ds_read_b128 v[176:179], v147 offset:49152
	ds_read_b128 v[180:183], v147 offset:50176
	ds_read_b128 v[184:187], v147 offset:51200
	ds_read_b128 v[188:191], v147 offset:52224
	ds_read_b128 v[192:195], v147 offset:53248
	ds_read_b128 v[196:199], v147 offset:54272
	ds_read_b128 v[200:203], v147 offset:55296
	ds_read_b128 v[204:207], v147 offset:56320
	global_load_lds_dwordx4 v[140:141], off
	s_add_i32 m0, s29, 0x2000
	s_add_u32 s6, s6, 0x80080
	v_lshl_add_u64 v[140:141], v[208:209], 0, s[68:69]
	s_addc_u32 s7, s7, 0
	s_add_i32 s29, s31, s49
	global_load_lds_dwordx4 v[140:141], off
	v_lshl_add_u64 v[140:141], s[6:7], 0, v[0:1]
	s_mov_b32 m0, s29
	s_nop 0
	global_load_lds_dwordx4 v[140:141], off
	v_lshl_add_u64 v[140:141], s[6:7], 0, v[130:131]
	s_add_i32 m0, s29, 0x2000
	s_nop 0
	global_load_lds_dwordx4 v[140:141], off
	v_lshl_add_u64 v[140:141], v[210:211], 0, s[68:69]
	s_mov_b32 m0, s55
	s_nop 0
	global_load_lds_dwordx4 v[140:141], off
	v_lshl_add_u64 v[140:141], v[212:213], 0, s[68:69]
	s_mov_b32 m0, s56
	s_nop 0
	global_load_lds_dwordx4 v[140:141], off
	s_waitcnt vmcnt(8) lgkmcnt(0)
	s_barrier
	s_setprio 1
	v_mfma_f32_16x16x32_bf16 v[62:65], v[136:139], v[176:179], v[62:65]
	v_mfma_f32_16x16x32_bf16 v[58:61], v[152:155], v[176:179], v[58:61]
	v_mfma_f32_16x16x32_bf16 v[46:49], v[136:139], v[184:187], v[46:49]
	v_mfma_f32_16x16x32_bf16 v[42:45], v[152:155], v[184:187], v[42:45]
	v_mfma_f32_16x16x32_bf16 v[30:33], v[136:139], v[192:195], v[30:33]
	v_mfma_f32_16x16x32_bf16 v[26:29], v[152:155], v[192:195], v[26:29]
	v_mfma_f32_16x16x32_bf16 v[14:17], v[136:139], v[200:203], v[14:17]
	v_mfma_f32_16x16x32_bf16 v[10:13], v[152:155], v[200:203], v[10:13]
	v_mfma_f32_16x16x32_bf16 v[62:65], v[148:151], v[180:183], v[62:65]
	v_mfma_f32_16x16x32_bf16 v[58:61], v[156:159], v[180:183], v[58:61]
	v_mfma_f32_16x16x32_bf16 v[46:49], v[148:151], v[188:191], v[46:49]
	v_mfma_f32_16x16x32_bf16 v[42:45], v[156:159], v[188:191], v[42:45]
	v_mfma_f32_16x16x32_bf16 v[30:33], v[148:151], v[196:199], v[30:33]
	v_mfma_f32_16x16x32_bf16 v[26:29], v[156:159], v[196:199], v[26:29]
	v_mfma_f32_16x16x32_bf16 v[14:17], v[148:151], v[204:207], v[14:17]
	v_mfma_f32_16x16x32_bf16 v[10:13], v[156:159], v[204:207], v[10:13]
	s_setprio 0
	s_setprio 1
	v_mfma_f32_16x16x32_bf16 v[54:57], v[160:163], v[176:179], v[54:57]
	v_mfma_f32_16x16x32_bf16 v[50:53], v[168:171], v[176:179], v[50:53]
	v_mfma_f32_16x16x32_bf16 v[38:41], v[160:163], v[184:187], v[38:41]
	v_mfma_f32_16x16x32_bf16 v[34:37], v[168:171], v[184:187], v[34:37]
	v_mfma_f32_16x16x32_bf16 v[22:25], v[160:163], v[192:195], v[22:25]
	v_mfma_f32_16x16x32_bf16 v[18:21], v[168:171], v[192:195], v[18:21]
	v_mfma_f32_16x16x32_bf16 v[6:9], v[160:163], v[200:203], v[6:9]
	v_mfma_f32_16x16x32_bf16 v[2:5], v[168:171], v[200:203], v[2:5]
	v_mfma_f32_16x16x32_bf16 v[54:57], v[164:167], v[180:183], v[54:57]
	v_mfma_f32_16x16x32_bf16 v[50:53], v[172:175], v[180:183], v[50:53]
	v_mfma_f32_16x16x32_bf16 v[38:41], v[164:167], v[188:191], v[38:41]
	v_mfma_f32_16x16x32_bf16 v[34:37], v[172:175], v[188:191], v[34:37]
	v_mfma_f32_16x16x32_bf16 v[22:25], v[164:167], v[196:199], v[22:25]
	v_mfma_f32_16x16x32_bf16 v[18:21], v[172:175], v[196:199], v[18:21]
	v_mfma_f32_16x16x32_bf16 v[6:9], v[164:167], v[204:207], v[6:9]
	v_mfma_f32_16x16x32_bf16 v[2:5], v[172:175], v[204:207], v[2:5]
	s_barrier
	s_setprio 0
	s_add_i32 s28, s28, 2
	s_add_u32 s4, s4, 0x100
	s_addc_u32 s5, s5, 0
	s_add_u32 s22, s22, 0x100
	s_addc_u32 s23, s23, 0
	s_cmp_gt_u32 s28, 29
	s_cbranch_scc0 .LBB0_838
	s_and_b64 vcc, exec, s[26:27]
	s_cbranch_vccz .LBB0_841
	s_barrier

; #define PG8_STAGE(bufoff, gbase, voff) do { _Pragma("unroll") for (int _i = 0; _i < 2; ++_i) \
;         __builtin_amdgcn_global_load_lds((const unsigned*)((const char*)(gbase) + (voff)[_i]), (LAS unsigned*)(lds + (bufoff) + ldsw + _i * 8192), 16, 0, 0); } while (0)
; #define PG8_LDA(dst, b, h) do { _Pragma("unroll") for (int m = 0; m < 4; ++m) _Pragma("unroll") for (int k = 0; k < 2; ++k) dst[m][k] = *(const LAS bf16x8*)(lds + PG8_SA(b, h) + aoff + m * 2048 + k * 1024); } while (0)
; #define PG8_LDB(dst, b, h) do { _Pragma("unroll") for (int n = 0; n < 2; ++n) _Pragma("unroll") for (int k = 0; k < 2; ++k) dst[n][k] = *(const LAS bf16x8*)(lds + PG8_SB(b, h) + boff + n * 2048 + k * 1024); } while (0)
; #define PG8_MMA(ai, bj, At, Bt) do { __builtin_amdgcn_s_setprio(1); _Pragma("unroll") for (int m = 0; m < 4; ++m) _Pragma("unroll") for (int n = 0; n < 2; ++n) _Pragma("unroll") for (int k = 0; k < 2; ++k) \
;         acc[ai][bj][m][n] = __builtin_amdgcn_mfma_f32_16x16x32_bf16(Bt[n][k], At[m][k], acc[ai][bj][m][n], 0, 0, 0); __builtin_amdgcn_s_setprio(0); } while (0)
; #define PG8_WAIT_V(n) asm volatile("s_waitcnt vmcnt(" #n ")" ::: "memory")
; #define PG8_WAIT_L(n) asm volatile("s_waitcnt lgkmcnt(" #n ")" ::: "memory")
; template <class Epi, class Sched, bool ALIGN_EPI, bool LAST_FUSED = false, bool PERM = false, bool CARRY = false>
; __device__ __forceinline__ void gemm_phase(LAS unsigned char* lds, const int tid, const int K, const int lda, const int ldb, const Sched& S, const Epi& E) {
;     ...
;         for (int t = 0; t < nt; t += 2) {
;             const bool last = (t == nt - 2);
;             const char* a1 = cA + (size_t)(t + 1) * kstep;
;             const char* a2 = last ? nA : cA + (size_t)(t + 2) * kstep; const char* b2 = last ? nB : cB + (size_t)(t + 2) * kstep;
;             const char* a3 = a2 + kstep; const char* b3 = b2 + kstep;
;             PG8_LDB(B0, 0, 0); PG8_LDB(B1, 0, 1); PG8_SCHED; PG8_LDA(At, 0, 0); PG8_STAGE(PG8_SA(1, 1), a1 + hstepA, voffA);
;             PG8_WAIT_V(8); PG8_WAIT_L(0); PG8_BAR; PG8_MMA(0, 0, At, B0); PG8_MMA(0, 1, At, B1); PG8_BAR; PG8_SCHED;
;             PG8_LDA(At, 0, 1); PG8_STAGE(PG8_SB(0, 0), b2, voffB); PG8_STAGE(PG8_SB(0, 1), b2 + hstepB, voffB); PG8_STAGE(PG8_SA(0, 0), a2, voffA);
;             PG8_WAIT_V(8); PG8_WAIT_L(0); PG8_BAR; PG8_MMA(1, 0, At, B0); PG8_MMA(1, 1, At, B1); PG8_BAR; PG8_SCHED;
.LBB0_1077:
	s_add_u32 s23, s26, 0xfff80080
	s_addc_u32 s28, s27, -1
	s_add_i32 s29, 0, 0x10000
	s_cmp_eq_u32 s15, 28
	s_cselect_b32 s37, s17, s28
	s_cselect_b32 s36, s16, s23
	s_cselect_b32 s31, s19, s13
	s_cselect_b32 s30, s18, s5
	s_add_i32 s23, 0, 0x14000
	v_add_u32_e32 v152, s29, v142
	v_add_u32_e32 v168, s23, v142
	ds_read_b128 v[136:139], v152
	ds_read_b128 v[144:147], v152 offset:1024
	ds_read_b128 v[148:151], v152 offset:2048
	ds_read_b128 v[152:155], v152 offset:3072
	ds_read_b128 v[156:159], v168
	ds_read_b128 v[160:163], v168 offset:1024
	ds_read_b128 v[164:167], v168 offset:2048
	ds_read_b128 v[168:171], v168 offset:3072
	v_lshl_add_u64 v[204:205], s[26:27], 0, v[132:133]
	s_add_i32 m0, s46, 0xc000
	ds_read_b128 v[172:175], v143
	ds_read_b128 v[176:179], v143 offset:1024
	ds_read_b128 v[180:183], v143 offset:2048
	ds_read_b128 v[184:187], v143 offset:3072
	ds_read_b128 v[188:191], v143 offset:4096
	ds_read_b128 v[192:195], v143 offset:5120
	ds_read_b128 v[196:199], v143 offset:6144
	ds_read_b128 v[200:203], v143 offset:7168
	global_load_lds_dwordx4 v[204:205], off
	v_lshl_add_u64 v[204:205], s[26:27], 0, v[134:135]
	s_add_i32 m0, s46, 0xe000
	s_nop 0
	global_load_lds_dwordx4 v[204:205], off
	s_waitcnt vmcnt(8) lgkmcnt(0)
	s_barrier
	s_setprio 1
	v_mfma_f32_16x16x32_bf16 v[126:129], v[136:139], v[172:175], v[126:129]
	v_mfma_f32_16x16x32_bf16 v[122:125], v[148:151], v[172:175], v[122:125]
	v_mfma_f32_16x16x32_bf16 v[110:113], v[136:139], v[180:183], v[110:113]
	v_mfma_f32_16x16x32_bf16 v[106:109], v[148:151], v[180:183], v[106:109]
	v_mfma_f32_16x16x32_bf16 v[94:97], v[136:139], v[188:191], v[94:97]
	v_mfma_f32_16x16x32_bf16 v[90:93], v[148:151], v[188:191], v[90:93]
	v_mfma_f32_16x16x32_bf16 v[78:81], v[136:139], v[196:199], v[78:81]
	v_mfma_f32_16x16x32_bf16 v[74:77], v[148:151], v[196:199], v[74:77]
	v_mfma_f32_16x16x32_bf16 v[126:129], v[144:147], v[176:179], v[126:129]
	v_mfma_f32_16x16x32_bf16 v[122:125], v[152:155], v[176:179], v[122:125]
	v_mfma_f32_16x16x32_bf16 v[110:113], v[144:147], v[184:187], v[110:113]
	v_mfma_f32_16x16x32_bf16 v[106:109], v[152:155], v[184:187], v[106:109]
	v_mfma_f32_16x16x32_bf16 v[94:97], v[144:147], v[192:195], v[94:97]
	v_mfma_f32_16x16x32_bf16 v[90:93], v[152:155], v[192:195], v[90:93]
	v_mfma_f32_16x16x32_bf16 v[78:81], v[144:147], v[200:203], v[78:81]
	v_mfma_f32_16x16x32_bf16 v[74:77], v[152:155], v[200:203], v[74:77]
	s_setprio 0
	s_setprio 1
	v_mfma_f32_16x16x32_bf16 v[118:121], v[156:159], v[172:175], v[118:121]
	v_mfma_f32_16x16x32_bf16 v[114:117], v[164:167], v[172:175], v[114:117]
	v_mfma_f32_16x16x32_bf16 v[102:105], v[156:159], v[180:183], v[102:105]
	v_mfma_f32_16x16x32_bf16 v[98:101], v[164:167], v[180:183], v[98:101]
	v_mfma_f32_16x16x32_bf16 v[86:89], v[156:159], v[188:191], v[86:89]
	v_mfma_f32_16x16x32_bf16 v[82:85], v[164:167], v[188:191], v[82:85]
	v_mfma_f32_16x16x32_bf16 v[70:73], v[156:159], v[196:199], v[70:73]
	v_mfma_f32_16x16x32_bf16 v[66:69], v[164:167], v[196:199], v[66:69]
	v_mfma_f32_16x16x32_bf16 v[118:121], v[160:163], v[176:179], v[118:121]
	v_mfma_f32_16x16x32_bf16 v[114:117], v[168:171], v[176:179], v[114:117]
	v_mfma_f32_16x16x32_bf16 v[102:105], v[160:163], v[184:187], v[102:105]
	v_mfma_f32_16x16x32_bf16 v[98:101], v[168:171], v[184:187], v[98:101]
	v_mfma_f32_16x16x32_bf16 v[86:89], v[160:163], v[192:195], v[86:89]
	v_mfma_f32_16x16x32_bf16 v[82:85], v[168:171], v[192:195], v[82:85]
	v_mfma_f32_16x16x32_bf16 v[70:73], v[160:163], v[200:203], v[70:73]
	v_mfma_f32_16x16x32_bf16 v[66:69], v[168:171], v[200:203], v[66:69]
	s_barrier
	s_setprio 0
	s_add_i32 s28, s29, s43
	v_lshl_add_u64 v[204:205], s[30:31], 0, v[0:1]
	s_mov_b32 m0, s28
	ds_read_b128 v[172:175], v143 offset:16384
	ds_read_b128 v[176:179], v143 offset:17408
	ds_read_b128 v[180:183], v143 offset:18432
	ds_read_b128 v[184:187], v143 offset:19456
	ds_read_b128 v[188:191], v143 offset:20480
	ds_read_b128 v[192:195], v143 offset:21504
	ds_read_b128 v[196:199], v143 offset:22528
	ds_read_b128 v[200:203], v143 offset:23552
	global_load_lds_dwordx4 v[204:205], off
	s_add_i32 m0, s28, 0x2000
	s_add_u32 s28, s30, 0x80000
	v_lshl_add_u64 v[206:207], s[30:31], 0, v[130:131]
	s_addc_u32 s29, s31, 0
	s_add_i32 s23, s23, s43
	global_load_lds_dwordx4 v[206:207], off
	v_lshl_add_u64 v[208:209], s[28:29], 0, v[0:1]
	s_mov_b32 m0, s23
	v_lshl_add_u64 v[210:211], s[36:37], 0, v[130:131]
	global_load_lds_dwordx4 v[208:209], off
	v_lshl_add_u64 v[208:209], s[28:29], 0, v[130:131]
	s_add_i32 m0, s23, 0x2000
	s_nop 0
	global_load_lds_dwordx4 v[208:209], off
	v_lshl_add_u64 v[208:209], s[36:37], 0, v[0:1]
	s_mov_b32 m0, s46
	s_nop 0
	global_load_lds_dwordx4 v[208:209], off
	s_mov_b32 m0, s47
	s_nop 0
	global_load_lds_dwordx4 v[210:211], off
	s_waitcnt vmcnt(8) lgkmcnt(0)
	s_barrier
; #define PG8_STAGE(bufoff, gbase, voff) do { _Pragma("unroll") for (int _i = 0; _i < 2; ++_i) \
;         __builtin_amdgcn_global_load_lds((const unsigned*)((const char*)(gbase) + (voff)[_i]), (LAS unsigned*)(lds + (bufoff) + ldsw + _i * 8192), 16, 0, 0); } while (0)
; #define PG8_LDA(dst, b, h) do { _Pragma("unroll") for (int m = 0; m < 4; ++m) _Pragma("unroll") for (int k = 0; k < 2; ++k) dst[m][k] = *(const LAS bf16x8*)(lds + PG8_SA(b, h) + aoff + m * 2048 + k * 1024); } while (0)
; #define PG8_LDB(dst, b, h) do { _Pragma("unroll") for (int n = 0; n < 2; ++n) _Pragma("unroll") for (int k = 0; k < 2; ++k) dst[n][k] = *(const LAS bf16x8*)(lds + PG8_SB(b, h) + boff + n * 2048 + k * 1024); } while (0)
; #define PG8_MMA(ai, bj, At, Bt) do { __builtin_amdgcn_s_setprio(1); _Pragma("unroll") for (int m = 0; m < 4; ++m) _Pragma("unroll") for (int n = 0; n < 2; ++n) _Pragma("unroll") for (int k = 0; k < 2; ++k) \
;         acc[ai][bj][m][n] = __builtin_amdgcn_mfma_f32_16x16x32_bf16(Bt[n][k], At[m][k], acc[ai][bj][m][n], 0, 0, 0); __builtin_amdgcn_s_setprio(0); } while (0)
; #define PG8_WAIT_V(n) asm volatile("s_waitcnt vmcnt(" #n ")" ::: "memory")
; #define PG8_WAIT_L(n) asm volatile("s_waitcnt lgkmcnt(" #n ")" ::: "memory")
; #define PG8_BAR __builtin_amdgcn_s_barrier()
; #define PG8_SCHED __builtin_amdgcn_sched_barrier(0)
; template <class Epi, class Sched, bool ALIGN_EPI, bool LAST_FUSED = false, bool PERM = false, bool CARRY = false>
; __device__ __forceinline__ void gemm_phase(LAS unsigned char* lds, const int tid, const int K, const int lda, const int ldb, const Sched& S, const Epi& E) {
;     ...
;             PG8_WAIT_V(8); PG8_WAIT_L(0); PG8_BAR; PG8_MMA(1, 0, At, B0); PG8_MMA(1, 1, At, B1); PG8_BAR; PG8_SCHED;
;             PG8_LDB(B0, 1, 0); PG8_LDB(B1, 1, 1); PG8_SCHED; PG8_LDA(At, 1, 0); PG8_STAGE(PG8_SA(0, 1), a2 + hstepA, voffA);
;             PG8_WAIT_V(8); PG8_WAIT_L(0); PG8_BAR; PG8_MMA(0, 0, At, B0); PG8_MMA(0, 1, At, B1); PG8_BAR; PG8_SCHED;
;             PG8_LDA(At, 1, 1); PG8_STAGE(PG8_SB(1, 0), b3, voffB); PG8_STAGE(PG8_SB(1, 1), b3 + hstepB, voffB); PG8_STAGE(PG8_SA(1, 0), a3, voffA);
;             PG8_WAIT_V(8); PG8_WAIT_L(0); PG8_BAR; PG8_MMA(1, 0, At, B0); PG8_MMA(1, 1, At, B1); PG8_BAR; PG8_SCHED;
	s_setprio 1
	v_mfma_f32_16x16x32_bf16 v[62:65], v[136:139], v[172:175], v[62:65]
	v_mfma_f32_16x16x32_bf16 v[58:61], v[148:151], v[172:175], v[58:61]
	v_mfma_f32_16x16x32_bf16 v[46:49], v[136:139], v[180:183], v[46:49]
	v_mfma_f32_16x16x32_bf16 v[42:45], v[148:151], v[180:183], v[42:45]
	v_mfma_f32_16x16x32_bf16 v[30:33], v[136:139], v[188:191], v[30:33]
	v_mfma_f32_16x16x32_bf16 v[26:29], v[148:151], v[188:191], v[26:29]
	v_mfma_f32_16x16x32_bf16 v[14:17], v[136:139], v[196:199], v[14:17]
	v_mfma_f32_16x16x32_bf16 v[10:13], v[148:151], v[196:199], v[10:13]
	v_mfma_f32_16x16x32_bf16 v[62:65], v[144:147], v[176:179], v[62:65]
	v_mfma_f32_16x16x32_bf16 v[58:61], v[152:155], v[176:179], v[58:61]
	v_mfma_f32_16x16x32_bf16 v[46:49], v[144:147], v[184:187], v[46:49]
	v_mfma_f32_16x16x32_bf16 v[42:45], v[152:155], v[184:187], v[42:45]
	v_mfma_f32_16x16x32_bf16 v[30:33], v[144:147], v[192:195], v[30:33]
	v_mfma_f32_16x16x32_bf16 v[26:29], v[152:155], v[192:195], v[26:29]
	v_mfma_f32_16x16x32_bf16 v[14:17], v[144:147], v[200:203], v[14:17]
	v_mfma_f32_16x16x32_bf16 v[10:13], v[152:155], v[200:203], v[10:13]
	s_setprio 0
	s_setprio 1
	v_mfma_f32_16x16x32_bf16 v[54:57], v[156:159], v[172:175], v[54:57]
	v_mfma_f32_16x16x32_bf16 v[50:53], v[164:167], v[172:175], v[50:53]
	v_mfma_f32_16x16x32_bf16 v[38:41], v[156:159], v[180:183], v[38:41]
	v_mfma_f32_16x16x32_bf16 v[34:37], v[164:167], v[180:183], v[34:37]
	v_mfma_f32_16x16x32_bf16 v[22:25], v[156:159], v[188:191], v[22:25]
	v_mfma_f32_16x16x32_bf16 v[18:21], v[164:167], v[188:191], v[18:21]
	v_mfma_f32_16x16x32_bf16 v[6:9], v[156:159], v[196:199], v[6:9]
	v_mfma_f32_16x16x32_bf16 v[2:5], v[164:167], v[196:199], v[2:5]
	v_mfma_f32_16x16x32_bf16 v[54:57], v[160:163], v[176:179], v[54:57]
	v_mfma_f32_16x16x32_bf16 v[50:53], v[168:171], v[176:179], v[50:53]
	v_mfma_f32_16x16x32_bf16 v[38:41], v[160:163], v[184:187], v[38:41]
	v_mfma_f32_16x16x32_bf16 v[34:37], v[168:171], v[184:187], v[34:37]
	v_mfma_f32_16x16x32_bf16 v[22:25], v[160:163], v[192:195], v[22:25]
	v_mfma_f32_16x16x32_bf16 v[18:21], v[168:171], v[192:195], v[18:21]
	v_mfma_f32_16x16x32_bf16 v[6:9], v[160:163], v[200:203], v[6:9]
	v_mfma_f32_16x16x32_bf16 v[2:5], v[168:171], v[200:203], v[2:5]
	s_barrier
	s_setprio 0
	s_add_i32 s23, 0, 0x18000
	s_add_i32 s35, 0, 0x1c000
	v_add_u32_e32 v152, s23, v142
	v_add_u32_e32 v168, s35, v142
	ds_read_b128 v[136:139], v152
	ds_read_b128 v[144:147], v152 offset:1024
	ds_read_b128 v[148:151], v152 offset:2048
	ds_read_b128 v[152:155], v152 offset:3072
	ds_read_b128 v[156:159], v168
	ds_read_b128 v[160:163], v168 offset:1024
	ds_read_b128 v[164:167], v168 offset:2048
	ds_read_b128 v[168:171], v168 offset:3072
	s_add_u32 s28, s36, 0x80000
	s_addc_u32 s29, s37, 0
	s_mov_b32 m0, s48
	v_lshl_add_u64 v[212:213], s[28:29], 0, v[0:1]
	ds_read_b128 v[172:175], v143 offset:32768
	ds_read_b128 v[176:179], v143 offset:33792
	ds_read_b128 v[180:183], v143 offset:34816
	ds_read_b128 v[184:187], v143 offset:35840
	ds_read_b128 v[188:191], v143 offset:36864
	ds_read_b128 v[192:195], v143 offset:37888
	ds_read_b128 v[196:199], v143 offset:38912
	ds_read_b128 v[200:203], v143 offset:39936
	global_load_lds_dwordx4 v[212:213], off
	v_lshl_add_u64 v[212:213], s[28:29], 0, v[130:131]
	s_mov_b32 m0, s49
	s_nop 0
	global_load_lds_dwordx4 v[212:213], off
	s_waitcnt vmcnt(8) lgkmcnt(0)
	s_barrier
	s_setprio 1
	v_mfma_f32_16x16x32_bf16 v[126:129], v[136:139], v[172:175], v[126:129]
	v_mfma_f32_16x16x32_bf16 v[122:125], v[148:151], v[172:175], v[122:125]
	v_mfma_f32_16x16x32_bf16 v[110:113], v[136:139], v[180:183], v[110:113]
	v_mfma_f32_16x16x32_bf16 v[106:109], v[148:151], v[180:183], v[106:109]
	v_mfma_f32_16x16x32_bf16 v[94:97], v[136:139], v[188:191], v[94:97]
	v_mfma_f32_16x16x32_bf16 v[90:93], v[148:151], v[188:191], v[90:93]
	v_mfma_f32_16x16x32_bf16 v[78:81], v[136:139], v[196:199], v[78:81]
	v_mfma_f32_16x16x32_bf16 v[74:77], v[148:151], v[196:199], v[74:77]
	v_mfma_f32_16x16x32_bf16 v[126:129], v[144:147], v[176:179], v[126:129]
	v_mfma_f32_16x16x32_bf16 v[122:125], v[152:155], v[176:179], v[122:125]
	v_mfma_f32_16x16x32_bf16 v[110:113], v[144:147], v[184:187], v[110:113]
	v_mfma_f32_16x16x32_bf16 v[106:109], v[152:155], v[184:187], v[106:109]
	v_mfma_f32_16x16x32_bf16 v[94:97], v[144:147], v[192:195], v[94:97]
	v_mfma_f32_16x16x32_bf16 v[90:93], v[152:155], v[192:195], v[90:93]
	v_mfma_f32_16x16x32_bf16 v[78:81], v[144:147], v[200:203], v[78:81]
	v_mfma_f32_16x16x32_bf16 v[74:77], v[152:155], v[200:203], v[74:77]
	s_setprio 0
	s_setprio 1
	v_mfma_f32_16x16x32_bf16 v[118:121], v[156:159], v[172:175], v[118:121]
	v_mfma_f32_16x16x32_bf16 v[114:117], v[164:167], v[172:175], v[114:117]
	v_mfma_f32_16x16x32_bf16 v[102:105], v[156:159], v[180:183], v[102:105]
	v_mfma_f32_16x16x32_bf16 v[98:101], v[164:167], v[180:183], v[98:101]
	v_mfma_f32_16x16x32_bf16 v[86:89], v[156:159], v[188:191], v[86:89]
	v_mfma_f32_16x16x32_bf16 v[82:85], v[164:167], v[188:191], v[82:85]
	v_mfma_f32_16x16x32_bf16 v[70:73], v[156:159], v[196:199], v[70:73]
	v_mfma_f32_16x16x32_bf16 v[66:69], v[164:167], v[196:199], v[66:69]
	v_mfma_f32_16x16x32_bf16 v[118:121], v[160:163], v[176:179], v[118:121]
	v_mfma_f32_16x16x32_bf16 v[114:117], v[168:171], v[176:179], v[114:117]
	v_mfma_f32_16x16x32_bf16 v[102:105], v[160:163], v[184:187], v[102:105]
	v_mfma_f32_16x16x32_bf16 v[98:101], v[168:171], v[184:187], v[98:101]
	v_mfma_f32_16x16x32_bf16 v[86:89], v[160:163], v[192:195], v[86:89]
	v_mfma_f32_16x16x32_bf16 v[82:85], v[168:171], v[192:195], v[82:85]
	v_mfma_f32_16x16x32_bf16 v[70:73], v[160:163], v[200:203], v[70:73]
	v_mfma_f32_16x16x32_bf16 v[66:69], v[168:171], v[200:203], v[66:69]
	s_barrier
; #define PG8_STAGE(bufoff, gbase, voff) do { _Pragma("unroll") for (int _i = 0; _i < 2; ++_i) \
;         __builtin_amdgcn_global_load_lds((const unsigned*)((const char*)(gbase) + (voff)[_i]), (LAS unsigned*)(lds + (bufoff) + ldsw + _i * 8192), 16, 0, 0); } while (0)
; #define PG8_LDA(dst, b, h) do { _Pragma("unroll") for (int m = 0; m < 4; ++m) _Pragma("unroll") for (int k = 0; k < 2; ++k) dst[m][k] = *(const LAS bf16x8*)(lds + PG8_SA(b, h) + aoff + m * 2048 + k * 1024); } while (0)
; #define PG8_MMA(ai, bj, At, Bt) do { __builtin_amdgcn_s_setprio(1); _Pragma("unroll") for (int m = 0; m < 4; ++m) _Pragma("unroll") for (int n = 0; n < 2; ++n) _Pragma("unroll") for (int k = 0; k < 2; ++k) \
;         acc[ai][bj][m][n] = __builtin_amdgcn_mfma_f32_16x16x32_bf16(Bt[n][k], At[m][k], acc[ai][bj][m][n], 0, 0, 0); __builtin_amdgcn_s_setprio(0); } while (0)
; #define PG8_WAIT_V(n) asm volatile("s_waitcnt vmcnt(" #n ")" ::: "memory")
; #define PG8_WAIT_L(n) asm volatile("s_waitcnt lgkmcnt(" #n ")" ::: "memory")
; #define PG8_BAR __builtin_amdgcn_s_barrier()
; #define PG8_SCHED __builtin_amdgcn_sched_barrier(0)
; template <class Epi, class Sched, bool ALIGN_EPI, bool LAST_FUSED = false, bool PERM = false, bool CARRY = false>
; __device__ __forceinline__ void gemm_phase(LAS unsigned char* lds, const int tid, const int K, const int lda, const int ldb, const Sched& S, const Epi& E) {
;     ...
;             PG8_LDA(At, 1, 1); PG8_STAGE(PG8_SB(1, 0), b3, voffB); PG8_STAGE(PG8_SB(1, 1), b3 + hstepB, voffB); PG8_STAGE(PG8_SA(1, 0), a3, voffA);
;             PG8_WAIT_V(8); PG8_WAIT_L(0); PG8_BAR; PG8_MMA(1, 0, At, B0); PG8_MMA(1, 1, At, B1); PG8_BAR; PG8_SCHED;
;         }
;         if constexpr (ALIGN_EPI) { if (wr == 0) PG8_BAR; }
	s_setprio 0
	s_add_i32 s23, s23, s43
	v_lshl_add_u64 v[204:205], v[204:205], 0, s[68:69]
	s_mov_b32 m0, s23
	ds_read_b128 v[172:175], v143 offset:49152
	ds_read_b128 v[176:179], v143 offset:50176
	ds_read_b128 v[180:183], v143 offset:51200
	ds_read_b128 v[184:187], v143 offset:52224
	ds_read_b128 v[188:191], v143 offset:53248
	ds_read_b128 v[192:195], v143 offset:54272
	ds_read_b128 v[196:199], v143 offset:55296
	ds_read_b128 v[200:203], v143 offset:56320
	global_load_lds_dwordx4 v[204:205], off
	s_add_i32 m0, s23, 0x2000
	s_add_u32 s28, s30, 0x80080
	v_lshl_add_u64 v[204:205], v[206:207], 0, s[68:69]
	s_addc_u32 s29, s31, 0
	s_add_i32 s23, s35, s43
	global_load_lds_dwordx4 v[204:205], off
	v_lshl_add_u64 v[204:205], s[28:29], 0, v[0:1]
	s_mov_b32 m0, s23
	s_nop 0
	global_load_lds_dwordx4 v[204:205], off
	v_lshl_add_u64 v[204:205], s[28:29], 0, v[130:131]
	s_add_i32 m0, s23, 0x2000
	s_nop 0
	global_load_lds_dwordx4 v[204:205], off
	v_lshl_add_u64 v[204:205], v[208:209], 0, s[68:69]
	s_mov_b32 m0, s51
	s_nop 0
	global_load_lds_dwordx4 v[204:205], off
	v_lshl_add_u64 v[204:205], v[210:211], 0, s[68:69]
	s_mov_b32 m0, s52
	s_nop 0
	global_load_lds_dwordx4 v[204:205], off
	s_waitcnt vmcnt(8) lgkmcnt(0)
	s_barrier
	s_setprio 1
	v_mfma_f32_16x16x32_bf16 v[62:65], v[136:139], v[172:175], v[62:65]
	v_mfma_f32_16x16x32_bf16 v[58:61], v[148:151], v[172:175], v[58:61]
	v_mfma_f32_16x16x32_bf16 v[46:49], v[136:139], v[180:183], v[46:49]
	v_mfma_f32_16x16x32_bf16 v[42:45], v[148:151], v[180:183], v[42:45]
	v_mfma_f32_16x16x32_bf16 v[30:33], v[136:139], v[188:191], v[30:33]
	v_mfma_f32_16x16x32_bf16 v[26:29], v[148:151], v[188:191], v[26:29]
	v_mfma_f32_16x16x32_bf16 v[14:17], v[136:139], v[196:199], v[14:17]
	v_mfma_f32_16x16x32_bf16 v[10:13], v[148:151], v[196:199], v[10:13]
	v_mfma_f32_16x16x32_bf16 v[62:65], v[144:147], v[176:179], v[62:65]
	v_mfma_f32_16x16x32_bf16 v[58:61], v[152:155], v[176:179], v[58:61]
	v_mfma_f32_16x16x32_bf16 v[46:49], v[144:147], v[184:187], v[46:49]
	v_mfma_f32_16x16x32_bf16 v[42:45], v[152:155], v[184:187], v[42:45]
	v_mfma_f32_16x16x32_bf16 v[30:33], v[144:147], v[192:195], v[30:33]
	v_mfma_f32_16x16x32_bf16 v[26:29], v[152:155], v[192:195], v[26:29]
	v_mfma_f32_16x16x32_bf16 v[14:17], v[144:147], v[200:203], v[14:17]
	v_mfma_f32_16x16x32_bf16 v[10:13], v[152:155], v[200:203], v[10:13]
	s_setprio 0
	s_setprio 1
	v_mfma_f32_16x16x32_bf16 v[54:57], v[156:159], v[172:175], v[54:57]
	v_mfma_f32_16x16x32_bf16 v[50:53], v[164:167], v[172:175], v[50:53]
	v_mfma_f32_16x16x32_bf16 v[38:41], v[156:159], v[180:183], v[38:41]
	v_mfma_f32_16x16x32_bf16 v[34:37], v[164:167], v[180:183], v[34:37]
	v_mfma_f32_16x16x32_bf16 v[22:25], v[156:159], v[188:191], v[22:25]
	v_mfma_f32_16x16x32_bf16 v[18:21], v[164:167], v[188:191], v[18:21]
	v_mfma_f32_16x16x32_bf16 v[6:9], v[156:159], v[196:199], v[6:9]
	v_mfma_f32_16x16x32_bf16 v[2:5], v[164:167], v[196:199], v[2:5]
	v_mfma_f32_16x16x32_bf16 v[54:57], v[160:163], v[176:179], v[54:57]
	v_mfma_f32_16x16x32_bf16 v[50:53], v[168:171], v[176:179], v[50:53]
	v_mfma_f32_16x16x32_bf16 v[38:41], v[160:163], v[184:187], v[38:41]
	v_mfma_f32_16x16x32_bf16 v[34:37], v[168:171], v[184:187], v[34:37]
	v_mfma_f32_16x16x32_bf16 v[22:25], v[160:163], v[192:195], v[22:25]
	v_mfma_f32_16x16x32_bf16 v[18:21], v[168:171], v[192:195], v[18:21]
	v_mfma_f32_16x16x32_bf16 v[6:9], v[160:163], v[200:203], v[6:9]
	v_mfma_f32_16x16x32_bf16 v[2:5], v[168:171], v[200:203], v[2:5]
	s_barrier
	s_setprio 0
	s_add_i32 s15, s15, 2
	s_add_u32 s26, s26, 0x100
	s_addc_u32 s27, s27, 0
	s_add_u32 s5, s5, 0x100
	s_addc_u32 s13, s13, 0
	s_cmp_gt_u32 s15, 29
	s_cbranch_scc0 .LBB0_1077
	s_and_b64 vcc, exec, s[10:11]
	s_cbranch_vccz .LBB0_1080
	s_barrier

; #define PG8_STAGE(bufoff, gbase, voff) do { _Pragma("unroll") for (int _i = 0; _i < 2; ++_i) \
;         __builtin_amdgcn_global_load_lds((const unsigned*)((const char*)(gbase) + (voff)[_i]), (LAS unsigned*)(lds + (bufoff) + ldsw + _i * 8192), 16, 0, 0); } while (0)
; #define PG8_LDA(dst, b, h) do { _Pragma("unroll") for (int m = 0; m < 4; ++m) _Pragma("unroll") for (int k = 0; k < 2; ++k) dst[m][k] = *(const LAS bf16x8*)(lds + PG8_SA(b, h) + aoff + m * 2048 + k * 1024); } while (0)
; #define PG8_LDB(dst, b, h) do { _Pragma("unroll") for (int n = 0; n < 2; ++n) _Pragma("unroll") for (int k = 0; k < 2; ++k) dst[n][k] = *(const LAS bf16x8*)(lds + PG8_SB(b, h) + boff + n * 2048 + k * 1024); } while (0)
; #define PG8_WAIT_V(n) asm volatile("s_waitcnt vmcnt(" #n ")" ::: "memory")
; #define PG8_WAIT_L(n) asm volatile("s_waitcnt lgkmcnt(" #n ")" ::: "memory")
; #define PG8_BAR __builtin_amdgcn_s_barrier()
; #define PG8_SCHED __builtin_amdgcn_sched_barrier(0)
; template <class Epi, class Sched, bool ALIGN_EPI, bool LAST_FUSED = false, bool PERM = false, bool CARRY = false>
; __device__ __forceinline__ void gemm_phase(LAS unsigned char* lds, const int tid, const int K, const int lda, const int ldb, const Sched& S, const Epi& E) {
;     ...
;         const bool has_next = S.next(KD_IDX(ui + 1), nxt);
;         const char* nA = has_next ? nxt.a : cA; const char* nB = has_next ? nxt.b : cB; const int nt = cur.nt;
; #pragma unroll 1
;         for (int t = 0; t < nt; t += 2) {
;             const bool last = (t == nt - 2);
;             const char* a1 = cA + (size_t)(t + 1) * kstep;
;             const char* a2 = last ? nA : cA + (size_t)(t + 2) * kstep; const char* b2 = last ? nB : cB + (size_t)(t + 2) * kstep;
;             const char* a3 = a2 + kstep; const char* b3 = b2 + kstep;
;             PG8_LDB(B0, 0, 0); PG8_LDB(B1, 0, 1); PG8_SCHED; PG8_LDA(At, 0, 0); PG8_STAGE(PG8_SA(1, 1), a1 + hstepA, voffA);
;             PG8_WAIT_V(8); PG8_WAIT_L(0); PG8_BAR; PG8_MMA(0, 0, At, B0); PG8_MMA(0, 1, At, B1); PG8_BAR; PG8_SCHED;
;             PG8_LDA(At, 0, 1); PG8_STAGE(PG8_SB(0, 0), b2, voffB); PG8_STAGE(PG8_SB(0, 1), b2 + hstepB, voffB); PG8_STAGE(PG8_SA(0, 0), a2, voffA);
;             PG8_WAIT_V(8); PG8_WAIT_L(0); PG8_BAR; PG8_MMA(1, 0, At, B0); PG8_MMA(1, 1, At, B1); PG8_BAR; PG8_SCHED;
.LBB0_1367:
	s_add_u32 s19, s38, s17
	s_addc_u32 s23, s39, 0
	s_add_u32 s35, s19, 0x100
	s_addc_u32 s37, s23, 0
	s_and_b64 s[28:29], s[46:47], exec
	s_cselect_b32 s51, s27, s37
	s_cselect_b32 s50, s26, s35
	s_add_u32 s17, s40, s17
	s_addc_u32 s28, s41, 0
	s_add_u32 s17, s17, 0x100
	s_addc_u32 s35, s28, 0
	s_add_i32 s45, 0, 0x10000
	s_and_b64 s[28:29], s[46:47], exec
	s_cselect_b32 s55, s31, s35
	s_cselect_b32 s54, s30, s17
	s_add_i32 s47, 0, 0x14000
	s_add_u32 s52, s19, 0x80080
	s_addc_u32 s53, s23, 0
	s_add_i32 s44, s45, s61
	s_add_i32 m0, s63, 0xc000
	s_add_i32 s79, s63, 0xe000
	s_add_i32 s29, s44, 0x2000
	s_add_u32 s58, s54, 0x10000
	v_add_u32_e32 v46, s45, v216
	v_add_u32_e32 v164, s47, v216
	s_addc_u32 s59, s55, 0
	s_add_i32 s37, s47, s61
	ds_read_b128 v[26:29], v46
	ds_read_b128 v[34:37], v46 offset:1024
	ds_read_b128 v[38:41], v46 offset:2048
	ds_read_b128 v[46:49], v46 offset:3072
	ds_read_b128 v[54:57], v164
	ds_read_b128 v[58:61], v164 offset:1024
	ds_read_b128 v[160:163], v164 offset:2048
	ds_read_b128 v[164:167], v164 offset:3072
	s_add_i32 s35, s37, 0x2000
	s_add_i32 s28, 0, 0x18000
	s_add_i32 s23, 0, 0x1c000
	s_add_u32 s48, s50, 0x80000
	s_addc_u32 s49, s51, 0
	s_add_i32 s19, s28, s61
	s_add_i32 s17, s19, 0x2000
	s_add_u32 s46, s54, 0x10080
	s_addc_u32 s47, s55, 0
	s_add_i32 s78, s23, s61
	s_add_i32 s45, s78, 0x2000
	v_lshl_add_u64 v[200:201], s[52:53], 0, v[158:159]
	ds_read_b128 v[168:171], v217
	ds_read_b128 v[172:175], v217 offset:1024
	ds_read_b128 v[176:179], v217 offset:2048
	ds_read_b128 v[180:183], v217 offset:3072
	ds_read_b128 v[184:187], v217 offset:4096
	ds_read_b128 v[188:191], v217 offset:5120
	ds_read_b128 v[192:195], v217 offset:6144
	ds_read_b128 v[196:199], v217 offset:7168
	global_load_lds_dwordx4 v[200:201], off
	v_lshl_add_u64 v[200:201], s[52:53], 0, v[156:157]
	s_mov_b32 m0, s79
	s_nop 0
	global_load_lds_dwordx4 v[200:201], off
	s_waitcnt vmcnt(8) lgkmcnt(0)
	s_barrier
	s_setprio 1
	v_mfma_f32_16x16x32_bf16 v[150:153], v[26:29], v[168:171], v[150:153]
	v_mfma_f32_16x16x32_bf16 v[142:145], v[38:41], v[168:171], v[142:145]
	v_mfma_f32_16x16x32_bf16 v[134:137], v[26:29], v[176:179], v[134:137]
	v_mfma_f32_16x16x32_bf16 v[126:129], v[38:41], v[176:179], v[126:129]
	v_mfma_f32_16x16x32_bf16 v[118:121], v[26:29], v[184:187], v[118:121]
	v_mfma_f32_16x16x32_bf16 v[110:113], v[38:41], v[184:187], v[110:113]
	v_mfma_f32_16x16x32_bf16 v[102:105], v[26:29], v[192:195], v[102:105]
	v_mfma_f32_16x16x32_bf16 v[94:97], v[38:41], v[192:195], v[94:97]
	v_mfma_f32_16x16x32_bf16 v[150:153], v[34:37], v[172:175], v[150:153]
	v_mfma_f32_16x16x32_bf16 v[142:145], v[46:49], v[172:175], v[142:145]
	v_mfma_f32_16x16x32_bf16 v[134:137], v[34:37], v[180:183], v[134:137]
	v_mfma_f32_16x16x32_bf16 v[126:129], v[46:49], v[180:183], v[126:129]
	v_mfma_f32_16x16x32_bf16 v[118:121], v[34:37], v[188:191], v[118:121]
	v_mfma_f32_16x16x32_bf16 v[110:113], v[46:49], v[188:191], v[110:113]
	v_mfma_f32_16x16x32_bf16 v[102:105], v[34:37], v[196:199], v[102:105]
	v_mfma_f32_16x16x32_bf16 v[94:97], v[46:49], v[196:199], v[94:97]
	s_setprio 0
	s_setprio 1
	v_mfma_f32_16x16x32_bf16 v[146:149], v[54:57], v[168:171], v[146:149]
	v_mfma_f32_16x16x32_bf16 v[138:141], v[160:163], v[168:171], v[138:141]
	v_mfma_f32_16x16x32_bf16 v[130:133], v[54:57], v[176:179], v[130:133]
	v_mfma_f32_16x16x32_bf16 v[122:125], v[160:163], v[176:179], v[122:125]
	v_mfma_f32_16x16x32_bf16 v[114:117], v[54:57], v[184:187], v[114:117]
	v_mfma_f32_16x16x32_bf16 v[106:109], v[160:163], v[184:187], v[106:109]
	v_mfma_f32_16x16x32_bf16 v[98:101], v[54:57], v[192:195], v[98:101]
	v_mfma_f32_16x16x32_bf16 v[90:93], v[160:163], v[192:195], v[90:93]
	v_mfma_f32_16x16x32_bf16 v[146:149], v[58:61], v[172:175], v[146:149]
	v_mfma_f32_16x16x32_bf16 v[138:141], v[164:167], v[172:175], v[138:141]
	v_mfma_f32_16x16x32_bf16 v[130:133], v[58:61], v[180:183], v[130:133]
	v_mfma_f32_16x16x32_bf16 v[122:125], v[164:167], v[180:183], v[122:125]
	v_mfma_f32_16x16x32_bf16 v[114:117], v[58:61], v[188:191], v[114:117]
	v_mfma_f32_16x16x32_bf16 v[106:109], v[164:167], v[188:191], v[106:109]
	v_mfma_f32_16x16x32_bf16 v[98:101], v[58:61], v[196:199], v[98:101]
	v_mfma_f32_16x16x32_bf16 v[90:93], v[164:167], v[196:199], v[90:93]
	s_barrier
	s_setprio 0
	s_mov_b32 m0, s44
	v_lshl_add_u64 v[204:205], s[54:55], 0, v[0:1]
	ds_read_b128 v[168:171], v217 offset:16384
	ds_read_b128 v[172:175], v217 offset:17408
	ds_read_b128 v[176:179], v217 offset:18432
	ds_read_b128 v[180:183], v217 offset:19456
	ds_read_b128 v[184:187], v217 offset:20480
	ds_read_b128 v[188:191], v217 offset:21504
	ds_read_b128 v[192:195], v217 offset:22528
	ds_read_b128 v[196:199], v217 offset:23552
	global_load_lds_dwordx4 v[204:205], off
	v_lshl_add_u64 v[206:207], s[54:55], 0, v[154:155]
	s_mov_b32 m0, s29
	v_lshl_add_u64 v[200:201], s[58:59], 0, v[0:1]
	global_load_lds_dwordx4 v[206:207], off
	s_mov_b32 m0, s37
	v_lshl_add_u64 v[208:209], s[50:51], 0, v[158:159]
	global_load_lds_dwordx4 v[200:201], off
	v_lshl_add_u64 v[200:201], s[58:59], 0, v[154:155]
	s_mov_b32 m0, s35
	v_lshl_add_u64 v[210:211], s[50:51], 0, v[156:157]
	global_load_lds_dwordx4 v[200:201], off
	s_mov_b32 m0, s63
	s_nop 0
	global_load_lds_dwordx4 v[208:209], off
	s_mov_b32 m0, s64
	s_nop 0
	global_load_lds_dwordx4 v[210:211], off
	s_waitcnt vmcnt(8) lgkmcnt(0)
	s_barrier
; #define PG8_STAGE(bufoff, gbase, voff) do { _Pragma("unroll") for (int _i = 0; _i < 2; ++_i) \
;         __builtin_amdgcn_global_load_lds((const unsigned*)((const char*)(gbase) + (voff)[_i]), (LAS unsigned*)(lds + (bufoff) + ldsw + _i * 8192), 16, 0, 0); } while (0)
; #define PG8_LDA(dst, b, h) do { _Pragma("unroll") for (int m = 0; m < 4; ++m) _Pragma("unroll") for (int k = 0; k < 2; ++k) dst[m][k] = *(const LAS bf16x8*)(lds + PG8_SA(b, h) + aoff + m * 2048 + k * 1024); } while (0)
; #define PG8_LDB(dst, b, h) do { _Pragma("unroll") for (int n = 0; n < 2; ++n) _Pragma("unroll") for (int k = 0; k < 2; ++k) dst[n][k] = *(const LAS bf16x8*)(lds + PG8_SB(b, h) + boff + n * 2048 + k * 1024); } while (0)
; #define PG8_MMA(ai, bj, At, Bt) do { __builtin_amdgcn_s_setprio(1); _Pragma("unroll") for (int m = 0; m < 4; ++m) _Pragma("unroll") for (int n = 0; n < 2; ++n) _Pragma("unroll") for (int k = 0; k < 2; ++k) \
;         acc[ai][bj][m][n] = __builtin_amdgcn_mfma_f32_16x16x32_bf16(Bt[n][k], At[m][k], acc[ai][bj][m][n], 0, 0, 0); __builtin_amdgcn_s_setprio(0); } while (0)
; #define PG8_WAIT_V(n) asm volatile("s_waitcnt vmcnt(" #n ")" ::: "memory")
; #define PG8_WAIT_L(n) asm volatile("s_waitcnt lgkmcnt(" #n ")" ::: "memory")
; #define PG8_BAR __builtin_amdgcn_s_barrier()
; #define PG8_SCHED __builtin_amdgcn_sched_barrier(0)
; template <class Epi, class Sched, bool ALIGN_EPI, bool LAST_FUSED = false, bool PERM = false, bool CARRY = false>
; __device__ __forceinline__ void gemm_phase(LAS unsigned char* lds, const int tid, const int K, const int lda, const int ldb, const Sched& S, const Epi& E) {
;     ...
;             PG8_WAIT_V(8); PG8_WAIT_L(0); PG8_BAR; PG8_MMA(1, 0, At, B0); PG8_MMA(1, 1, At, B1); PG8_BAR; PG8_SCHED;
;             PG8_LDB(B0, 1, 0); PG8_LDB(B1, 1, 1); PG8_SCHED; PG8_LDA(At, 1, 0); PG8_STAGE(PG8_SA(0, 1), a2 + hstepA, voffA);
;             PG8_WAIT_V(8); PG8_WAIT_L(0); PG8_BAR; PG8_MMA(0, 0, At, B0); PG8_MMA(0, 1, At, B1); PG8_BAR; PG8_SCHED;
;             PG8_LDA(At, 1, 1); PG8_STAGE(PG8_SB(1, 0), b3, voffB); PG8_STAGE(PG8_SB(1, 1), b3 + hstepB, voffB); PG8_STAGE(PG8_SA(1, 0), a3, voffA);
;             PG8_WAIT_V(8); PG8_WAIT_L(0); PG8_BAR; PG8_MMA(1, 0, At, B0); PG8_MMA(1, 1, At, B1); PG8_BAR; PG8_SCHED;
	s_setprio 1
	v_mfma_f32_16x16x32_bf16 v[86:89], v[26:29], v[168:171], v[86:89]
	v_mfma_f32_16x16x32_bf16 v[78:81], v[38:41], v[168:171], v[78:81]
	v_mfma_f32_16x16x32_bf16 v[70:73], v[26:29], v[176:179], v[70:73]
	v_mfma_f32_16x16x32_bf16 v[62:65], v[38:41], v[176:179], v[62:65]
	v_mfma_f32_16x16x32_bf16 v[42:45], v[26:29], v[184:187], v[42:45]
	v_mfma_f32_16x16x32_bf16 v[22:25], v[38:41], v[184:187], v[22:25]
	v_mfma_f32_16x16x32_bf16 v[14:17], v[26:29], v[192:195], v[14:17]
	v_mfma_f32_16x16x32_bf16 v[6:9], v[38:41], v[192:195], v[6:9]
	v_mfma_f32_16x16x32_bf16 v[86:89], v[34:37], v[172:175], v[86:89]
	v_mfma_f32_16x16x32_bf16 v[78:81], v[46:49], v[172:175], v[78:81]
	v_mfma_f32_16x16x32_bf16 v[70:73], v[34:37], v[180:183], v[70:73]
	v_mfma_f32_16x16x32_bf16 v[62:65], v[46:49], v[180:183], v[62:65]
	v_mfma_f32_16x16x32_bf16 v[42:45], v[34:37], v[188:191], v[42:45]
	v_mfma_f32_16x16x32_bf16 v[22:25], v[46:49], v[188:191], v[22:25]
	v_mfma_f32_16x16x32_bf16 v[14:17], v[34:37], v[196:199], v[14:17]
	v_mfma_f32_16x16x32_bf16 v[6:9], v[46:49], v[196:199], v[6:9]
	s_setprio 0
	s_setprio 1
	v_mfma_f32_16x16x32_bf16 v[30:33], v[54:57], v[184:187], v[30:33]
	v_mfma_f32_16x16x32_bf16 v[18:21], v[160:163], v[184:187], v[18:21]
	v_mfma_f32_16x16x32_bf16 v[10:13], v[54:57], v[192:195], v[10:13]
	v_mfma_f32_16x16x32_bf16 v[2:5], v[160:163], v[192:195], v[2:5]
	v_mfma_f32_16x16x32_bf16 v[26:29], v[54:57], v[168:171], v[82:85]
	v_mfma_f32_16x16x32_bf16 v[34:37], v[160:163], v[168:171], v[74:77]
	v_mfma_f32_16x16x32_bf16 v[38:41], v[54:57], v[176:179], v[66:69]
	v_mfma_f32_16x16x32_bf16 v[46:49], v[160:163], v[176:179], v[50:53]
	v_mfma_f32_16x16x32_bf16 v[30:33], v[58:61], v[188:191], v[30:33]
	v_mfma_f32_16x16x32_bf16 v[18:21], v[164:167], v[188:191], v[18:21]
	v_mfma_f32_16x16x32_bf16 v[10:13], v[58:61], v[196:199], v[10:13]
	v_mfma_f32_16x16x32_bf16 v[2:5], v[164:167], v[196:199], v[2:5]
	v_mfma_f32_16x16x32_bf16 v[26:29], v[58:61], v[172:175], v[26:29]
	v_mfma_f32_16x16x32_bf16 v[34:37], v[164:167], v[172:175], v[34:37]
	v_mfma_f32_16x16x32_bf16 v[38:41], v[58:61], v[180:183], v[38:41]
	v_mfma_f32_16x16x32_bf16 v[46:49], v[164:167], v[180:183], v[46:49]
	s_barrier
	s_setprio 0
	v_add_u32_e32 v66, s28, v216
	v_add_u32_e32 v74, s23, v216
	ds_read_b128 v[50:53], v66
	ds_read_b128 v[54:57], v66 offset:1024
	ds_read_b128 v[58:61], v66 offset:2048
	ds_read_b128 v[66:69], v66 offset:3072
	ds_read_b128 v[160:163], v74
	ds_read_b128 v[164:167], v74 offset:1024
	ds_read_b128 v[168:171], v74 offset:2048
	ds_read_b128 v[172:175], v74 offset:3072
	s_mov_b32 m0, s65
	v_lshl_add_u64 v[200:201], s[48:49], 0, v[158:159]
	ds_read_b128 v[74:77], v217 offset:32768
	ds_read_b128 v[82:85], v217 offset:33792
	ds_read_b128 v[176:179], v217 offset:34816
	ds_read_b128 v[180:183], v217 offset:35840
	ds_read_b128 v[184:187], v217 offset:36864
	ds_read_b128 v[188:191], v217 offset:37888
	ds_read_b128 v[192:195], v217 offset:38912
	ds_read_b128 v[196:199], v217 offset:39936
	global_load_lds_dwordx4 v[200:201], off
	v_lshl_add_u64 v[200:201], s[48:49], 0, v[156:157]
	s_mov_b32 m0, s66
	s_nop 0
	global_load_lds_dwordx4 v[200:201], off
	s_waitcnt vmcnt(8) lgkmcnt(0)
	s_barrier
	s_setprio 1
	v_mfma_f32_16x16x32_bf16 v[150:153], v[50:53], v[74:77], v[150:153]
	v_mfma_f32_16x16x32_bf16 v[142:145], v[58:61], v[74:77], v[142:145]
	v_mfma_f32_16x16x32_bf16 v[134:137], v[50:53], v[176:179], v[134:137]
	v_mfma_f32_16x16x32_bf16 v[126:129], v[58:61], v[176:179], v[126:129]
	v_mfma_f32_16x16x32_bf16 v[118:121], v[50:53], v[184:187], v[118:121]
	v_mfma_f32_16x16x32_bf16 v[110:113], v[58:61], v[184:187], v[110:113]
	v_mfma_f32_16x16x32_bf16 v[102:105], v[50:53], v[192:195], v[102:105]
	v_mfma_f32_16x16x32_bf16 v[94:97], v[58:61], v[192:195], v[94:97]
	v_mfma_f32_16x16x32_bf16 v[150:153], v[54:57], v[82:85], v[150:153]
	v_mfma_f32_16x16x32_bf16 v[142:145], v[66:69], v[82:85], v[142:145]
	v_mfma_f32_16x16x32_bf16 v[134:137], v[54:57], v[180:183], v[134:137]
	v_mfma_f32_16x16x32_bf16 v[126:129], v[66:69], v[180:183], v[126:129]
	v_mfma_f32_16x16x32_bf16 v[118:121], v[54:57], v[188:191], v[118:121]
	v_mfma_f32_16x16x32_bf16 v[110:113], v[66:69], v[188:191], v[110:113]
	v_mfma_f32_16x16x32_bf16 v[102:105], v[54:57], v[196:199], v[102:105]
	v_mfma_f32_16x16x32_bf16 v[94:97], v[66:69], v[196:199], v[94:97]
	s_setprio 0
	s_setprio 1
	v_mfma_f32_16x16x32_bf16 v[146:149], v[160:163], v[74:77], v[146:149]
	v_mfma_f32_16x16x32_bf16 v[74:77], v[168:171], v[74:77], v[138:141]
	v_mfma_f32_16x16x32_bf16 v[138:141], v[172:175], v[82:85], v[74:77]
	v_mfma_f32_16x16x32_bf16 v[74:77], v[160:163], v[176:179], v[130:133]
	v_mfma_f32_16x16x32_bf16 v[130:133], v[164:167], v[180:183], v[74:77]
	v_mfma_f32_16x16x32_bf16 v[74:77], v[168:171], v[176:179], v[122:125]
	v_mfma_f32_16x16x32_bf16 v[122:125], v[172:175], v[180:183], v[74:77]
	v_mfma_f32_16x16x32_bf16 v[74:77], v[160:163], v[184:187], v[114:117]
	v_mfma_f32_16x16x32_bf16 v[114:117], v[164:167], v[188:191], v[74:77]
	v_mfma_f32_16x16x32_bf16 v[74:77], v[168:171], v[184:187], v[106:109]
	v_mfma_f32_16x16x32_bf16 v[106:109], v[172:175], v[188:191], v[74:77]
	v_mfma_f32_16x16x32_bf16 v[74:77], v[160:163], v[192:195], v[98:101]
	v_mfma_f32_16x16x32_bf16 v[98:101], v[164:167], v[196:199], v[74:77]
	v_mfma_f32_16x16x32_bf16 v[74:77], v[168:171], v[192:195], v[90:93]
	v_mfma_f32_16x16x32_bf16 v[146:149], v[164:167], v[82:85], v[146:149]
	v_mfma_f32_16x16x32_bf16 v[90:93], v[172:175], v[196:199], v[74:77]
	s_barrier
; #define PG8_STAGE(bufoff, gbase, voff) do { _Pragma("unroll") for (int _i = 0; _i < 2; ++_i) \
;         __builtin_amdgcn_global_load_lds((const unsigned*)((const char*)(gbase) + (voff)[_i]), (LAS unsigned*)(lds + (bufoff) + ldsw + _i * 8192), 16, 0, 0); } while (0)
; #define PG8_LDA(dst, b, h) do { _Pragma("unroll") for (int m = 0; m < 4; ++m) _Pragma("unroll") for (int k = 0; k < 2; ++k) dst[m][k] = *(const LAS bf16x8*)(lds + PG8_SA(b, h) + aoff + m * 2048 + k * 1024); } while (0)
; #define PG8_MMA(ai, bj, At, Bt) do { __builtin_amdgcn_s_setprio(1); _Pragma("unroll") for (int m = 0; m < 4; ++m) _Pragma("unroll") for (int n = 0; n < 2; ++n) _Pragma("unroll") for (int k = 0; k < 2; ++k) \
;         acc[ai][bj][m][n] = __builtin_amdgcn_mfma_f32_16x16x32_bf16(Bt[n][k], At[m][k], acc[ai][bj][m][n], 0, 0, 0); __builtin_amdgcn_s_setprio(0); } while (0)
; #define PG8_WAIT_V(n) asm volatile("s_waitcnt vmcnt(" #n ")" ::: "memory")
; #define PG8_WAIT_L(n) asm volatile("s_waitcnt lgkmcnt(" #n ")" ::: "memory")
; #define PG8_BAR __builtin_amdgcn_s_barrier()
; #define PG8_SCHED __builtin_amdgcn_sched_barrier(0)
; template <class Epi, class Sched, bool ALIGN_EPI, bool LAST_FUSED = false, bool PERM = false, bool CARRY = false>
; __device__ __forceinline__ void gemm_phase(LAS unsigned char* lds, const int tid, const int K, const int lda, const int ldb, const Sched& S, const Epi& E) {
;     ...
;             PG8_LDA(At, 1, 1); PG8_STAGE(PG8_SB(1, 0), b3, voffB); PG8_STAGE(PG8_SB(1, 1), b3 + hstepB, voffB); PG8_STAGE(PG8_SA(1, 0), a3, voffA);
;             PG8_WAIT_V(8); PG8_WAIT_L(0); PG8_BAR; PG8_MMA(1, 0, At, B0); PG8_MMA(1, 1, At, B1); PG8_BAR; PG8_SCHED;
;         }
;         if constexpr (ALIGN_EPI) { if (wr == 0) PG8_BAR; }
	s_setprio 0
	s_mov_b32 m0, s19
	v_lshl_add_u64 v[82:83], v[204:205], 0, s[68:69]
	s_nop 1
	ds_read_b128 v[74:77], v217 offset:49152
	ds_read_b128 v[176:179], v217 offset:50176
	ds_read_b128 v[180:183], v217 offset:51200
	ds_read_b128 v[184:187], v217 offset:52224
	ds_read_b128 v[188:191], v217 offset:53248
	ds_read_b128 v[192:195], v217 offset:54272
	ds_read_b128 v[196:199], v217 offset:55296
	ds_read_b128 v[200:203], v217 offset:56320
	global_load_lds_dwordx4 v[82:83], off
	v_lshl_add_u64 v[82:83], v[206:207], 0, s[68:69]
	s_mov_b32 m0, s17
	s_nop 0
	global_load_lds_dwordx4 v[82:83], off
	v_lshl_add_u64 v[82:83], s[46:47], 0, v[0:1]
	s_mov_b32 m0, s78
	s_nop 0
	global_load_lds_dwordx4 v[82:83], off
	v_lshl_add_u64 v[82:83], s[46:47], 0, v[154:155]
	s_mov_b32 m0, s45
	s_nop 0
	global_load_lds_dwordx4 v[82:83], off
	v_lshl_add_u64 v[82:83], v[208:209], 0, s[68:69]
	s_mov_b32 m0, s74
	s_nop 0
	global_load_lds_dwordx4 v[82:83], off
	v_lshl_add_u64 v[82:83], v[210:211], 0, s[68:69]
	s_mov_b32 m0, s75
	s_nop 0
	global_load_lds_dwordx4 v[82:83], off
	s_waitcnt vmcnt(8) lgkmcnt(0)
	s_barrier
	s_setprio 1
	v_mfma_f32_16x16x32_bf16 v[82:85], v[50:53], v[74:77], v[86:89]
	v_mfma_f32_16x16x32_bf16 v[78:81], v[58:61], v[74:77], v[78:81]
	v_mfma_f32_16x16x32_bf16 v[70:73], v[50:53], v[180:183], v[70:73]
	v_mfma_f32_16x16x32_bf16 v[62:65], v[58:61], v[180:183], v[62:65]
	v_mfma_f32_16x16x32_bf16 v[42:45], v[50:53], v[188:191], v[42:45]
	v_mfma_f32_16x16x32_bf16 v[22:25], v[58:61], v[188:191], v[22:25]
	v_mfma_f32_16x16x32_bf16 v[14:17], v[50:53], v[196:199], v[14:17]
	v_mfma_f32_16x16x32_bf16 v[6:9], v[58:61], v[196:199], v[6:9]
	v_mfma_f32_16x16x32_bf16 v[86:89], v[54:57], v[176:179], v[82:85]
	v_mfma_f32_16x16x32_bf16 v[78:81], v[66:69], v[176:179], v[78:81]
	v_mfma_f32_16x16x32_bf16 v[70:73], v[54:57], v[184:187], v[70:73]
	v_mfma_f32_16x16x32_bf16 v[62:65], v[66:69], v[184:187], v[62:65]
	v_mfma_f32_16x16x32_bf16 v[42:45], v[54:57], v[192:195], v[42:45]
	v_mfma_f32_16x16x32_bf16 v[22:25], v[66:69], v[192:195], v[22:25]
	v_mfma_f32_16x16x32_bf16 v[14:17], v[54:57], v[200:203], v[14:17]
	v_mfma_f32_16x16x32_bf16 v[6:9], v[66:69], v[200:203], v[6:9]
	s_setprio 0
	s_setprio 1
	v_mfma_f32_16x16x32_bf16 v[26:29], v[160:163], v[74:77], v[26:29]
	v_mfma_f32_16x16x32_bf16 v[82:85], v[164:167], v[176:179], v[26:29]
	v_mfma_f32_16x16x32_bf16 v[26:29], v[168:171], v[74:77], v[34:37]
	v_mfma_f32_16x16x32_bf16 v[74:77], v[172:175], v[176:179], v[26:29]
	v_mfma_f32_16x16x32_bf16 v[26:29], v[160:163], v[180:183], v[38:41]
	v_mfma_f32_16x16x32_bf16 v[66:69], v[164:167], v[184:187], v[26:29]
	v_mfma_f32_16x16x32_bf16 v[26:29], v[168:171], v[180:183], v[46:49]
	v_mfma_f32_16x16x32_bf16 v[50:53], v[172:175], v[184:187], v[26:29]
	v_mfma_f32_16x16x32_bf16 v[26:29], v[160:163], v[188:191], v[30:33]
	v_mfma_f32_16x16x32_bf16 v[18:21], v[168:171], v[188:191], v[18:21]
	v_mfma_f32_16x16x32_bf16 v[10:13], v[160:163], v[196:199], v[10:13]
	v_mfma_f32_16x16x32_bf16 v[2:5], v[168:171], v[196:199], v[2:5]
	v_mfma_f32_16x16x32_bf16 v[30:33], v[164:167], v[192:195], v[26:29]
	v_mfma_f32_16x16x32_bf16 v[18:21], v[172:175], v[192:195], v[18:21]
	v_mfma_f32_16x16x32_bf16 v[10:13], v[164:167], v[200:203], v[10:13]
	v_mfma_f32_16x16x32_bf16 v[2:5], v[172:175], v[200:203], v[2:5]
	s_barrier
	s_setprio 0
	s_movk_i32 s17, 0x100
	s_andn2_b64 vcc, exec, s[42:43]
	s_mov_b64 s[46:47], -1
	s_mov_b64 s[42:43], 0
	s_cbranch_vccz .LBB0_1367
	s_and_b64 vcc, exec, s[14:15]
	s_cbranch_vccz .LBB0_1370
	s_barrier

; #define PG8_STAGE(bufoff, gbase, voff) do { _Pragma("unroll") for (int _i = 0; _i < 2; ++_i) \
;         __builtin_amdgcn_global_load_lds((const unsigned*)((const char*)(gbase) + (voff)[_i]), (LAS unsigned*)(lds + (bufoff) + ldsw + _i * 8192), 16, 0, 0); } while (0)
; #define PG8_LDA(dst, b, h) do { _Pragma("unroll") for (int m = 0; m < 4; ++m) _Pragma("unroll") for (int k = 0; k < 2; ++k) dst[m][k] = *(const LAS bf16x8*)(lds + PG8_SA(b, h) + aoff + m * 2048 + k * 1024); } while (0)
; #define PG8_LDB(dst, b, h) do { _Pragma("unroll") for (int n = 0; n < 2; ++n) _Pragma("unroll") for (int k = 0; k < 2; ++k) dst[n][k] = *(const LAS bf16x8*)(lds + PG8_SB(b, h) + boff + n * 2048 + k * 1024); } while (0)
; #define PG8_MMA(ai, bj, At, Bt) do { __builtin_amdgcn_s_setprio(1); _Pragma("unroll") for (int m = 0; m < 4; ++m) _Pragma("unroll") for (int n = 0; n < 2; ++n) _Pragma("unroll") for (int k = 0; k < 2; ++k) \
;         acc[ai][bj][m][n] = __builtin_amdgcn_mfma_f32_16x16x32_bf16(Bt[n][k], At[m][k], acc[ai][bj][m][n], 0, 0, 0); __builtin_amdgcn_s_setprio(0); } while (0)
; #define PG8_WAIT_V(n) asm volatile("s_waitcnt vmcnt(" #n ")" ::: "memory")
; #define PG8_WAIT_L(n) asm volatile("s_waitcnt lgkmcnt(" #n ")" ::: "memory")
; template <class Epi, class Sched, bool ALIGN_EPI, bool LAST_FUSED = false, bool PERM = false, bool CARRY = false>
; __device__ __forceinline__ void gemm_phase(LAS unsigned char* lds, const int tid, const int K, const int lda, const int ldb, const Sched& S, const Epi& E) {
;     ...
;         for (int t = 0; t < nt; t += 2) {
;             const bool last = (t == nt - 2);
;             const char* a1 = cA + (size_t)(t + 1) * kstep;
;             const char* a2 = last ? nA : cA + (size_t)(t + 2) * kstep; const char* b2 = last ? nB : cB + (size_t)(t + 2) * kstep;
;             const char* a3 = a2 + kstep; const char* b3 = b2 + kstep;
;             PG8_LDB(B0, 0, 0); PG8_LDB(B1, 0, 1); PG8_SCHED; PG8_LDA(At, 0, 0); PG8_STAGE(PG8_SA(1, 1), a1 + hstepA, voffA);
;             PG8_WAIT_V(8); PG8_WAIT_L(0); PG8_BAR; PG8_MMA(0, 0, At, B0); PG8_MMA(0, 1, At, B1); PG8_BAR; PG8_SCHED;
;             PG8_LDA(At, 0, 1); PG8_STAGE(PG8_SB(0, 0), b2, voffB); PG8_STAGE(PG8_SB(0, 1), b2 + hstepB, voffB); PG8_STAGE(PG8_SA(0, 0), a2, voffA);
;             PG8_WAIT_V(8); PG8_WAIT_L(0); PG8_BAR; PG8_MMA(1, 0, At, B0); PG8_MMA(1, 1, At, B1); PG8_BAR; PG8_SCHED;
.LBB0_1585:
	s_add_u32 s52, s42, s48
	s_addc_u32 s53, s43, s49
	s_add_u32 s76, s40, s48
	s_addc_u32 s77, s41, s49
	s_add_i32 s96, 0, 0x10000
	s_cmp_eq_u32 s3, s95
	s_cselect_b32 s53, s24, s53
	s_cselect_b32 s52, s55, s52
	s_cselect_b32 s77, s93, s77
	s_cselect_b32 s76, s94, s76
	s_add_i32 vcc_lo, 0, 0x14000
	v_add_u32_e32 v156, s96, v140
	v_add_u32_e32 v172, vcc_lo, v140
	ds_read_b128 v[142:145], v156
	ds_read_b128 v[146:149], v156 offset:1024
	ds_read_b128 v[150:153], v156 offset:2048
	ds_read_b128 v[156:159], v156 offset:3072
	ds_read_b128 v[160:163], v172
	ds_read_b128 v[164:167], v172 offset:1024
	ds_read_b128 v[168:171], v172 offset:2048
	ds_read_b128 v[172:175], v172 offset:3072
	v_lshl_add_u64 v[208:209], s[42:43], 0, v[138:139]
	s_add_i32 m0, s35, 0xc000
	ds_read_b128 v[176:179], v141
	ds_read_b128 v[180:183], v141 offset:1024
	ds_read_b128 v[184:187], v141 offset:2048
	ds_read_b128 v[188:191], v141 offset:3072
	ds_read_b128 v[192:195], v141 offset:4096
	ds_read_b128 v[196:199], v141 offset:5120
	ds_read_b128 v[200:203], v141 offset:6144
	ds_read_b128 v[204:207], v141 offset:7168
	global_load_lds_dwordx4 v[208:209], off
	v_lshl_add_u64 v[208:209], s[42:43], 0, v[128:129]
	s_add_i32 m0, s35, 0xe000
	s_nop 0
	global_load_lds_dwordx4 v[208:209], off
	s_waitcnt vmcnt(8) lgkmcnt(0)
	s_barrier
	s_setprio 1
	v_mfma_f32_16x16x32_bf16 v[62:65], v[142:145], v[176:179], v[62:65]
	v_mfma_f32_16x16x32_bf16 v[42:45], v[150:153], v[176:179], v[42:45]
	v_mfma_f32_16x16x32_bf16 v[18:21], v[142:145], v[184:187], v[18:21]
	v_mfma_f32_16x16x32_bf16 v[14:17], v[150:153], v[184:187], v[14:17]
	v_mfma_f32_16x16x32_bf16 v[38:41], v[142:145], v[192:195], v[38:41]
	v_mfma_f32_16x16x32_bf16 v[30:33], v[150:153], v[192:195], v[30:33]
	v_mfma_f32_16x16x32_bf16 v[58:61], v[142:145], v[200:203], v[58:61]
	v_mfma_f32_16x16x32_bf16 v[54:57], v[150:153], v[200:203], v[54:57]
	v_mfma_f32_16x16x32_bf16 v[62:65], v[146:149], v[180:183], v[62:65]
	v_mfma_f32_16x16x32_bf16 v[42:45], v[156:159], v[180:183], v[42:45]
	v_mfma_f32_16x16x32_bf16 v[18:21], v[146:149], v[188:191], v[18:21]
	v_mfma_f32_16x16x32_bf16 v[14:17], v[156:159], v[188:191], v[14:17]
	v_mfma_f32_16x16x32_bf16 v[38:41], v[146:149], v[196:199], v[38:41]
	v_mfma_f32_16x16x32_bf16 v[30:33], v[156:159], v[196:199], v[30:33]
	v_mfma_f32_16x16x32_bf16 v[58:61], v[146:149], v[204:207], v[58:61]
	v_mfma_f32_16x16x32_bf16 v[54:57], v[156:159], v[204:207], v[54:57]
	s_setprio 0
	s_setprio 1
	v_mfma_f32_16x16x32_bf16 v[34:37], v[160:163], v[176:179], v[34:37]
	v_mfma_f32_16x16x32_bf16 v[2:5], v[168:171], v[176:179], v[2:5]
	v_mfma_f32_16x16x32_bf16 v[10:13], v[160:163], v[184:187], v[10:13]
	v_mfma_f32_16x16x32_bf16 v[6:9], v[168:171], v[184:187], v[6:9]
	v_mfma_f32_16x16x32_bf16 v[26:29], v[160:163], v[192:195], v[26:29]
	v_mfma_f32_16x16x32_bf16 v[22:25], v[168:171], v[192:195], v[22:25]
	v_mfma_f32_16x16x32_bf16 v[50:53], v[160:163], v[200:203], v[50:53]
	v_mfma_f32_16x16x32_bf16 v[46:49], v[168:171], v[200:203], v[46:49]
	v_mfma_f32_16x16x32_bf16 v[34:37], v[164:167], v[180:183], v[34:37]
	v_mfma_f32_16x16x32_bf16 v[2:5], v[172:175], v[180:183], v[2:5]
	v_mfma_f32_16x16x32_bf16 v[10:13], v[164:167], v[188:191], v[10:13]
	v_mfma_f32_16x16x32_bf16 v[6:9], v[172:175], v[188:191], v[6:9]
	v_mfma_f32_16x16x32_bf16 v[26:29], v[164:167], v[196:199], v[26:29]
	v_mfma_f32_16x16x32_bf16 v[22:25], v[172:175], v[196:199], v[22:25]
	v_mfma_f32_16x16x32_bf16 v[50:53], v[164:167], v[204:207], v[50:53]
	v_mfma_f32_16x16x32_bf16 v[46:49], v[172:175], v[204:207], v[46:49]
	s_barrier
	s_setprio 0
	s_add_i32 s96, s96, s87
	v_lshl_add_u64 v[208:209], s[76:77], 0, v[0:1]
	s_mov_b32 m0, s96
	ds_read_b128 v[176:179], v141 offset:16384
	ds_read_b128 v[180:183], v141 offset:17408
	ds_read_b128 v[184:187], v141 offset:18432
	ds_read_b128 v[188:191], v141 offset:19456
	ds_read_b128 v[192:195], v141 offset:20480
	ds_read_b128 v[196:199], v141 offset:21504
	ds_read_b128 v[200:203], v141 offset:22528
	ds_read_b128 v[204:207], v141 offset:23552
	global_load_lds_dwordx4 v[208:209], off
	s_add_i32 m0, s96, 0x2000
	s_add_u32 s96, s76, 0x80000
	v_lshl_add_u64 v[210:211], s[76:77], 0, v[122:123]
	s_addc_u32 s97, s77, 0
	s_add_i32 vcc_lo, vcc_lo, s87
	global_load_lds_dwordx4 v[210:211], off
	v_lshl_add_u64 v[212:213], s[96:97], 0, v[0:1]
	s_mov_b32 m0, vcc_lo
	v_lshl_add_u64 v[214:215], s[52:53], 0, v[122:123]
	global_load_lds_dwordx4 v[212:213], off
	v_lshl_add_u64 v[212:213], s[96:97], 0, v[122:123]
	s_add_i32 m0, vcc_lo, 0x2000
	s_nop 0
	global_load_lds_dwordx4 v[212:213], off
	v_lshl_add_u64 v[212:213], s[52:53], 0, v[0:1]
	s_mov_b32 m0, s35
	s_nop 0
	global_load_lds_dwordx4 v[212:213], off
	s_mov_b32 m0, s28
	s_nop 0
	global_load_lds_dwordx4 v[214:215], off
	s_waitcnt vmcnt(8) lgkmcnt(0)
	s_barrier
; #define PG8_STAGE(bufoff, gbase, voff) do { _Pragma("unroll") for (int _i = 0; _i < 2; ++_i) \
;         __builtin_amdgcn_global_load_lds((const unsigned*)((const char*)(gbase) + (voff)[_i]), (LAS unsigned*)(lds + (bufoff) + ldsw + _i * 8192), 16, 0, 0); } while (0)
; #define PG8_LDA(dst, b, h) do { _Pragma("unroll") for (int m = 0; m < 4; ++m) _Pragma("unroll") for (int k = 0; k < 2; ++k) dst[m][k] = *(const LAS bf16x8*)(lds + PG8_SA(b, h) + aoff + m * 2048 + k * 1024); } while (0)
; #define PG8_LDB(dst, b, h) do { _Pragma("unroll") for (int n = 0; n < 2; ++n) _Pragma("unroll") for (int k = 0; k < 2; ++k) dst[n][k] = *(const LAS bf16x8*)(lds + PG8_SB(b, h) + boff + n * 2048 + k * 1024); } while (0)
; #define PG8_MMA(ai, bj, At, Bt) do { __builtin_amdgcn_s_setprio(1); _Pragma("unroll") for (int m = 0; m < 4; ++m) _Pragma("unroll") for (int n = 0; n < 2; ++n) _Pragma("unroll") for (int k = 0; k < 2; ++k) \
;         acc[ai][bj][m][n] = __builtin_amdgcn_mfma_f32_16x16x32_bf16(Bt[n][k], At[m][k], acc[ai][bj][m][n], 0, 0, 0); __builtin_amdgcn_s_setprio(0); } while (0)
; #define PG8_WAIT_V(n) asm volatile("s_waitcnt vmcnt(" #n ")" ::: "memory")
; #define PG8_WAIT_L(n) asm volatile("s_waitcnt lgkmcnt(" #n ")" ::: "memory")
; #define PG8_BAR __builtin_amdgcn_s_barrier()
; #define PG8_SCHED __builtin_amdgcn_sched_barrier(0)
; template <class Epi, class Sched, bool ALIGN_EPI, bool LAST_FUSED = false, bool PERM = false, bool CARRY = false>
; __device__ __forceinline__ void gemm_phase(LAS unsigned char* lds, const int tid, const int K, const int lda, const int ldb, const Sched& S, const Epi& E) {
;     ...
;             PG8_WAIT_V(8); PG8_WAIT_L(0); PG8_BAR; PG8_MMA(1, 0, At, B0); PG8_MMA(1, 1, At, B1); PG8_BAR; PG8_SCHED;
;             PG8_LDB(B0, 1, 0); PG8_LDB(B1, 1, 1); PG8_SCHED; PG8_LDA(At, 1, 0); PG8_STAGE(PG8_SA(0, 1), a2 + hstepA, voffA);
;             PG8_WAIT_V(8); PG8_WAIT_L(0); PG8_BAR; PG8_MMA(0, 0, At, B0); PG8_MMA(0, 1, At, B1); PG8_BAR; PG8_SCHED;
;             PG8_LDA(At, 1, 1); PG8_STAGE(PG8_SB(1, 0), b3, voffB); PG8_STAGE(PG8_SB(1, 1), b3 + hstepB, voffB); PG8_STAGE(PG8_SA(1, 0), a3, voffA);
;             PG8_WAIT_V(8); PG8_WAIT_L(0); PG8_BAR; PG8_MMA(1, 0, At, B0); PG8_MMA(1, 1, At, B1); PG8_BAR; PG8_SCHED;
	s_setprio 1
	v_mfma_f32_16x16x32_bf16 v[78:81], v[142:145], v[176:179], v[78:81]
	v_mfma_f32_16x16x32_bf16 v[74:77], v[150:153], v[176:179], v[74:77]
	v_mfma_f32_16x16x32_bf16 v[98:101], v[142:145], v[184:187], v[98:101]
	v_mfma_f32_16x16x32_bf16 v[94:97], v[150:153], v[184:187], v[94:97]
	v_mfma_f32_16x16x32_bf16 v[118:121], v[142:145], v[192:195], v[118:121]
	v_mfma_f32_16x16x32_bf16 v[114:117], v[150:153], v[192:195], v[114:117]
	v_mfma_f32_16x16x32_bf16 v[134:137], v[142:145], v[200:203], v[134:137]
	v_mfma_f32_16x16x32_bf16 v[130:133], v[150:153], v[200:203], v[130:133]
	v_mfma_f32_16x16x32_bf16 v[78:81], v[146:149], v[180:183], v[78:81]
	v_mfma_f32_16x16x32_bf16 v[74:77], v[156:159], v[180:183], v[74:77]
	v_mfma_f32_16x16x32_bf16 v[98:101], v[146:149], v[188:191], v[98:101]
	v_mfma_f32_16x16x32_bf16 v[94:97], v[156:159], v[188:191], v[94:97]
	v_mfma_f32_16x16x32_bf16 v[118:121], v[146:149], v[196:199], v[118:121]
	v_mfma_f32_16x16x32_bf16 v[114:117], v[156:159], v[196:199], v[114:117]
	v_mfma_f32_16x16x32_bf16 v[134:137], v[146:149], v[204:207], v[134:137]
	v_mfma_f32_16x16x32_bf16 v[130:133], v[156:159], v[204:207], v[130:133]
	s_setprio 0
	s_setprio 1
	v_mfma_f32_16x16x32_bf16 v[70:73], v[160:163], v[176:179], v[70:73]
	v_mfma_f32_16x16x32_bf16 v[66:69], v[168:171], v[176:179], v[66:69]
	v_mfma_f32_16x16x32_bf16 v[90:93], v[160:163], v[184:187], v[90:93]
	v_mfma_f32_16x16x32_bf16 v[86:89], v[168:171], v[184:187], v[86:89]
	v_mfma_f32_16x16x32_bf16 v[110:113], v[160:163], v[192:195], v[110:113]
	v_mfma_f32_16x16x32_bf16 v[106:109], v[168:171], v[192:195], v[106:109]
	v_mfma_f32_16x16x32_bf16 v[102:105], v[160:163], v[200:203], v[102:105]
	v_mfma_f32_16x16x32_bf16 v[82:85], v[168:171], v[200:203], v[82:85]
	v_mfma_f32_16x16x32_bf16 v[70:73], v[164:167], v[180:183], v[70:73]
	v_mfma_f32_16x16x32_bf16 v[66:69], v[172:175], v[180:183], v[66:69]
	v_mfma_f32_16x16x32_bf16 v[90:93], v[164:167], v[188:191], v[90:93]
	v_mfma_f32_16x16x32_bf16 v[86:89], v[172:175], v[188:191], v[86:89]
	v_mfma_f32_16x16x32_bf16 v[110:113], v[164:167], v[196:199], v[110:113]
	v_mfma_f32_16x16x32_bf16 v[106:109], v[172:175], v[196:199], v[106:109]
	v_mfma_f32_16x16x32_bf16 v[102:105], v[164:167], v[204:207], v[102:105]
	v_mfma_f32_16x16x32_bf16 v[82:85], v[172:175], v[204:207], v[82:85]
	s_barrier
	s_setprio 0
	s_add_i32 s96, 0, 0x18000
	s_add_i32 s97, 0, 0x1c000
	v_add_u32_e32 v156, s96, v140
	v_add_u32_e32 v172, s97, v140
	ds_read_b128 v[142:145], v156
	ds_read_b128 v[146:149], v156 offset:1024
	ds_read_b128 v[150:153], v156 offset:2048
	ds_read_b128 v[156:159], v156 offset:3072
	ds_read_b128 v[160:163], v172
	ds_read_b128 v[164:167], v172 offset:1024
	ds_read_b128 v[168:171], v172 offset:2048
	ds_read_b128 v[172:175], v172 offset:3072
	s_add_u32 s52, s52, 0x80000
	s_addc_u32 s53, s53, 0
	s_mov_b32 m0, s29
	v_lshl_add_u64 v[216:217], s[52:53], 0, v[0:1]
	ds_read_b128 v[176:179], v141 offset:32768
	ds_read_b128 v[180:183], v141 offset:33792
	ds_read_b128 v[184:187], v141 offset:34816
	ds_read_b128 v[188:191], v141 offset:35840
	ds_read_b128 v[192:195], v141 offset:36864
	ds_read_b128 v[196:199], v141 offset:37888
	ds_read_b128 v[200:203], v141 offset:38912
	ds_read_b128 v[204:207], v141 offset:39936
	global_load_lds_dwordx4 v[216:217], off
	v_lshl_add_u64 v[216:217], s[52:53], 0, v[122:123]
	s_mov_b32 m0, s14
	s_nop 0
	global_load_lds_dwordx4 v[216:217], off
	s_waitcnt vmcnt(8) lgkmcnt(0)
	s_barrier
	s_setprio 1
	v_mfma_f32_16x16x32_bf16 v[62:65], v[142:145], v[176:179], v[62:65]
	v_mfma_f32_16x16x32_bf16 v[42:45], v[150:153], v[176:179], v[42:45]
	v_mfma_f32_16x16x32_bf16 v[18:21], v[142:145], v[184:187], v[18:21]
	v_mfma_f32_16x16x32_bf16 v[14:17], v[150:153], v[184:187], v[14:17]
	v_mfma_f32_16x16x32_bf16 v[38:41], v[142:145], v[192:195], v[38:41]
	v_mfma_f32_16x16x32_bf16 v[30:33], v[150:153], v[192:195], v[30:33]
	v_mfma_f32_16x16x32_bf16 v[58:61], v[142:145], v[200:203], v[58:61]
	v_mfma_f32_16x16x32_bf16 v[54:57], v[150:153], v[200:203], v[54:57]
	v_mfma_f32_16x16x32_bf16 v[62:65], v[146:149], v[180:183], v[62:65]
	v_mfma_f32_16x16x32_bf16 v[42:45], v[156:159], v[180:183], v[42:45]
	v_mfma_f32_16x16x32_bf16 v[18:21], v[146:149], v[188:191], v[18:21]
	v_mfma_f32_16x16x32_bf16 v[14:17], v[156:159], v[188:191], v[14:17]
	v_mfma_f32_16x16x32_bf16 v[38:41], v[146:149], v[196:199], v[38:41]
	v_mfma_f32_16x16x32_bf16 v[30:33], v[156:159], v[196:199], v[30:33]
	v_mfma_f32_16x16x32_bf16 v[58:61], v[146:149], v[204:207], v[58:61]
	v_mfma_f32_16x16x32_bf16 v[54:57], v[156:159], v[204:207], v[54:57]
	s_setprio 0
	s_setprio 1
	v_mfma_f32_16x16x32_bf16 v[34:37], v[160:163], v[176:179], v[34:37]
	v_mfma_f32_16x16x32_bf16 v[2:5], v[168:171], v[176:179], v[2:5]
	v_mfma_f32_16x16x32_bf16 v[10:13], v[160:163], v[184:187], v[10:13]
	v_mfma_f32_16x16x32_bf16 v[6:9], v[168:171], v[184:187], v[6:9]
	v_mfma_f32_16x16x32_bf16 v[26:29], v[160:163], v[192:195], v[26:29]
	v_mfma_f32_16x16x32_bf16 v[22:25], v[168:171], v[192:195], v[22:25]
	v_mfma_f32_16x16x32_bf16 v[50:53], v[160:163], v[200:203], v[50:53]
	v_mfma_f32_16x16x32_bf16 v[46:49], v[168:171], v[200:203], v[46:49]
	v_mfma_f32_16x16x32_bf16 v[34:37], v[164:167], v[180:183], v[34:37]
	v_mfma_f32_16x16x32_bf16 v[2:5], v[172:175], v[180:183], v[2:5]
	v_mfma_f32_16x16x32_bf16 v[10:13], v[164:167], v[188:191], v[10:13]
	v_mfma_f32_16x16x32_bf16 v[6:9], v[172:175], v[188:191], v[6:9]
	v_mfma_f32_16x16x32_bf16 v[26:29], v[164:167], v[196:199], v[26:29]
	v_mfma_f32_16x16x32_bf16 v[22:25], v[172:175], v[196:199], v[22:25]
	v_mfma_f32_16x16x32_bf16 v[50:53], v[164:167], v[204:207], v[50:53]
	v_mfma_f32_16x16x32_bf16 v[46:49], v[172:175], v[204:207], v[46:49]
	s_barrier
; #define PG8_STAGE(bufoff, gbase, voff) do { _Pragma("unroll") for (int _i = 0; _i < 2; ++_i) \
;         __builtin_amdgcn_global_load_lds((const unsigned*)((const char*)(gbase) + (voff)[_i]), (LAS unsigned*)(lds + (bufoff) + ldsw + _i * 8192), 16, 0, 0); } while (0)
; #define PG8_LDA(dst, b, h) do { _Pragma("unroll") for (int m = 0; m < 4; ++m) _Pragma("unroll") for (int k = 0; k < 2; ++k) dst[m][k] = *(const LAS bf16x8*)(lds + PG8_SA(b, h) + aoff + m * 2048 + k * 1024); } while (0)
; #define PG8_MMA(ai, bj, At, Bt) do { __builtin_amdgcn_s_setprio(1); _Pragma("unroll") for (int m = 0; m < 4; ++m) _Pragma("unroll") for (int n = 0; n < 2; ++n) _Pragma("unroll") for (int k = 0; k < 2; ++k) \
;         acc[ai][bj][m][n] = __builtin_amdgcn_mfma_f32_16x16x32_bf16(Bt[n][k], At[m][k], acc[ai][bj][m][n], 0, 0, 0); __builtin_amdgcn_s_setprio(0); } while (0)
; #define PG8_WAIT_V(n) asm volatile("s_waitcnt vmcnt(" #n ")" ::: "memory")
; #define PG8_WAIT_L(n) asm volatile("s_waitcnt lgkmcnt(" #n ")" ::: "memory")
; #define PG8_BAR __builtin_amdgcn_s_barrier()
; #define PG8_SCHED __builtin_amdgcn_sched_barrier(0)
; template <class Epi, class Sched, bool ALIGN_EPI, bool LAST_FUSED = false, bool PERM = false, bool CARRY = false>
; __device__ __forceinline__ void gemm_phase(LAS unsigned char* lds, const int tid, const int K, const int lda, const int ldb, const Sched& S, const Epi& E) {
;     ...
;             PG8_LDA(At, 1, 1); PG8_STAGE(PG8_SB(1, 0), b3, voffB); PG8_STAGE(PG8_SB(1, 1), b3 + hstepB, voffB); PG8_STAGE(PG8_SA(1, 0), a3, voffA);
;             PG8_WAIT_V(8); PG8_WAIT_L(0); PG8_BAR; PG8_MMA(1, 0, At, B0); PG8_MMA(1, 1, At, B1); PG8_BAR; PG8_SCHED;
;         }
;         if constexpr (ALIGN_EPI) { if (wr == 0) PG8_BAR; }
	s_setprio 0
	s_add_i32 s52, s96, s87
	v_lshl_add_u64 v[208:209], v[208:209], 0, s[68:69]
	s_mov_b32 m0, s52
	ds_read_b128 v[176:179], v141 offset:49152
	ds_read_b128 v[180:183], v141 offset:50176
	ds_read_b128 v[184:187], v141 offset:51200
	ds_read_b128 v[188:191], v141 offset:52224
	ds_read_b128 v[192:195], v141 offset:53248
	ds_read_b128 v[196:199], v141 offset:54272
	ds_read_b128 v[200:203], v141 offset:55296
	ds_read_b128 v[204:207], v141 offset:56320
	global_load_lds_dwordx4 v[208:209], off
	s_add_i32 m0, s52, 0x2000
	s_add_u32 s52, s76, 0x80080
	v_lshl_add_u64 v[208:209], v[210:211], 0, s[68:69]
	s_addc_u32 s53, s77, 0
	s_add_i32 s76, s97, s87
	global_load_lds_dwordx4 v[208:209], off
	v_lshl_add_u64 v[208:209], s[52:53], 0, v[0:1]
	s_mov_b32 m0, s76
	s_nop 0
	global_load_lds_dwordx4 v[208:209], off
	v_lshl_add_u64 v[208:209], s[52:53], 0, v[122:123]
	s_add_i32 m0, s76, 0x2000
	s_nop 0
	global_load_lds_dwordx4 v[208:209], off
	v_lshl_add_u64 v[208:209], v[212:213], 0, s[68:69]
	s_mov_b32 m0, s85
	s_nop 0
	global_load_lds_dwordx4 v[208:209], off
	v_lshl_add_u64 v[208:209], v[214:215], 0, s[68:69]
	s_mov_b32 m0, s89
	s_nop 0
	global_load_lds_dwordx4 v[208:209], off
	s_waitcnt vmcnt(8) lgkmcnt(0)
	s_barrier
	s_setprio 1
	v_mfma_f32_16x16x32_bf16 v[78:81], v[142:145], v[176:179], v[78:81]
	v_mfma_f32_16x16x32_bf16 v[74:77], v[150:153], v[176:179], v[74:77]
	v_mfma_f32_16x16x32_bf16 v[98:101], v[142:145], v[184:187], v[98:101]
	v_mfma_f32_16x16x32_bf16 v[94:97], v[150:153], v[184:187], v[94:97]
	v_mfma_f32_16x16x32_bf16 v[118:121], v[142:145], v[192:195], v[118:121]
	v_mfma_f32_16x16x32_bf16 v[114:117], v[150:153], v[192:195], v[114:117]
	v_mfma_f32_16x16x32_bf16 v[134:137], v[142:145], v[200:203], v[134:137]
	v_mfma_f32_16x16x32_bf16 v[130:133], v[150:153], v[200:203], v[130:133]
	v_mfma_f32_16x16x32_bf16 v[78:81], v[146:149], v[180:183], v[78:81]
	v_mfma_f32_16x16x32_bf16 v[74:77], v[156:159], v[180:183], v[74:77]
	v_mfma_f32_16x16x32_bf16 v[98:101], v[146:149], v[188:191], v[98:101]
	v_mfma_f32_16x16x32_bf16 v[94:97], v[156:159], v[188:191], v[94:97]
	v_mfma_f32_16x16x32_bf16 v[118:121], v[146:149], v[196:199], v[118:121]
	v_mfma_f32_16x16x32_bf16 v[114:117], v[156:159], v[196:199], v[114:117]
	v_mfma_f32_16x16x32_bf16 v[134:137], v[146:149], v[204:207], v[134:137]
	v_mfma_f32_16x16x32_bf16 v[130:133], v[156:159], v[204:207], v[130:133]
	s_setprio 0
	s_setprio 1
	v_mfma_f32_16x16x32_bf16 v[70:73], v[160:163], v[176:179], v[70:73]
	v_mfma_f32_16x16x32_bf16 v[66:69], v[168:171], v[176:179], v[66:69]
	v_mfma_f32_16x16x32_bf16 v[90:93], v[160:163], v[184:187], v[90:93]
	v_mfma_f32_16x16x32_bf16 v[86:89], v[168:171], v[184:187], v[86:89]
	v_mfma_f32_16x16x32_bf16 v[110:113], v[160:163], v[192:195], v[110:113]
	v_mfma_f32_16x16x32_bf16 v[106:109], v[168:171], v[192:195], v[106:109]
	v_mfma_f32_16x16x32_bf16 v[102:105], v[160:163], v[200:203], v[102:105]
	v_mfma_f32_16x16x32_bf16 v[82:85], v[168:171], v[200:203], v[82:85]
	v_mfma_f32_16x16x32_bf16 v[70:73], v[164:167], v[180:183], v[70:73]
	v_mfma_f32_16x16x32_bf16 v[66:69], v[172:175], v[180:183], v[66:69]
	v_mfma_f32_16x16x32_bf16 v[90:93], v[164:167], v[188:191], v[90:93]
	v_mfma_f32_16x16x32_bf16 v[86:89], v[172:175], v[188:191], v[86:89]
	v_mfma_f32_16x16x32_bf16 v[110:113], v[164:167], v[196:199], v[110:113]
	v_mfma_f32_16x16x32_bf16 v[106:109], v[172:175], v[196:199], v[106:109]
	v_mfma_f32_16x16x32_bf16 v[102:105], v[164:167], v[204:207], v[102:105]
	v_mfma_f32_16x16x32_bf16 v[82:85], v[172:175], v[204:207], v[82:85]
	s_barrier
	s_setprio 0
	s_add_i32 s52, s95, 2
	s_add_u32 s48, s48, 0x100
	s_addc_u32 s49, s49, 0
	v_lshl_add_u64 v[138:139], v[138:139], 0, s[72:73]
	v_lshl_add_u64 v[128:129], v[128:129], 0, s[72:73]
	s_cmp_ge_i32 s95, s3
	s_mov_b32 s95, s52
	s_cbranch_scc0 .LBB0_1585
	s_and_b64 vcc, exec, s[36:37]
	s_cbranch_vccz .LBB0_1588
	s_barrier

; #define PG8_STAGE(bufoff, gbase, voff) do { _Pragma("unroll") for (int _i = 0; _i < 2; ++_i) \
;         __builtin_amdgcn_global_load_lds((const unsigned*)((const char*)(gbase) + (voff)[_i]), (LAS unsigned*)(lds + (bufoff) + ldsw + _i * 8192), 16, 0, 0); } while (0)
; #define PG8_LDA(dst, b, h) do { _Pragma("unroll") for (int m = 0; m < 4; ++m) _Pragma("unroll") for (int k = 0; k < 2; ++k) dst[m][k] = *(const LAS bf16x8*)(lds + PG8_SA(b, h) + aoff + m * 2048 + k * 1024); } while (0)
; #define PG8_LDB(dst, b, h) do { _Pragma("unroll") for (int n = 0; n < 2; ++n) _Pragma("unroll") for (int k = 0; k < 2; ++k) dst[n][k] = *(const LAS bf16x8*)(lds + PG8_SB(b, h) + boff + n * 2048 + k * 1024); } while (0)
; #define PG8_MMA(ai, bj, At, Bt) do { __builtin_amdgcn_s_setprio(1); _Pragma("unroll") for (int m = 0; m < 4; ++m) _Pragma("unroll") for (int n = 0; n < 2; ++n) _Pragma("unroll") for (int k = 0; k < 2; ++k) \
;         acc[ai][bj][m][n] = __builtin_amdgcn_mfma_f32_16x16x32_bf16(Bt[n][k], At[m][k], acc[ai][bj][m][n], 0, 0, 0); __builtin_amdgcn_s_setprio(0); } while (0)
; #define PG8_WAIT_V(n) asm volatile("s_waitcnt vmcnt(" #n ")" ::: "memory")
; #define PG8_WAIT_L(n) asm volatile("s_waitcnt lgkmcnt(" #n ")" ::: "memory")
; template <class Epi, class Sched, bool ALIGN_EPI, bool LAST_FUSED = false, bool PERM = false, bool CARRY = false>
; __device__ __forceinline__ void gemm_phase(LAS unsigned char* lds, const int tid, const int K, const int lda, const int ldb, const Sched& S, const Epi& E) {
;     ...
;         for (int t = 0; t < nt; t += 2) {
;             const bool last = (t == nt - 2);
;             const char* a1 = cA + (size_t)(t + 1) * kstep;
;             const char* a2 = last ? nA : cA + (size_t)(t + 2) * kstep; const char* b2 = last ? nB : cB + (size_t)(t + 2) * kstep;
;             const char* a3 = a2 + kstep; const char* b3 = b2 + kstep;
;             PG8_LDB(B0, 0, 0); PG8_LDB(B1, 0, 1); PG8_SCHED; PG8_LDA(At, 0, 0); PG8_STAGE(PG8_SA(1, 1), a1 + hstepA, voffA);
;             PG8_WAIT_V(8); PG8_WAIT_L(0); PG8_BAR; PG8_MMA(0, 0, At, B0); PG8_MMA(0, 1, At, B1); PG8_BAR; PG8_SCHED;
;             PG8_LDA(At, 0, 1); PG8_STAGE(PG8_SB(0, 0), b2, voffB); PG8_STAGE(PG8_SB(0, 1), b2 + hstepB, voffB); PG8_STAGE(PG8_SA(0, 0), a2, voffA);
;             PG8_WAIT_V(8); PG8_WAIT_L(0); PG8_BAR; PG8_MMA(1, 0, At, B0); PG8_MMA(1, 1, At, B1); PG8_BAR; PG8_SCHED;
.LBB0_1662:
	s_add_u32 s52, s38, s48
	s_addc_u32 s53, s39, s49
	s_add_u32 s66, s40, s48
	s_addc_u32 s67, s41, s49
	s_waitcnt lgkmcnt(0)
	s_add_i32 s90, 0, 0x10000
	s_cmp_eq_u32 s3, s89
	s_cselect_b32 s53, s24, s53
	s_cselect_b32 s52, s85, s52
	s_cselect_b32 s67, s86, s67
	s_cselect_b32 s66, s87, s66
	s_add_i32 s92, 0, 0x14000
	v_add_u32_e32 v156, s90, v140
	v_add_u32_e32 v172, s92, v140
	ds_read_b128 v[142:145], v156
	ds_read_b128 v[146:149], v156 offset:1024
	ds_read_b128 v[150:153], v156 offset:2048
	ds_read_b128 v[156:159], v156 offset:3072
	ds_read_b128 v[160:163], v172
	ds_read_b128 v[164:167], v172 offset:1024
	ds_read_b128 v[168:171], v172 offset:2048
	ds_read_b128 v[172:175], v172 offset:3072
	v_lshl_add_u64 v[208:209], s[38:39], 0, v[138:139]
	s_add_i32 m0, s35, 0xc000
	ds_read_b128 v[176:179], v141
	ds_read_b128 v[180:183], v141 offset:1024
	ds_read_b128 v[184:187], v141 offset:2048
	ds_read_b128 v[188:191], v141 offset:3072
	ds_read_b128 v[192:195], v141 offset:4096
	ds_read_b128 v[196:199], v141 offset:5120
	ds_read_b128 v[200:203], v141 offset:6144
	ds_read_b128 v[204:207], v141 offset:7168
	global_load_lds_dwordx4 v[208:209], off
	v_lshl_add_u64 v[208:209], s[38:39], 0, v[128:129]
	s_add_i32 m0, s35, 0xe000
	s_nop 0
	global_load_lds_dwordx4 v[208:209], off
	s_waitcnt vmcnt(8) lgkmcnt(0)
	s_barrier
	s_setprio 1
	v_mfma_f32_16x16x32_bf16 v[62:65], v[142:145], v[176:179], v[62:65]
	v_mfma_f32_16x16x32_bf16 v[42:45], v[150:153], v[176:179], v[42:45]
	v_mfma_f32_16x16x32_bf16 v[18:21], v[142:145], v[184:187], v[18:21]
	v_mfma_f32_16x16x32_bf16 v[14:17], v[150:153], v[184:187], v[14:17]
	v_mfma_f32_16x16x32_bf16 v[38:41], v[142:145], v[192:195], v[38:41]
	v_mfma_f32_16x16x32_bf16 v[30:33], v[150:153], v[192:195], v[30:33]
	v_mfma_f32_16x16x32_bf16 v[58:61], v[142:145], v[200:203], v[58:61]
	v_mfma_f32_16x16x32_bf16 v[54:57], v[150:153], v[200:203], v[54:57]
	v_mfma_f32_16x16x32_bf16 v[62:65], v[146:149], v[180:183], v[62:65]
	v_mfma_f32_16x16x32_bf16 v[42:45], v[156:159], v[180:183], v[42:45]
	v_mfma_f32_16x16x32_bf16 v[18:21], v[146:149], v[188:191], v[18:21]
	v_mfma_f32_16x16x32_bf16 v[14:17], v[156:159], v[188:191], v[14:17]
	v_mfma_f32_16x16x32_bf16 v[38:41], v[146:149], v[196:199], v[38:41]
	v_mfma_f32_16x16x32_bf16 v[30:33], v[156:159], v[196:199], v[30:33]
	v_mfma_f32_16x16x32_bf16 v[58:61], v[146:149], v[204:207], v[58:61]
	v_mfma_f32_16x16x32_bf16 v[54:57], v[156:159], v[204:207], v[54:57]
	s_setprio 0
	s_setprio 1
	v_mfma_f32_16x16x32_bf16 v[34:37], v[160:163], v[176:179], v[34:37]
	v_mfma_f32_16x16x32_bf16 v[2:5], v[168:171], v[176:179], v[2:5]
	v_mfma_f32_16x16x32_bf16 v[10:13], v[160:163], v[184:187], v[10:13]
	v_mfma_f32_16x16x32_bf16 v[6:9], v[168:171], v[184:187], v[6:9]
	v_mfma_f32_16x16x32_bf16 v[26:29], v[160:163], v[192:195], v[26:29]
	v_mfma_f32_16x16x32_bf16 v[22:25], v[168:171], v[192:195], v[22:25]
	v_mfma_f32_16x16x32_bf16 v[50:53], v[160:163], v[200:203], v[50:53]
	v_mfma_f32_16x16x32_bf16 v[46:49], v[168:171], v[200:203], v[46:49]
	v_mfma_f32_16x16x32_bf16 v[34:37], v[164:167], v[180:183], v[34:37]
	v_mfma_f32_16x16x32_bf16 v[2:5], v[172:175], v[180:183], v[2:5]
	v_mfma_f32_16x16x32_bf16 v[10:13], v[164:167], v[188:191], v[10:13]
	v_mfma_f32_16x16x32_bf16 v[6:9], v[172:175], v[188:191], v[6:9]
	v_mfma_f32_16x16x32_bf16 v[26:29], v[164:167], v[196:199], v[26:29]
	v_mfma_f32_16x16x32_bf16 v[22:25], v[172:175], v[196:199], v[22:25]
	v_mfma_f32_16x16x32_bf16 v[50:53], v[164:167], v[204:207], v[50:53]
	v_mfma_f32_16x16x32_bf16 v[46:49], v[172:175], v[204:207], v[46:49]
	s_barrier
	s_setprio 0
	s_add_i32 s90, s90, s76
	v_lshl_add_u64 v[208:209], s[66:67], 0, v[0:1]
	s_mov_b32 m0, s90
	ds_read_b128 v[176:179], v141 offset:16384
	ds_read_b128 v[180:183], v141 offset:17408
	ds_read_b128 v[184:187], v141 offset:18432
	ds_read_b128 v[188:191], v141 offset:19456
	ds_read_b128 v[192:195], v141 offset:20480
	ds_read_b128 v[196:199], v141 offset:21504
	ds_read_b128 v[200:203], v141 offset:22528
	ds_read_b128 v[204:207], v141 offset:23552
	global_load_lds_dwordx4 v[208:209], off
	s_add_i32 m0, s90, 0x2000
	s_add_u32 s90, s66, 0x100000
	v_lshl_add_u64 v[210:211], s[66:67], 0, v[122:123]
	s_addc_u32 s91, s67, 0
	s_add_i32 s92, s92, s76
	global_load_lds_dwordx4 v[210:211], off
	v_lshl_add_u64 v[212:213], s[90:91], 0, v[0:1]
	s_mov_b32 m0, s92
	v_lshl_add_u64 v[214:215], s[52:53], 0, v[122:123]
	global_load_lds_dwordx4 v[212:213], off
	v_lshl_add_u64 v[212:213], s[90:91], 0, v[122:123]
	s_add_i32 m0, s92, 0x2000
	s_nop 0
	global_load_lds_dwordx4 v[212:213], off
	v_lshl_add_u64 v[212:213], s[52:53], 0, v[0:1]
	s_mov_b32 m0, s35
	s_nop 0
	global_load_lds_dwordx4 v[212:213], off
	s_mov_b32 m0, s28
	s_nop 0
	global_load_lds_dwordx4 v[214:215], off
	s_waitcnt vmcnt(8) lgkmcnt(0)
	s_barrier
; #define PG8_STAGE(bufoff, gbase, voff) do { _Pragma("unroll") for (int _i = 0; _i < 2; ++_i) \
;         __builtin_amdgcn_global_load_lds((const unsigned*)((const char*)(gbase) + (voff)[_i]), (LAS unsigned*)(lds + (bufoff) + ldsw + _i * 8192), 16, 0, 0); } while (0)
; #define PG8_LDA(dst, b, h) do { _Pragma("unroll") for (int m = 0; m < 4; ++m) _Pragma("unroll") for (int k = 0; k < 2; ++k) dst[m][k] = *(const LAS bf16x8*)(lds + PG8_SA(b, h) + aoff + m * 2048 + k * 1024); } while (0)
; #define PG8_LDB(dst, b, h) do { _Pragma("unroll") for (int n = 0; n < 2; ++n) _Pragma("unroll") for (int k = 0; k < 2; ++k) dst[n][k] = *(const LAS bf16x8*)(lds + PG8_SB(b, h) + boff + n * 2048 + k * 1024); } while (0)
; #define PG8_MMA(ai, bj, At, Bt) do { __builtin_amdgcn_s_setprio(1); _Pragma("unroll") for (int m = 0; m < 4; ++m) _Pragma("unroll") for (int n = 0; n < 2; ++n) _Pragma("unroll") for (int k = 0; k < 2; ++k) \
;         acc[ai][bj][m][n] = __builtin_amdgcn_mfma_f32_16x16x32_bf16(Bt[n][k], At[m][k], acc[ai][bj][m][n], 0, 0, 0); __builtin_amdgcn_s_setprio(0); } while (0)
; #define PG8_WAIT_V(n) asm volatile("s_waitcnt vmcnt(" #n ")" ::: "memory")
; #define PG8_WAIT_L(n) asm volatile("s_waitcnt lgkmcnt(" #n ")" ::: "memory")
; #define PG8_BAR __builtin_amdgcn_s_barrier()
; #define PG8_SCHED __builtin_amdgcn_sched_barrier(0)
; template <class Epi, class Sched, bool ALIGN_EPI, bool LAST_FUSED = false, bool PERM = false, bool CARRY = false>
; __device__ __forceinline__ void gemm_phase(LAS unsigned char* lds, const int tid, const int K, const int lda, const int ldb, const Sched& S, const Epi& E) {
;     ...
;             PG8_WAIT_V(8); PG8_WAIT_L(0); PG8_BAR; PG8_MMA(1, 0, At, B0); PG8_MMA(1, 1, At, B1); PG8_BAR; PG8_SCHED;
;             PG8_LDB(B0, 1, 0); PG8_LDB(B1, 1, 1); PG8_SCHED; PG8_LDA(At, 1, 0); PG8_STAGE(PG8_SA(0, 1), a2 + hstepA, voffA);
;             PG8_WAIT_V(8); PG8_WAIT_L(0); PG8_BAR; PG8_MMA(0, 0, At, B0); PG8_MMA(0, 1, At, B1); PG8_BAR; PG8_SCHED;
;             PG8_LDA(At, 1, 1); PG8_STAGE(PG8_SB(1, 0), b3, voffB); PG8_STAGE(PG8_SB(1, 1), b3 + hstepB, voffB); PG8_STAGE(PG8_SA(1, 0), a3, voffA);
;             PG8_WAIT_V(8); PG8_WAIT_L(0); PG8_BAR; PG8_MMA(1, 0, At, B0); PG8_MMA(1, 1, At, B1); PG8_BAR; PG8_SCHED;
	s_setprio 1
	v_mfma_f32_16x16x32_bf16 v[78:81], v[142:145], v[176:179], v[78:81]
	v_mfma_f32_16x16x32_bf16 v[74:77], v[150:153], v[176:179], v[74:77]
	v_mfma_f32_16x16x32_bf16 v[98:101], v[142:145], v[184:187], v[98:101]
	v_mfma_f32_16x16x32_bf16 v[94:97], v[150:153], v[184:187], v[94:97]
	v_mfma_f32_16x16x32_bf16 v[118:121], v[142:145], v[192:195], v[118:121]
	v_mfma_f32_16x16x32_bf16 v[114:117], v[150:153], v[192:195], v[114:117]
	v_mfma_f32_16x16x32_bf16 v[134:137], v[142:145], v[200:203], v[134:137]
	v_mfma_f32_16x16x32_bf16 v[130:133], v[150:153], v[200:203], v[130:133]
	v_mfma_f32_16x16x32_bf16 v[78:81], v[146:149], v[180:183], v[78:81]
	v_mfma_f32_16x16x32_bf16 v[74:77], v[156:159], v[180:183], v[74:77]
	v_mfma_f32_16x16x32_bf16 v[98:101], v[146:149], v[188:191], v[98:101]
	v_mfma_f32_16x16x32_bf16 v[94:97], v[156:159], v[188:191], v[94:97]
	v_mfma_f32_16x16x32_bf16 v[118:121], v[146:149], v[196:199], v[118:121]
	v_mfma_f32_16x16x32_bf16 v[114:117], v[156:159], v[196:199], v[114:117]
	v_mfma_f32_16x16x32_bf16 v[134:137], v[146:149], v[204:207], v[134:137]
	v_mfma_f32_16x16x32_bf16 v[130:133], v[156:159], v[204:207], v[130:133]
	s_setprio 0
	s_setprio 1
	v_mfma_f32_16x16x32_bf16 v[70:73], v[160:163], v[176:179], v[70:73]
	v_mfma_f32_16x16x32_bf16 v[66:69], v[168:171], v[176:179], v[66:69]
	v_mfma_f32_16x16x32_bf16 v[90:93], v[160:163], v[184:187], v[90:93]
	v_mfma_f32_16x16x32_bf16 v[86:89], v[168:171], v[184:187], v[86:89]
	v_mfma_f32_16x16x32_bf16 v[110:113], v[160:163], v[192:195], v[110:113]
	v_mfma_f32_16x16x32_bf16 v[106:109], v[168:171], v[192:195], v[106:109]
	v_mfma_f32_16x16x32_bf16 v[102:105], v[160:163], v[200:203], v[102:105]
	v_mfma_f32_16x16x32_bf16 v[82:85], v[168:171], v[200:203], v[82:85]
	v_mfma_f32_16x16x32_bf16 v[70:73], v[164:167], v[180:183], v[70:73]
	v_mfma_f32_16x16x32_bf16 v[66:69], v[172:175], v[180:183], v[66:69]
	v_mfma_f32_16x16x32_bf16 v[90:93], v[164:167], v[188:191], v[90:93]
	v_mfma_f32_16x16x32_bf16 v[86:89], v[172:175], v[188:191], v[86:89]
	v_mfma_f32_16x16x32_bf16 v[110:113], v[164:167], v[196:199], v[110:113]
	v_mfma_f32_16x16x32_bf16 v[106:109], v[172:175], v[196:199], v[106:109]
	v_mfma_f32_16x16x32_bf16 v[102:105], v[164:167], v[204:207], v[102:105]
	v_mfma_f32_16x16x32_bf16 v[82:85], v[172:175], v[204:207], v[82:85]
	s_barrier
	s_setprio 0
	s_add_i32 s90, 0, 0x18000
	s_add_i32 s91, 0, 0x1c000
	v_add_u32_e32 v156, s90, v140
	v_add_u32_e32 v172, s91, v140
	ds_read_b128 v[142:145], v156
	ds_read_b128 v[146:149], v156 offset:1024
	ds_read_b128 v[150:153], v156 offset:2048
	ds_read_b128 v[156:159], v156 offset:3072
	ds_read_b128 v[160:163], v172
	ds_read_b128 v[164:167], v172 offset:1024
	ds_read_b128 v[168:171], v172 offset:2048
	ds_read_b128 v[172:175], v172 offset:3072
	s_add_u32 s52, s52, 0x100000
	s_addc_u32 s53, s53, 0
	s_mov_b32 m0, s29
	v_lshl_add_u64 v[216:217], s[52:53], 0, v[0:1]
	ds_read_b128 v[176:179], v141 offset:32768
	ds_read_b128 v[180:183], v141 offset:33792
	ds_read_b128 v[184:187], v141 offset:34816
	ds_read_b128 v[188:191], v141 offset:35840
	ds_read_b128 v[192:195], v141 offset:36864
	ds_read_b128 v[196:199], v141 offset:37888
	ds_read_b128 v[200:203], v141 offset:38912
	ds_read_b128 v[204:207], v141 offset:39936
	global_load_lds_dwordx4 v[216:217], off
	v_lshl_add_u64 v[216:217], s[52:53], 0, v[122:123]
	s_mov_b32 m0, s14
	s_nop 0
	global_load_lds_dwordx4 v[216:217], off
	s_waitcnt vmcnt(8) lgkmcnt(0)
	s_barrier
	s_setprio 1
	v_mfma_f32_16x16x32_bf16 v[62:65], v[142:145], v[176:179], v[62:65]
	v_mfma_f32_16x16x32_bf16 v[42:45], v[150:153], v[176:179], v[42:45]
	v_mfma_f32_16x16x32_bf16 v[18:21], v[142:145], v[184:187], v[18:21]
	v_mfma_f32_16x16x32_bf16 v[14:17], v[150:153], v[184:187], v[14:17]
	v_mfma_f32_16x16x32_bf16 v[38:41], v[142:145], v[192:195], v[38:41]
	v_mfma_f32_16x16x32_bf16 v[30:33], v[150:153], v[192:195], v[30:33]
	v_mfma_f32_16x16x32_bf16 v[58:61], v[142:145], v[200:203], v[58:61]
	v_mfma_f32_16x16x32_bf16 v[54:57], v[150:153], v[200:203], v[54:57]
	v_mfma_f32_16x16x32_bf16 v[62:65], v[146:149], v[180:183], v[62:65]
	v_mfma_f32_16x16x32_bf16 v[42:45], v[156:159], v[180:183], v[42:45]
	v_mfma_f32_16x16x32_bf16 v[18:21], v[146:149], v[188:191], v[18:21]
	v_mfma_f32_16x16x32_bf16 v[14:17], v[156:159], v[188:191], v[14:17]
	v_mfma_f32_16x16x32_bf16 v[38:41], v[146:149], v[196:199], v[38:41]
	v_mfma_f32_16x16x32_bf16 v[30:33], v[156:159], v[196:199], v[30:33]
	v_mfma_f32_16x16x32_bf16 v[58:61], v[146:149], v[204:207], v[58:61]
	v_mfma_f32_16x16x32_bf16 v[54:57], v[156:159], v[204:207], v[54:57]
	s_setprio 0
	s_setprio 1
	v_mfma_f32_16x16x32_bf16 v[34:37], v[160:163], v[176:179], v[34:37]
	v_mfma_f32_16x16x32_bf16 v[2:5], v[168:171], v[176:179], v[2:5]
	v_mfma_f32_16x16x32_bf16 v[10:13], v[160:163], v[184:187], v[10:13]
	v_mfma_f32_16x16x32_bf16 v[6:9], v[168:171], v[184:187], v[6:9]
	v_mfma_f32_16x16x32_bf16 v[26:29], v[160:163], v[192:195], v[26:29]
	v_mfma_f32_16x16x32_bf16 v[22:25], v[168:171], v[192:195], v[22:25]
	v_mfma_f32_16x16x32_bf16 v[50:53], v[160:163], v[200:203], v[50:53]
	v_mfma_f32_16x16x32_bf16 v[46:49], v[168:171], v[200:203], v[46:49]
	v_mfma_f32_16x16x32_bf16 v[34:37], v[164:167], v[180:183], v[34:37]
	v_mfma_f32_16x16x32_bf16 v[2:5], v[172:175], v[180:183], v[2:5]
	v_mfma_f32_16x16x32_bf16 v[10:13], v[164:167], v[188:191], v[10:13]
	v_mfma_f32_16x16x32_bf16 v[6:9], v[172:175], v[188:191], v[6:9]
	v_mfma_f32_16x16x32_bf16 v[26:29], v[164:167], v[196:199], v[26:29]
	v_mfma_f32_16x16x32_bf16 v[22:25], v[172:175], v[196:199], v[22:25]
	v_mfma_f32_16x16x32_bf16 v[50:53], v[164:167], v[204:207], v[50:53]
	v_mfma_f32_16x16x32_bf16 v[46:49], v[172:175], v[204:207], v[46:49]
	s_barrier
; #define PG8_STAGE(bufoff, gbase, voff) do { _Pragma("unroll") for (int _i = 0; _i < 2; ++_i) \
;         __builtin_amdgcn_global_load_lds((const unsigned*)((const char*)(gbase) + (voff)[_i]), (LAS unsigned*)(lds + (bufoff) + ldsw + _i * 8192), 16, 0, 0); } while (0)
; #define PG8_LDA(dst, b, h) do { _Pragma("unroll") for (int m = 0; m < 4; ++m) _Pragma("unroll") for (int k = 0; k < 2; ++k) dst[m][k] = *(const LAS bf16x8*)(lds + PG8_SA(b, h) + aoff + m * 2048 + k * 1024); } while (0)
; #define PG8_MMA(ai, bj, At, Bt) do { __builtin_amdgcn_s_setprio(1); _Pragma("unroll") for (int m = 0; m < 4; ++m) _Pragma("unroll") for (int n = 0; n < 2; ++n) _Pragma("unroll") for (int k = 0; k < 2; ++k) \
;         acc[ai][bj][m][n] = __builtin_amdgcn_mfma_f32_16x16x32_bf16(Bt[n][k], At[m][k], acc[ai][bj][m][n], 0, 0, 0); __builtin_amdgcn_s_setprio(0); } while (0)
; #define PG8_WAIT_V(n) asm volatile("s_waitcnt vmcnt(" #n ")" ::: "memory")
; #define PG8_WAIT_L(n) asm volatile("s_waitcnt lgkmcnt(" #n ")" ::: "memory")
; #define PG8_BAR __builtin_amdgcn_s_barrier()
; #define PG8_SCHED __builtin_amdgcn_sched_barrier(0)
; template <class Epi, class Sched, bool ALIGN_EPI, bool LAST_FUSED = false, bool PERM = false, bool CARRY = false>
; __device__ __forceinline__ void gemm_phase(LAS unsigned char* lds, const int tid, const int K, const int lda, const int ldb, const Sched& S, const Epi& E) {
;     ...
;             PG8_LDA(At, 1, 1); PG8_STAGE(PG8_SB(1, 0), b3, voffB); PG8_STAGE(PG8_SB(1, 1), b3 + hstepB, voffB); PG8_STAGE(PG8_SA(1, 0), a3, voffA);
;             PG8_WAIT_V(8); PG8_WAIT_L(0); PG8_BAR; PG8_MMA(1, 0, At, B0); PG8_MMA(1, 1, At, B1); PG8_BAR; PG8_SCHED;
;         }
;         if constexpr (ALIGN_EPI) { if (wr == 0) PG8_BAR; }
	s_setprio 0
	s_add_i32 s52, s90, s76
	v_lshl_add_u64 v[208:209], v[208:209], 0, s[68:69]
	s_mov_b32 m0, s52
	ds_read_b128 v[176:179], v141 offset:49152
	ds_read_b128 v[180:183], v141 offset:50176
	ds_read_b128 v[184:187], v141 offset:51200
	ds_read_b128 v[188:191], v141 offset:52224
	ds_read_b128 v[192:195], v141 offset:53248
	ds_read_b128 v[196:199], v141 offset:54272
	ds_read_b128 v[200:203], v141 offset:55296
	ds_read_b128 v[204:207], v141 offset:56320
	global_load_lds_dwordx4 v[208:209], off
	s_add_i32 m0, s52, 0x2000
	s_add_u32 s52, s66, 0x100080
	v_lshl_add_u64 v[208:209], v[210:211], 0, s[68:69]
	s_addc_u32 s53, s67, 0
	s_add_i32 s66, s91, s76
	global_load_lds_dwordx4 v[208:209], off
	v_lshl_add_u64 v[208:209], s[52:53], 0, v[0:1]
	s_mov_b32 m0, s66
	s_nop 0
	global_load_lds_dwordx4 v[208:209], off
	v_lshl_add_u64 v[208:209], s[52:53], 0, v[122:123]
	s_add_i32 m0, s66, 0x2000
	s_nop 0
	global_load_lds_dwordx4 v[208:209], off
	v_lshl_add_u64 v[208:209], v[212:213], 0, s[68:69]
	s_mov_b32 m0, s77
	s_nop 0
	global_load_lds_dwordx4 v[208:209], off
	v_lshl_add_u64 v[208:209], v[214:215], 0, s[68:69]
	s_mov_b32 m0, s79
	s_nop 0
	global_load_lds_dwordx4 v[208:209], off
	s_waitcnt vmcnt(8) lgkmcnt(0)
	s_barrier
	s_setprio 1
	v_mfma_f32_16x16x32_bf16 v[78:81], v[142:145], v[176:179], v[78:81]
	v_mfma_f32_16x16x32_bf16 v[74:77], v[150:153], v[176:179], v[74:77]
	v_mfma_f32_16x16x32_bf16 v[98:101], v[142:145], v[184:187], v[98:101]
	v_mfma_f32_16x16x32_bf16 v[94:97], v[150:153], v[184:187], v[94:97]
	v_mfma_f32_16x16x32_bf16 v[118:121], v[142:145], v[192:195], v[118:121]
	v_mfma_f32_16x16x32_bf16 v[114:117], v[150:153], v[192:195], v[114:117]
	v_mfma_f32_16x16x32_bf16 v[134:137], v[142:145], v[200:203], v[134:137]
	v_mfma_f32_16x16x32_bf16 v[130:133], v[150:153], v[200:203], v[130:133]
	v_mfma_f32_16x16x32_bf16 v[78:81], v[146:149], v[180:183], v[78:81]
	v_mfma_f32_16x16x32_bf16 v[74:77], v[156:159], v[180:183], v[74:77]
	v_mfma_f32_16x16x32_bf16 v[98:101], v[146:149], v[188:191], v[98:101]
	v_mfma_f32_16x16x32_bf16 v[94:97], v[156:159], v[188:191], v[94:97]
	v_mfma_f32_16x16x32_bf16 v[118:121], v[146:149], v[196:199], v[118:121]
	v_mfma_f32_16x16x32_bf16 v[114:117], v[156:159], v[196:199], v[114:117]
	v_mfma_f32_16x16x32_bf16 v[134:137], v[146:149], v[204:207], v[134:137]
	v_mfma_f32_16x16x32_bf16 v[130:133], v[156:159], v[204:207], v[130:133]
	s_setprio 0
	s_setprio 1
	v_mfma_f32_16x16x32_bf16 v[70:73], v[160:163], v[176:179], v[70:73]
	v_mfma_f32_16x16x32_bf16 v[66:69], v[168:171], v[176:179], v[66:69]
	v_mfma_f32_16x16x32_bf16 v[90:93], v[160:163], v[184:187], v[90:93]
	v_mfma_f32_16x16x32_bf16 v[86:89], v[168:171], v[184:187], v[86:89]
	v_mfma_f32_16x16x32_bf16 v[110:113], v[160:163], v[192:195], v[110:113]
	v_mfma_f32_16x16x32_bf16 v[106:109], v[168:171], v[192:195], v[106:109]
	v_mfma_f32_16x16x32_bf16 v[102:105], v[160:163], v[200:203], v[102:105]
	v_mfma_f32_16x16x32_bf16 v[82:85], v[168:171], v[200:203], v[82:85]
	v_mfma_f32_16x16x32_bf16 v[70:73], v[164:167], v[180:183], v[70:73]
	v_mfma_f32_16x16x32_bf16 v[66:69], v[172:175], v[180:183], v[66:69]
	v_mfma_f32_16x16x32_bf16 v[90:93], v[164:167], v[188:191], v[90:93]
	v_mfma_f32_16x16x32_bf16 v[86:89], v[172:175], v[188:191], v[86:89]
	v_mfma_f32_16x16x32_bf16 v[110:113], v[164:167], v[196:199], v[110:113]
	v_mfma_f32_16x16x32_bf16 v[106:109], v[172:175], v[196:199], v[106:109]
	v_mfma_f32_16x16x32_bf16 v[102:105], v[164:167], v[204:207], v[102:105]
	v_mfma_f32_16x16x32_bf16 v[82:85], v[172:175], v[204:207], v[82:85]
	s_barrier
	s_setprio 0
	s_add_i32 s52, s89, 2
	s_add_u32 s48, s48, 0x100
	s_addc_u32 s49, s49, 0
	v_lshl_add_u64 v[138:139], v[138:139], 0, s[72:73]
	v_lshl_add_u64 v[128:129], v[128:129], 0, s[72:73]
	s_cmp_ge_i32 s89, s3
	s_mov_b32 s89, s52
	s_cbranch_scc0 .LBB0_1662
	s_and_b64 vcc, exec, s[36:37]
	s_cbranch_vccz .LBB0_1665
	s_barrier

; #define PG8_STAGE(bufoff, gbase, voff) do { _Pragma("unroll") for (int _i = 0; _i < 2; ++_i) \
;         __builtin_amdgcn_global_load_lds((const unsigned*)((const char*)(gbase) + (voff)[_i]), (LAS unsigned*)(lds + (bufoff) + ldsw + _i * 8192), 16, 0, 0); } while (0)
; #define PG8_LDA(dst, b, h) do { _Pragma("unroll") for (int m = 0; m < 4; ++m) _Pragma("unroll") for (int k = 0; k < 2; ++k) dst[m][k] = *(const LAS bf16x8*)(lds + PG8_SA(b, h) + aoff + m * 2048 + k * 1024); } while (0)
; #define PG8_LDB(dst, b, h) do { _Pragma("unroll") for (int n = 0; n < 2; ++n) _Pragma("unroll") for (int k = 0; k < 2; ++k) dst[n][k] = *(const LAS bf16x8*)(lds + PG8_SB(b, h) + boff + n * 2048 + k * 1024); } while (0)
; #define PG8_MMA(ai, bj, At, Bt) do { __builtin_amdgcn_s_setprio(1); _Pragma("unroll") for (int m = 0; m < 4; ++m) _Pragma("unroll") for (int n = 0; n < 2; ++n) _Pragma("unroll") for (int k = 0; k < 2; ++k) \
;         acc[ai][bj][m][n] = __builtin_amdgcn_mfma_f32_16x16x32_bf16(Bt[n][k], At[m][k], acc[ai][bj][m][n], 0, 0, 0); __builtin_amdgcn_s_setprio(0); } while (0)
; #define PG8_WAIT_V(n) asm volatile("s_waitcnt vmcnt(" #n ")" ::: "memory")
; #define PG8_WAIT_L(n) asm volatile("s_waitcnt lgkmcnt(" #n ")" ::: "memory")
; template <class Epi, class Sched, bool ALIGN_EPI, bool LAST_FUSED = false, bool PERM = false, bool CARRY = false>
; __device__ __forceinline__ void gemm_phase(LAS unsigned char* lds, const int tid, const int K, const int lda, const int ldb, const Sched& S, const Epi& E) {
;     ...
;         for (int t = 0; t < nt; t += 2) {
;             const bool last = (t == nt - 2);
;             const char* a1 = cA + (size_t)(t + 1) * kstep;
;             const char* a2 = last ? nA : cA + (size_t)(t + 2) * kstep; const char* b2 = last ? nB : cB + (size_t)(t + 2) * kstep;
;             const char* a3 = a2 + kstep; const char* b3 = b2 + kstep;
;             PG8_LDB(B0, 0, 0); PG8_LDB(B1, 0, 1); PG8_SCHED; PG8_LDA(At, 0, 0); PG8_STAGE(PG8_SA(1, 1), a1 + hstepA, voffA);
;             PG8_WAIT_V(8); PG8_WAIT_L(0); PG8_BAR; PG8_MMA(0, 0, At, B0); PG8_MMA(0, 1, At, B1); PG8_BAR; PG8_SCHED;
;             PG8_LDA(At, 0, 1); PG8_STAGE(PG8_SB(0, 0), b2, voffB); PG8_STAGE(PG8_SB(0, 1), b2 + hstepB, voffB); PG8_STAGE(PG8_SA(0, 0), a2, voffA);
;             PG8_WAIT_V(8); PG8_WAIT_L(0); PG8_BAR; PG8_MMA(1, 0, At, B0); PG8_MMA(1, 1, At, B1); PG8_BAR; PG8_SCHED;
.LBB0_1763:
	s_add_u32 s16, s48, 0xfff80080
	s_addc_u32 s17, s49, -1
	s_add_i32 s67, 0, 0x10000
	s_cmp_eq_u32 s41, 28
	s_cselect_b32 s53, s43, s17
	s_cselect_b32 s52, s42, s16
	v_add_u32_e32 v140, s67, v146
	s_cselect_b32 s55, s51, s39
	s_cselect_b32 s54, s50, s27
	s_add_i32 s16, 0, 0x14000
	ds_read_b128 v[148:151], v140
	ds_read_b128 v[152:155], v140 offset:1024
	ds_read_b128 v[156:159], v140 offset:2048
	ds_read_b128 v[160:163], v140 offset:3072
	v_add_u32_e32 v140, s16, v146
	ds_read_b128 v[164:167], v140
	ds_read_b128 v[168:171], v140 offset:1024
	ds_read_b128 v[172:175], v140 offset:2048
	ds_read_b128 v[176:179], v140 offset:3072
	v_lshl_add_u64 v[140:141], s[48:49], 0, v[136:137]
	s_add_i32 m0, s47, 0xc000
	ds_read_b128 v[180:183], v147
	ds_read_b128 v[184:187], v147 offset:1024
	ds_read_b128 v[188:191], v147 offset:2048
	ds_read_b128 v[192:195], v147 offset:3072
	ds_read_b128 v[196:199], v147 offset:4096
	ds_read_b128 v[200:203], v147 offset:5120
	ds_read_b128 v[204:207], v147 offset:6144
	ds_read_b128 v[208:211], v147 offset:7168
	global_load_lds_dwordx4 v[140:141], off
	v_lshl_add_u64 v[140:141], s[48:49], 0, v[138:139]
	s_add_i32 m0, s47, 0xe000
	s_nop 0
	global_load_lds_dwordx4 v[140:141], off
	s_waitcnt vmcnt(8) lgkmcnt(0)
	s_barrier
	s_setprio 1
	v_mfma_f32_16x16x32_bf16 v[126:129], v[148:151], v[180:183], v[126:129]
	v_mfma_f32_16x16x32_bf16 v[122:125], v[156:159], v[180:183], v[122:125]
	v_mfma_f32_16x16x32_bf16 v[110:113], v[148:151], v[188:191], v[110:113]
	v_mfma_f32_16x16x32_bf16 v[106:109], v[156:159], v[188:191], v[106:109]
	v_mfma_f32_16x16x32_bf16 v[94:97], v[148:151], v[196:199], v[94:97]
	v_mfma_f32_16x16x32_bf16 v[90:93], v[156:159], v[196:199], v[90:93]
	v_mfma_f32_16x16x32_bf16 v[78:81], v[148:151], v[204:207], v[78:81]
	v_mfma_f32_16x16x32_bf16 v[74:77], v[156:159], v[204:207], v[74:77]
	v_mfma_f32_16x16x32_bf16 v[126:129], v[152:155], v[184:187], v[126:129]
	v_mfma_f32_16x16x32_bf16 v[122:125], v[160:163], v[184:187], v[122:125]
	v_mfma_f32_16x16x32_bf16 v[110:113], v[152:155], v[192:195], v[110:113]
	v_mfma_f32_16x16x32_bf16 v[106:109], v[160:163], v[192:195], v[106:109]
	v_mfma_f32_16x16x32_bf16 v[94:97], v[152:155], v[200:203], v[94:97]
	v_mfma_f32_16x16x32_bf16 v[90:93], v[160:163], v[200:203], v[90:93]
	v_mfma_f32_16x16x32_bf16 v[78:81], v[152:155], v[208:211], v[78:81]
	v_mfma_f32_16x16x32_bf16 v[74:77], v[160:163], v[208:211], v[74:77]
	s_setprio 0
	s_setprio 1
	v_mfma_f32_16x16x32_bf16 v[118:121], v[164:167], v[180:183], v[118:121]
	v_mfma_f32_16x16x32_bf16 v[114:117], v[172:175], v[180:183], v[114:117]
	v_mfma_f32_16x16x32_bf16 v[102:105], v[164:167], v[188:191], v[102:105]
	v_mfma_f32_16x16x32_bf16 v[98:101], v[172:175], v[188:191], v[98:101]
	v_mfma_f32_16x16x32_bf16 v[86:89], v[164:167], v[196:199], v[86:89]
	v_mfma_f32_16x16x32_bf16 v[82:85], v[172:175], v[196:199], v[82:85]
	v_mfma_f32_16x16x32_bf16 v[70:73], v[164:167], v[204:207], v[70:73]
	v_mfma_f32_16x16x32_bf16 v[66:69], v[172:175], v[204:207], v[66:69]
	v_mfma_f32_16x16x32_bf16 v[118:121], v[168:171], v[184:187], v[118:121]
	v_mfma_f32_16x16x32_bf16 v[114:117], v[176:179], v[184:187], v[114:117]
	v_mfma_f32_16x16x32_bf16 v[102:105], v[168:171], v[192:195], v[102:105]
	v_mfma_f32_16x16x32_bf16 v[98:101], v[176:179], v[192:195], v[98:101]
	v_mfma_f32_16x16x32_bf16 v[86:89], v[168:171], v[200:203], v[86:89]
	v_mfma_f32_16x16x32_bf16 v[82:85], v[176:179], v[200:203], v[82:85]
	v_mfma_f32_16x16x32_bf16 v[70:73], v[168:171], v[208:211], v[70:73]
	v_mfma_f32_16x16x32_bf16 v[66:69], v[176:179], v[208:211], v[66:69]
	s_barrier
	s_setprio 0
	s_add_i32 s17, s67, s45
	v_lshl_add_u64 v[140:141], s[54:55], 0, v[0:1]
	s_mov_b32 m0, s17
	ds_read_b128 v[180:183], v147 offset:16384
	ds_read_b128 v[184:187], v147 offset:17408
	ds_read_b128 v[188:191], v147 offset:18432
	ds_read_b128 v[192:195], v147 offset:19456
	ds_read_b128 v[196:199], v147 offset:20480
	ds_read_b128 v[200:203], v147 offset:21504
	ds_read_b128 v[204:207], v147 offset:22528
	ds_read_b128 v[208:211], v147 offset:23552
	global_load_lds_dwordx4 v[140:141], off
	s_add_i32 m0, s17, 0x2000
	s_add_u32 s70, s54, 0x80000
	v_lshl_add_u64 v[212:213], s[54:55], 0, v[130:131]
	s_addc_u32 s71, s55, 0
	s_add_i32 s16, s16, s45
	global_load_lds_dwordx4 v[212:213], off
	v_lshl_add_u64 v[214:215], s[70:71], 0, v[0:1]
	s_mov_b32 m0, s16
	v_lshl_add_u64 v[216:217], s[52:53], 0, v[132:133]
	global_load_lds_dwordx4 v[214:215], off
	v_lshl_add_u64 v[214:215], s[70:71], 0, v[130:131]
	s_add_i32 m0, s16, 0x2000
	s_nop 0
	global_load_lds_dwordx4 v[214:215], off
	v_lshl_add_u64 v[214:215], s[52:53], 0, v[134:135]
	s_mov_b32 m0, s47
	s_nop 0
	global_load_lds_dwordx4 v[214:215], off
	s_mov_b32 m0, s57
	s_nop 0
	global_load_lds_dwordx4 v[216:217], off
	s_waitcnt vmcnt(8) lgkmcnt(0)
	s_barrier
; #define PG8_STAGE(bufoff, gbase, voff) do { _Pragma("unroll") for (int _i = 0; _i < 2; ++_i) \
;         __builtin_amdgcn_global_load_lds((const unsigned*)((const char*)(gbase) + (voff)[_i]), (LAS unsigned*)(lds + (bufoff) + ldsw + _i * 8192), 16, 0, 0); } while (0)
; #define PG8_LDA(dst, b, h) do { _Pragma("unroll") for (int m = 0; m < 4; ++m) _Pragma("unroll") for (int k = 0; k < 2; ++k) dst[m][k] = *(const LAS bf16x8*)(lds + PG8_SA(b, h) + aoff + m * 2048 + k * 1024); } while (0)
; #define PG8_LDB(dst, b, h) do { _Pragma("unroll") for (int n = 0; n < 2; ++n) _Pragma("unroll") for (int k = 0; k < 2; ++k) dst[n][k] = *(const LAS bf16x8*)(lds + PG8_SB(b, h) + boff + n * 2048 + k * 1024); } while (0)
; #define PG8_MMA(ai, bj, At, Bt) do { __builtin_amdgcn_s_setprio(1); _Pragma("unroll") for (int m = 0; m < 4; ++m) _Pragma("unroll") for (int n = 0; n < 2; ++n) _Pragma("unroll") for (int k = 0; k < 2; ++k) \
;         acc[ai][bj][m][n] = __builtin_amdgcn_mfma_f32_16x16x32_bf16(Bt[n][k], At[m][k], acc[ai][bj][m][n], 0, 0, 0); __builtin_amdgcn_s_setprio(0); } while (0)
; #define PG8_WAIT_V(n) asm volatile("s_waitcnt vmcnt(" #n ")" ::: "memory")
; #define PG8_WAIT_L(n) asm volatile("s_waitcnt lgkmcnt(" #n ")" ::: "memory")
; #define PG8_BAR __builtin_amdgcn_s_barrier()
; #define PG8_SCHED __builtin_amdgcn_sched_barrier(0)
; template <class Epi, class Sched, bool ALIGN_EPI, bool LAST_FUSED = false, bool PERM = false, bool CARRY = false>
; __device__ __forceinline__ void gemm_phase(LAS unsigned char* lds, const int tid, const int K, const int lda, const int ldb, const Sched& S, const Epi& E) {
;     ...
;             PG8_WAIT_V(8); PG8_WAIT_L(0); PG8_BAR; PG8_MMA(1, 0, At, B0); PG8_MMA(1, 1, At, B1); PG8_BAR; PG8_SCHED;
;             PG8_LDB(B0, 1, 0); PG8_LDB(B1, 1, 1); PG8_SCHED; PG8_LDA(At, 1, 0); PG8_STAGE(PG8_SA(0, 1), a2 + hstepA, voffA);
;             PG8_WAIT_V(8); PG8_WAIT_L(0); PG8_BAR; PG8_MMA(0, 0, At, B0); PG8_MMA(0, 1, At, B1); PG8_BAR; PG8_SCHED;
;             PG8_LDA(At, 1, 1); PG8_STAGE(PG8_SB(1, 0), b3, voffB); PG8_STAGE(PG8_SB(1, 1), b3 + hstepB, voffB); PG8_STAGE(PG8_SA(1, 0), a3, voffA);
;             PG8_WAIT_V(8); PG8_WAIT_L(0); PG8_BAR; PG8_MMA(1, 0, At, B0); PG8_MMA(1, 1, At, B1); PG8_BAR; PG8_SCHED;
	s_setprio 1
	v_mfma_f32_16x16x32_bf16 v[62:65], v[148:151], v[180:183], v[62:65]
	v_mfma_f32_16x16x32_bf16 v[58:61], v[156:159], v[180:183], v[58:61]
	v_mfma_f32_16x16x32_bf16 v[46:49], v[148:151], v[188:191], v[46:49]
	v_mfma_f32_16x16x32_bf16 v[42:45], v[156:159], v[188:191], v[42:45]
	v_mfma_f32_16x16x32_bf16 v[30:33], v[148:151], v[196:199], v[30:33]
	v_mfma_f32_16x16x32_bf16 v[26:29], v[156:159], v[196:199], v[26:29]
	v_mfma_f32_16x16x32_bf16 v[14:17], v[148:151], v[204:207], v[14:17]
	v_mfma_f32_16x16x32_bf16 v[10:13], v[156:159], v[204:207], v[10:13]
	v_mfma_f32_16x16x32_bf16 v[62:65], v[152:155], v[184:187], v[62:65]
	v_mfma_f32_16x16x32_bf16 v[58:61], v[160:163], v[184:187], v[58:61]
	v_mfma_f32_16x16x32_bf16 v[46:49], v[152:155], v[192:195], v[46:49]
	v_mfma_f32_16x16x32_bf16 v[42:45], v[160:163], v[192:195], v[42:45]
	v_mfma_f32_16x16x32_bf16 v[30:33], v[152:155], v[200:203], v[30:33]
	v_mfma_f32_16x16x32_bf16 v[26:29], v[160:163], v[200:203], v[26:29]
	v_mfma_f32_16x16x32_bf16 v[14:17], v[152:155], v[208:211], v[14:17]
	v_mfma_f32_16x16x32_bf16 v[10:13], v[160:163], v[208:211], v[10:13]
	s_setprio 0
	s_setprio 1
	v_mfma_f32_16x16x32_bf16 v[54:57], v[164:167], v[180:183], v[54:57]
	v_mfma_f32_16x16x32_bf16 v[50:53], v[172:175], v[180:183], v[50:53]
	v_mfma_f32_16x16x32_bf16 v[38:41], v[164:167], v[188:191], v[38:41]
	v_mfma_f32_16x16x32_bf16 v[34:37], v[172:175], v[188:191], v[34:37]
	v_mfma_f32_16x16x32_bf16 v[22:25], v[164:167], v[196:199], v[22:25]
	v_mfma_f32_16x16x32_bf16 v[18:21], v[172:175], v[196:199], v[18:21]
	v_mfma_f32_16x16x32_bf16 v[6:9], v[164:167], v[204:207], v[6:9]
	v_mfma_f32_16x16x32_bf16 v[2:5], v[172:175], v[204:207], v[2:5]
	v_mfma_f32_16x16x32_bf16 v[54:57], v[168:171], v[184:187], v[54:57]
	v_mfma_f32_16x16x32_bf16 v[50:53], v[176:179], v[184:187], v[50:53]
	v_mfma_f32_16x16x32_bf16 v[38:41], v[168:171], v[192:195], v[38:41]
	v_mfma_f32_16x16x32_bf16 v[34:37], v[176:179], v[192:195], v[34:37]
	v_mfma_f32_16x16x32_bf16 v[22:25], v[168:171], v[200:203], v[22:25]
	v_mfma_f32_16x16x32_bf16 v[18:21], v[176:179], v[200:203], v[18:21]
	v_mfma_f32_16x16x32_bf16 v[6:9], v[168:171], v[208:211], v[6:9]
	v_mfma_f32_16x16x32_bf16 v[2:5], v[176:179], v[208:211], v[2:5]
	s_barrier
	s_setprio 0
	s_add_i32 s16, 0, 0x18000
	s_add_i32 s17, 0, 0x1c000
	v_add_u32_e32 v160, s16, v146
	v_add_u32_e32 v176, s17, v146
	ds_read_b128 v[148:151], v160
	ds_read_b128 v[152:155], v160 offset:1024
	ds_read_b128 v[156:159], v160 offset:2048
	ds_read_b128 v[160:163], v160 offset:3072
	ds_read_b128 v[164:167], v176
	ds_read_b128 v[168:171], v176 offset:1024
	ds_read_b128 v[172:175], v176 offset:2048
	ds_read_b128 v[176:179], v176 offset:3072
	s_add_u32 s52, s52, 0x80000
	s_addc_u32 s53, s53, 0
	s_mov_b32 m0, s58
	v_lshl_add_u64 v[218:219], s[52:53], 0, v[134:135]
	ds_read_b128 v[180:183], v147 offset:32768
	ds_read_b128 v[184:187], v147 offset:33792
	ds_read_b128 v[188:191], v147 offset:34816
	ds_read_b128 v[192:195], v147 offset:35840
	ds_read_b128 v[196:199], v147 offset:36864
	ds_read_b128 v[200:203], v147 offset:37888
	ds_read_b128 v[204:207], v147 offset:38912
	ds_read_b128 v[208:211], v147 offset:39936
	global_load_lds_dwordx4 v[218:219], off
	v_lshl_add_u64 v[218:219], s[52:53], 0, v[132:133]
	s_mov_b32 m0, s59
	s_nop 0
	global_load_lds_dwordx4 v[218:219], off
	s_waitcnt vmcnt(8) lgkmcnt(0)
	s_barrier
	s_setprio 1
	v_mfma_f32_16x16x32_bf16 v[126:129], v[148:151], v[180:183], v[126:129]
	v_mfma_f32_16x16x32_bf16 v[122:125], v[156:159], v[180:183], v[122:125]
	v_mfma_f32_16x16x32_bf16 v[110:113], v[148:151], v[188:191], v[110:113]
	v_mfma_f32_16x16x32_bf16 v[106:109], v[156:159], v[188:191], v[106:109]
	v_mfma_f32_16x16x32_bf16 v[94:97], v[148:151], v[196:199], v[94:97]
	v_mfma_f32_16x16x32_bf16 v[90:93], v[156:159], v[196:199], v[90:93]
	v_mfma_f32_16x16x32_bf16 v[78:81], v[148:151], v[204:207], v[78:81]
	v_mfma_f32_16x16x32_bf16 v[74:77], v[156:159], v[204:207], v[74:77]
	v_mfma_f32_16x16x32_bf16 v[126:129], v[152:155], v[184:187], v[126:129]
	v_mfma_f32_16x16x32_bf16 v[122:125], v[160:163], v[184:187], v[122:125]
	v_mfma_f32_16x16x32_bf16 v[110:113], v[152:155], v[192:195], v[110:113]
	v_mfma_f32_16x16x32_bf16 v[106:109], v[160:163], v[192:195], v[106:109]
	v_mfma_f32_16x16x32_bf16 v[94:97], v[152:155], v[200:203], v[94:97]
	v_mfma_f32_16x16x32_bf16 v[90:93], v[160:163], v[200:203], v[90:93]
	v_mfma_f32_16x16x32_bf16 v[78:81], v[152:155], v[208:211], v[78:81]
	v_mfma_f32_16x16x32_bf16 v[74:77], v[160:163], v[208:211], v[74:77]
	s_setprio 0
	s_setprio 1
	v_mfma_f32_16x16x32_bf16 v[118:121], v[164:167], v[180:183], v[118:121]
	v_mfma_f32_16x16x32_bf16 v[114:117], v[172:175], v[180:183], v[114:117]
	v_mfma_f32_16x16x32_bf16 v[102:105], v[164:167], v[188:191], v[102:105]
	v_mfma_f32_16x16x32_bf16 v[98:101], v[172:175], v[188:191], v[98:101]
	v_mfma_f32_16x16x32_bf16 v[86:89], v[164:167], v[196:199], v[86:89]
	v_mfma_f32_16x16x32_bf16 v[82:85], v[172:175], v[196:199], v[82:85]
	v_mfma_f32_16x16x32_bf16 v[70:73], v[164:167], v[204:207], v[70:73]
	v_mfma_f32_16x16x32_bf16 v[66:69], v[172:175], v[204:207], v[66:69]
	v_mfma_f32_16x16x32_bf16 v[118:121], v[168:171], v[184:187], v[118:121]
	v_mfma_f32_16x16x32_bf16 v[114:117], v[176:179], v[184:187], v[114:117]
	v_mfma_f32_16x16x32_bf16 v[102:105], v[168:171], v[192:195], v[102:105]
	v_mfma_f32_16x16x32_bf16 v[98:101], v[176:179], v[192:195], v[98:101]
	v_mfma_f32_16x16x32_bf16 v[86:89], v[168:171], v[200:203], v[86:89]
	v_mfma_f32_16x16x32_bf16 v[82:85], v[176:179], v[200:203], v[82:85]
	v_mfma_f32_16x16x32_bf16 v[70:73], v[168:171], v[208:211], v[70:73]
	v_mfma_f32_16x16x32_bf16 v[66:69], v[176:179], v[208:211], v[66:69]
	s_barrier
; #define PG8_STAGE(bufoff, gbase, voff) do { _Pragma("unroll") for (int _i = 0; _i < 2; ++_i) \
;         __builtin_amdgcn_global_load_lds((const unsigned*)((const char*)(gbase) + (voff)[_i]), (LAS unsigned*)(lds + (bufoff) + ldsw + _i * 8192), 16, 0, 0); } while (0)
; #define PG8_LDA(dst, b, h) do { _Pragma("unroll") for (int m = 0; m < 4; ++m) _Pragma("unroll") for (int k = 0; k < 2; ++k) dst[m][k] = *(const LAS bf16x8*)(lds + PG8_SA(b, h) + aoff + m * 2048 + k * 1024); } while (0)
; #define PG8_MMA(ai, bj, At, Bt) do { __builtin_amdgcn_s_setprio(1); _Pragma("unroll") for (int m = 0; m < 4; ++m) _Pragma("unroll") for (int n = 0; n < 2; ++n) _Pragma("unroll") for (int k = 0; k < 2; ++k) \
;         acc[ai][bj][m][n] = __builtin_amdgcn_mfma_f32_16x16x32_bf16(Bt[n][k], At[m][k], acc[ai][bj][m][n], 0, 0, 0); __builtin_amdgcn_s_setprio(0); } while (0)
; #define PG8_WAIT_V(n) asm volatile("s_waitcnt vmcnt(" #n ")" ::: "memory")
; #define PG8_WAIT_L(n) asm volatile("s_waitcnt lgkmcnt(" #n ")" ::: "memory")
; #define PG8_BAR __builtin_amdgcn_s_barrier()
; #define PG8_SCHED __builtin_amdgcn_sched_barrier(0)
; template <class Epi, class Sched, bool ALIGN_EPI, bool LAST_FUSED = false, bool PERM = false, bool CARRY = false>
; __device__ __forceinline__ void gemm_phase(LAS unsigned char* lds, const int tid, const int K, const int lda, const int ldb, const Sched& S, const Epi& E) {
;     ...
;             PG8_LDA(At, 1, 1); PG8_STAGE(PG8_SB(1, 0), b3, voffB); PG8_STAGE(PG8_SB(1, 1), b3 + hstepB, voffB); PG8_STAGE(PG8_SA(1, 0), a3, voffA);
;             PG8_WAIT_V(8); PG8_WAIT_L(0); PG8_BAR; PG8_MMA(1, 0, At, B0); PG8_MMA(1, 1, At, B1); PG8_BAR; PG8_SCHED;
;         }
;         if constexpr (ALIGN_EPI) { if (wr == 0) PG8_BAR; }
	s_setprio 0
	s_add_i32 s16, s16, s45
	v_lshl_add_u64 v[140:141], v[140:141], 0, s[68:69]
	s_mov_b32 m0, s16
	ds_read_b128 v[180:183], v147 offset:49152
	ds_read_b128 v[184:187], v147 offset:50176
	ds_read_b128 v[188:191], v147 offset:51200
	ds_read_b128 v[192:195], v147 offset:52224
	ds_read_b128 v[196:199], v147 offset:53248
	ds_read_b128 v[200:203], v147 offset:54272
	ds_read_b128 v[204:207], v147 offset:55296
	ds_read_b128 v[208:211], v147 offset:56320
	global_load_lds_dwordx4 v[140:141], off
	s_add_i32 m0, s16, 0x2000
	s_add_u32 s52, s54, 0x80080
	v_lshl_add_u64 v[140:141], v[212:213], 0, s[68:69]
	s_addc_u32 s53, s55, 0
	s_add_i32 s16, s17, s45
	global_load_lds_dwordx4 v[140:141], off
	v_lshl_add_u64 v[140:141], s[52:53], 0, v[0:1]
	s_mov_b32 m0, s16
	s_nop 0
	global_load_lds_dwordx4 v[140:141], off
	v_lshl_add_u64 v[140:141], s[52:53], 0, v[130:131]
	s_add_i32 m0, s16, 0x2000
	s_nop 0
	global_load_lds_dwordx4 v[140:141], off
	v_lshl_add_u64 v[140:141], v[214:215], 0, s[68:69]
	s_mov_b32 m0, s61
	s_nop 0
	global_load_lds_dwordx4 v[140:141], off
	v_lshl_add_u64 v[140:141], v[216:217], 0, s[68:69]
	s_mov_b32 m0, s62
	s_nop 0
	global_load_lds_dwordx4 v[140:141], off
	s_waitcnt vmcnt(8) lgkmcnt(0)
	s_barrier
	s_setprio 1
	v_mfma_f32_16x16x32_bf16 v[62:65], v[148:151], v[180:183], v[62:65]
	v_mfma_f32_16x16x32_bf16 v[58:61], v[156:159], v[180:183], v[58:61]
	v_mfma_f32_16x16x32_bf16 v[46:49], v[148:151], v[188:191], v[46:49]
	v_mfma_f32_16x16x32_bf16 v[42:45], v[156:159], v[188:191], v[42:45]
	v_mfma_f32_16x16x32_bf16 v[30:33], v[148:151], v[196:199], v[30:33]
	v_mfma_f32_16x16x32_bf16 v[26:29], v[156:159], v[196:199], v[26:29]
	v_mfma_f32_16x16x32_bf16 v[14:17], v[148:151], v[204:207], v[14:17]
	v_mfma_f32_16x16x32_bf16 v[10:13], v[156:159], v[204:207], v[10:13]
	v_mfma_f32_16x16x32_bf16 v[62:65], v[152:155], v[184:187], v[62:65]
	v_mfma_f32_16x16x32_bf16 v[58:61], v[160:163], v[184:187], v[58:61]
	v_mfma_f32_16x16x32_bf16 v[46:49], v[152:155], v[192:195], v[46:49]
	v_mfma_f32_16x16x32_bf16 v[42:45], v[160:163], v[192:195], v[42:45]
	v_mfma_f32_16x16x32_bf16 v[30:33], v[152:155], v[200:203], v[30:33]
	v_mfma_f32_16x16x32_bf16 v[26:29], v[160:163], v[200:203], v[26:29]
	v_mfma_f32_16x16x32_bf16 v[14:17], v[152:155], v[208:211], v[14:17]
	v_mfma_f32_16x16x32_bf16 v[10:13], v[160:163], v[208:211], v[10:13]
	s_setprio 0
	s_setprio 1
	v_mfma_f32_16x16x32_bf16 v[54:57], v[164:167], v[180:183], v[54:57]
	v_mfma_f32_16x16x32_bf16 v[50:53], v[172:175], v[180:183], v[50:53]
	v_mfma_f32_16x16x32_bf16 v[38:41], v[164:167], v[188:191], v[38:41]
	v_mfma_f32_16x16x32_bf16 v[34:37], v[172:175], v[188:191], v[34:37]
	v_mfma_f32_16x16x32_bf16 v[22:25], v[164:167], v[196:199], v[22:25]
	v_mfma_f32_16x16x32_bf16 v[18:21], v[172:175], v[196:199], v[18:21]
	v_mfma_f32_16x16x32_bf16 v[6:9], v[164:167], v[204:207], v[6:9]
	v_mfma_f32_16x16x32_bf16 v[2:5], v[172:175], v[204:207], v[2:5]
	v_mfma_f32_16x16x32_bf16 v[54:57], v[168:171], v[184:187], v[54:57]
	v_mfma_f32_16x16x32_bf16 v[50:53], v[176:179], v[184:187], v[50:53]
	v_mfma_f32_16x16x32_bf16 v[38:41], v[168:171], v[192:195], v[38:41]
	v_mfma_f32_16x16x32_bf16 v[34:37], v[176:179], v[192:195], v[34:37]
	v_mfma_f32_16x16x32_bf16 v[22:25], v[168:171], v[200:203], v[22:25]
	v_mfma_f32_16x16x32_bf16 v[18:21], v[176:179], v[200:203], v[18:21]
	v_mfma_f32_16x16x32_bf16 v[6:9], v[168:171], v[208:211], v[6:9]
	v_mfma_f32_16x16x32_bf16 v[2:5], v[176:179], v[208:211], v[2:5]
	s_barrier
	s_setprio 0
	s_add_i32 s41, s41, 2
	s_add_u32 s48, s48, 0x100
	s_addc_u32 s49, s49, 0
	s_add_u32 s27, s27, 0x100
	s_addc_u32 s39, s39, 0
	s_cmp_gt_u32 s41, 29
	s_cbranch_scc0 .LBB0_1763
	s_and_b64 vcc, exec, s[36:37]
	s_cbranch_vccz .LBB0_1766
	s_barrier

; #define PG8_STAGE(bufoff, gbase, voff) do { _Pragma("unroll") for (int _i = 0; _i < 2; ++_i) \
;         __builtin_amdgcn_global_load_lds((const unsigned*)((const char*)(gbase) + (voff)[_i]), (LAS unsigned*)(lds + (bufoff) + ldsw + _i * 8192), 16, 0, 0); } while (0)
; #define PG8_LDA(dst, b, h) do { _Pragma("unroll") for (int m = 0; m < 4; ++m) _Pragma("unroll") for (int k = 0; k < 2; ++k) dst[m][k] = *(const LAS bf16x8*)(lds + PG8_SA(b, h) + aoff + m * 2048 + k * 1024); } while (0)
; #define PG8_LDB(dst, b, h) do { _Pragma("unroll") for (int n = 0; n < 2; ++n) _Pragma("unroll") for (int k = 0; k < 2; ++k) dst[n][k] = *(const LAS bf16x8*)(lds + PG8_SB(b, h) + boff + n * 2048 + k * 1024); } while (0)
; #define PG8_MMA(ai, bj, At, Bt) do { __builtin_amdgcn_s_setprio(1); _Pragma("unroll") for (int m = 0; m < 4; ++m) _Pragma("unroll") for (int n = 0; n < 2; ++n) _Pragma("unroll") for (int k = 0; k < 2; ++k) \
;         acc[ai][bj][m][n] = __builtin_amdgcn_mfma_f32_16x16x32_bf16(Bt[n][k], At[m][k], acc[ai][bj][m][n], 0, 0, 0); __builtin_amdgcn_s_setprio(0); } while (0)
; #define PG8_WAIT_V(n) asm volatile("s_waitcnt vmcnt(" #n ")" ::: "memory")
; #define PG8_WAIT_L(n) asm volatile("s_waitcnt lgkmcnt(" #n ")" ::: "memory")
; template <class Epi, class Sched, bool ALIGN_EPI, bool LAST_FUSED = false, bool PERM = false, bool CARRY = false>
; __device__ __forceinline__ void gemm_phase(LAS unsigned char* lds, const int tid, const int K, const int lda, const int ldb, const Sched& S, const Epi& E) {
;     ...
;         for (int t = 0; t < nt; t += 2) {
;             const bool last = (t == nt - 2);
;             const char* a1 = cA + (size_t)(t + 1) * kstep;
;             const char* a2 = last ? nA : cA + (size_t)(t + 2) * kstep; const char* b2 = last ? nB : cB + (size_t)(t + 2) * kstep;
;             const char* a3 = a2 + kstep; const char* b3 = b2 + kstep;
;             PG8_LDB(B0, 0, 0); PG8_LDB(B1, 0, 1); PG8_SCHED; PG8_LDA(At, 0, 0); PG8_STAGE(PG8_SA(1, 1), a1 + hstepA, voffA);
;             PG8_WAIT_V(8); PG8_WAIT_L(0); PG8_BAR; PG8_MMA(0, 0, At, B0); PG8_MMA(0, 1, At, B1); PG8_BAR; PG8_SCHED;
;             PG8_LDA(At, 0, 1); PG8_STAGE(PG8_SB(0, 0), b2, voffB); PG8_STAGE(PG8_SB(0, 1), b2 + hstepB, voffB); PG8_STAGE(PG8_SA(0, 0), a2, voffA);
;             PG8_WAIT_V(8); PG8_WAIT_L(0); PG8_BAR; PG8_MMA(1, 0, At, B0); PG8_MMA(1, 1, At, B1); PG8_BAR; PG8_SCHED;
.LBB0_1854:
	s_add_u32 s16, s66, vcc_lo
	s_addc_u32 s17, s67, vcc_hi
	s_add_u32 s52, s50, vcc_lo
	s_addc_u32 s53, s51, vcc_hi
	s_add_i32 s92, 0, 0x10000
	s_cmp_eq_u32 s87, s60
	s_cselect_b32 s57, s24, s17
	s_cselect_b32 s56, s91, s16
	v_add_u32_e32 v154, s92, v140
	s_cselect_b32 s53, s70, s53
	s_cselect_b32 s52, s71, s52
	s_add_i32 s93, 0, 0x14000
	ds_read_b128 v[142:145], v154
	ds_read_b128 v[146:149], v154 offset:1024
	ds_read_b128 v[150:153], v154 offset:2048
	ds_read_b128 v[158:161], v154 offset:3072
	v_add_u32_e32 v154, s93, v140
	ds_read_b128 v[162:165], v154
	ds_read_b128 v[166:169], v154 offset:1024
	ds_read_b128 v[170:173], v154 offset:2048
	ds_read_b128 v[174:177], v154 offset:3072
	v_lshl_add_u64 v[154:155], s[66:67], 0, v[138:139]
	s_add_i32 m0, s28, 0xc000
	ds_read_b128 v[178:181], v141
	ds_read_b128 v[182:185], v141 offset:1024
	ds_read_b128 v[186:189], v141 offset:2048
	ds_read_b128 v[190:193], v141 offset:3072
	ds_read_b128 v[194:197], v141 offset:4096
	ds_read_b128 v[198:201], v141 offset:5120
	ds_read_b128 v[202:205], v141 offset:6144
	ds_read_b128 v[206:209], v141 offset:7168
	global_load_lds_dwordx4 v[154:155], off
	v_lshl_add_u64 v[154:155], s[66:67], 0, v[128:129]
	s_add_i32 m0, s28, 0xe000
	s_nop 0
	global_load_lds_dwordx4 v[154:155], off
	s_waitcnt vmcnt(8) lgkmcnt(0)
	s_barrier
	s_setprio 1
	v_mfma_f32_16x16x32_bf16 v[118:121], v[142:145], v[178:181], v[118:121]
	v_mfma_f32_16x16x32_bf16 v[114:117], v[150:153], v[178:181], v[114:117]
	v_mfma_f32_16x16x32_bf16 v[110:113], v[142:145], v[186:189], v[110:113]
	v_mfma_f32_16x16x32_bf16 v[106:109], v[150:153], v[186:189], v[106:109]
	v_mfma_f32_16x16x32_bf16 v[86:89], v[142:145], v[194:197], v[86:89]
	v_mfma_f32_16x16x32_bf16 v[82:85], v[150:153], v[194:197], v[82:85]
	v_mfma_f32_16x16x32_bf16 v[78:81], v[142:145], v[202:205], v[78:81]
	v_mfma_f32_16x16x32_bf16 v[74:77], v[150:153], v[202:205], v[74:77]
	v_mfma_f32_16x16x32_bf16 v[118:121], v[146:149], v[182:185], v[118:121]
	v_mfma_f32_16x16x32_bf16 v[114:117], v[158:161], v[182:185], v[114:117]
	v_mfma_f32_16x16x32_bf16 v[110:113], v[146:149], v[190:193], v[110:113]
	v_mfma_f32_16x16x32_bf16 v[106:109], v[158:161], v[190:193], v[106:109]
	v_mfma_f32_16x16x32_bf16 v[86:89], v[146:149], v[198:201], v[86:89]
	v_mfma_f32_16x16x32_bf16 v[82:85], v[158:161], v[198:201], v[82:85]
	v_mfma_f32_16x16x32_bf16 v[78:81], v[146:149], v[206:209], v[78:81]
	v_mfma_f32_16x16x32_bf16 v[74:77], v[158:161], v[206:209], v[74:77]
	s_setprio 0
	s_setprio 1
	v_mfma_f32_16x16x32_bf16 v[98:101], v[162:165], v[178:181], v[98:101]
	v_mfma_f32_16x16x32_bf16 v[102:105], v[170:173], v[178:181], v[102:105]
	v_mfma_f32_16x16x32_bf16 v[90:93], v[162:165], v[186:189], v[90:93]
	v_mfma_f32_16x16x32_bf16 v[94:97], v[170:173], v[186:189], v[94:97]
	v_mfma_f32_16x16x32_bf16 v[66:69], v[162:165], v[194:197], v[66:69]
	v_mfma_f32_16x16x32_bf16 v[70:73], v[170:173], v[194:197], v[70:73]
	v_mfma_f32_16x16x32_bf16 v[50:53], v[162:165], v[202:205], v[50:53]
	v_mfma_f32_16x16x32_bf16 v[54:57], v[170:173], v[202:205], v[54:57]
	v_mfma_f32_16x16x32_bf16 v[98:101], v[166:169], v[182:185], v[98:101]
	v_mfma_f32_16x16x32_bf16 v[102:105], v[174:177], v[182:185], v[102:105]
	v_mfma_f32_16x16x32_bf16 v[90:93], v[166:169], v[190:193], v[90:93]
	v_mfma_f32_16x16x32_bf16 v[94:97], v[174:177], v[190:193], v[94:97]
	v_mfma_f32_16x16x32_bf16 v[66:69], v[166:169], v[198:201], v[66:69]
	v_mfma_f32_16x16x32_bf16 v[70:73], v[174:177], v[198:201], v[70:73]
	v_mfma_f32_16x16x32_bf16 v[50:53], v[166:169], v[206:209], v[50:53]
	v_mfma_f32_16x16x32_bf16 v[54:57], v[174:177], v[206:209], v[54:57]
	s_barrier
	s_setprio 0
	s_add_i32 s16, s92, s95
	v_lshl_add_u64 v[154:155], s[52:53], 0, v[0:1]
	s_mov_b32 m0, s16
	ds_read_b128 v[178:181], v141 offset:16384
	ds_read_b128 v[182:185], v141 offset:17408
	ds_read_b128 v[186:189], v141 offset:18432
	ds_read_b128 v[190:193], v141 offset:19456
	ds_read_b128 v[194:197], v141 offset:20480
	ds_read_b128 v[198:201], v141 offset:21504
	ds_read_b128 v[202:205], v141 offset:22528
	ds_read_b128 v[206:209], v141 offset:23552
	global_load_lds_dwordx4 v[154:155], off
	s_add_i32 m0, s16, 0x2000
	s_add_u32 s16, s52, 0x200000
	v_lshl_add_u64 v[210:211], s[52:53], 0, v[122:123]
	s_addc_u32 s17, s53, 0
	s_add_i32 s92, s93, s95
	global_load_lds_dwordx4 v[210:211], off
	v_lshl_add_u64 v[212:213], s[16:17], 0, v[0:1]
	s_mov_b32 m0, s92
	v_lshl_add_u64 v[214:215], s[56:57], 0, v[122:123]
	global_load_lds_dwordx4 v[212:213], off
	v_lshl_add_u64 v[212:213], s[16:17], 0, v[122:123]
	s_add_i32 m0, s92, 0x2000
	s_nop 0
	global_load_lds_dwordx4 v[212:213], off
	v_lshl_add_u64 v[212:213], s[56:57], 0, v[0:1]
	s_mov_b32 m0, s28
	s_nop 0
	global_load_lds_dwordx4 v[212:213], off
	s_mov_b32 m0, s29
	s_nop 0
	global_load_lds_dwordx4 v[214:215], off
	s_waitcnt vmcnt(8) lgkmcnt(0)
	s_barrier
; #define PG8_STAGE(bufoff, gbase, voff) do { _Pragma("unroll") for (int _i = 0; _i < 2; ++_i) \
;         __builtin_amdgcn_global_load_lds((const unsigned*)((const char*)(gbase) + (voff)[_i]), (LAS unsigned*)(lds + (bufoff) + ldsw + _i * 8192), 16, 0, 0); } while (0)
; #define PG8_LDA(dst, b, h) do { _Pragma("unroll") for (int m = 0; m < 4; ++m) _Pragma("unroll") for (int k = 0; k < 2; ++k) dst[m][k] = *(const LAS bf16x8*)(lds + PG8_SA(b, h) + aoff + m * 2048 + k * 1024); } while (0)
; #define PG8_LDB(dst, b, h) do { _Pragma("unroll") for (int n = 0; n < 2; ++n) _Pragma("unroll") for (int k = 0; k < 2; ++k) dst[n][k] = *(const LAS bf16x8*)(lds + PG8_SB(b, h) + boff + n * 2048 + k * 1024); } while (0)
; #define PG8_MMA(ai, bj, At, Bt) do { __builtin_amdgcn_s_setprio(1); _Pragma("unroll") for (int m = 0; m < 4; ++m) _Pragma("unroll") for (int n = 0; n < 2; ++n) _Pragma("unroll") for (int k = 0; k < 2; ++k) \
;         acc[ai][bj][m][n] = __builtin_amdgcn_mfma_f32_16x16x32_bf16(Bt[n][k], At[m][k], acc[ai][bj][m][n], 0, 0, 0); __builtin_amdgcn_s_setprio(0); } while (0)
; #define PG8_WAIT_V(n) asm volatile("s_waitcnt vmcnt(" #n ")" ::: "memory")
; #define PG8_WAIT_L(n) asm volatile("s_waitcnt lgkmcnt(" #n ")" ::: "memory")
; #define PG8_BAR __builtin_amdgcn_s_barrier()
; #define PG8_SCHED __builtin_amdgcn_sched_barrier(0)
; template <class Epi, class Sched, bool ALIGN_EPI, bool LAST_FUSED = false, bool PERM = false, bool CARRY = false>
; __device__ __forceinline__ void gemm_phase(LAS unsigned char* lds, const int tid, const int K, const int lda, const int ldb, const Sched& S, const Epi& E) {
;     ...
;             PG8_WAIT_V(8); PG8_WAIT_L(0); PG8_BAR; PG8_MMA(1, 0, At, B0); PG8_MMA(1, 1, At, B1); PG8_BAR; PG8_SCHED;
;             PG8_LDB(B0, 1, 0); PG8_LDB(B1, 1, 1); PG8_SCHED; PG8_LDA(At, 1, 0); PG8_STAGE(PG8_SA(0, 1), a2 + hstepA, voffA);
;             PG8_WAIT_V(8); PG8_WAIT_L(0); PG8_BAR; PG8_MMA(0, 0, At, B0); PG8_MMA(0, 1, At, B1); PG8_BAR; PG8_SCHED;
	s_setprio 1
	v_mfma_f32_16x16x32_bf16 v[62:65], v[142:145], v[178:181], v[62:65]
	v_mfma_f32_16x16x32_bf16 v[58:61], v[150:153], v[178:181], v[58:61]
	v_mfma_f32_16x16x32_bf16 v[38:41], v[142:145], v[186:189], v[38:41]
	v_mfma_f32_16x16x32_bf16 v[34:37], v[150:153], v[186:189], v[34:37]
	v_mfma_f32_16x16x32_bf16 v[22:25], v[142:145], v[194:197], v[22:25]
	v_mfma_f32_16x16x32_bf16 v[18:21], v[150:153], v[194:197], v[18:21]
	v_mfma_f32_16x16x32_bf16 v[134:137], v[142:145], v[202:205], v[134:137]
	v_mfma_f32_16x16x32_bf16 v[130:133], v[150:153], v[202:205], v[130:133]
	v_mfma_f32_16x16x32_bf16 v[62:65], v[146:149], v[182:185], v[62:65]
	v_mfma_f32_16x16x32_bf16 v[58:61], v[158:161], v[182:185], v[58:61]
	v_mfma_f32_16x16x32_bf16 v[38:41], v[146:149], v[190:193], v[38:41]
	v_mfma_f32_16x16x32_bf16 v[34:37], v[158:161], v[190:193], v[34:37]
	v_mfma_f32_16x16x32_bf16 v[22:25], v[146:149], v[198:201], v[22:25]
	v_mfma_f32_16x16x32_bf16 v[18:21], v[158:161], v[198:201], v[18:21]
	v_mfma_f32_16x16x32_bf16 v[134:137], v[146:149], v[206:209], v[134:137]
	v_mfma_f32_16x16x32_bf16 v[130:133], v[158:161], v[206:209], v[130:133]
	s_setprio 0
	s_setprio 1
	v_mfma_f32_16x16x32_bf16 v[42:45], v[162:165], v[178:181], v[42:45]
	v_mfma_f32_16x16x32_bf16 v[46:49], v[170:173], v[178:181], v[46:49]
	v_mfma_f32_16x16x32_bf16 v[26:29], v[162:165], v[186:189], v[26:29]
	v_mfma_f32_16x16x32_bf16 v[30:33], v[170:173], v[186:189], v[30:33]
	v_mfma_f32_16x16x32_bf16 v[14:17], v[162:165], v[194:197], v[14:17]
	v_mfma_f32_16x16x32_bf16 v[10:13], v[170:173], v[194:197], v[10:13]
	v_mfma_f32_16x16x32_bf16 v[6:9], v[162:165], v[202:205], v[6:9]
	v_mfma_f32_16x16x32_bf16 v[2:5], v[170:173], v[202:205], v[2:5]
	v_mfma_f32_16x16x32_bf16 v[42:45], v[166:169], v[182:185], v[42:45]
	v_mfma_f32_16x16x32_bf16 v[46:49], v[174:177], v[182:185], v[46:49]
	v_mfma_f32_16x16x32_bf16 v[26:29], v[166:169], v[190:193], v[26:29]
	v_mfma_f32_16x16x32_bf16 v[30:33], v[174:177], v[190:193], v[30:33]
	v_mfma_f32_16x16x32_bf16 v[14:17], v[166:169], v[198:201], v[14:17]
	v_mfma_f32_16x16x32_bf16 v[10:13], v[174:177], v[198:201], v[10:13]
	v_mfma_f32_16x16x32_bf16 v[6:9], v[166:169], v[206:209], v[6:9]
	v_mfma_f32_16x16x32_bf16 v[2:5], v[174:177], v[206:209], v[2:5]
	s_barrier
	s_setprio 0
	s_add_i32 s92, 0, 0x18000
	s_add_i32 s93, 0, 0x1c000
	v_add_u32_e32 v158, s92, v140
	v_add_u32_e32 v174, s93, v140
	ds_read_b128 v[142:145], v158
	ds_read_b128 v[146:149], v158 offset:1024
	ds_read_b128 v[150:153], v158 offset:2048
	ds_read_b128 v[158:161], v158 offset:3072
	ds_read_b128 v[162:165], v174
	ds_read_b128 v[166:169], v174 offset:1024
	ds_read_b128 v[170:173], v174 offset:2048
	ds_read_b128 v[174:177], v174 offset:3072
	s_add_u32 s16, s56, 0x200000
	s_addc_u32 s17, s57, 0
	s_mov_b32 m0, s14
	v_lshl_add_u64 v[216:217], s[16:17], 0, v[0:1]
	ds_read_b128 v[178:181], v141 offset:32768
	ds_read_b128 v[182:185], v141 offset:33792
	ds_read_b128 v[186:189], v141 offset:34816
	ds_read_b128 v[190:193], v141 offset:35840
	ds_read_b128 v[194:197], v141 offset:36864
	ds_read_b128 v[198:201], v141 offset:37888
	ds_read_b128 v[202:205], v141 offset:38912
	ds_read_b128 v[206:209], v141 offset:39936
	global_load_lds_dwordx4 v[216:217], off
	v_lshl_add_u64 v[216:217], s[16:17], 0, v[122:123]
	s_mov_b32 m0, s22
	s_nop 0
	global_load_lds_dwordx4 v[216:217], off
	s_waitcnt vmcnt(8) lgkmcnt(0)
	s_barrier
	s_setprio 1
	v_mfma_f32_16x16x32_bf16 v[118:121], v[142:145], v[178:181], v[118:121]
	v_mfma_f32_16x16x32_bf16 v[114:117], v[150:153], v[178:181], v[114:117]
	v_mfma_f32_16x16x32_bf16 v[110:113], v[142:145], v[186:189], v[110:113]
	v_mfma_f32_16x16x32_bf16 v[106:109], v[150:153], v[186:189], v[106:109]
	v_mfma_f32_16x16x32_bf16 v[86:89], v[142:145], v[194:197], v[86:89]
	v_mfma_f32_16x16x32_bf16 v[82:85], v[150:153], v[194:197], v[82:85]
	v_mfma_f32_16x16x32_bf16 v[78:81], v[142:145], v[202:205], v[78:81]
	v_mfma_f32_16x16x32_bf16 v[74:77], v[150:153], v[202:205], v[74:77]
	v_mfma_f32_16x16x32_bf16 v[118:121], v[146:149], v[182:185], v[118:121]
	v_mfma_f32_16x16x32_bf16 v[114:117], v[158:161], v[182:185], v[114:117]
	v_mfma_f32_16x16x32_bf16 v[110:113], v[146:149], v[190:193], v[110:113]
	v_mfma_f32_16x16x32_bf16 v[106:109], v[158:161], v[190:193], v[106:109]
	v_mfma_f32_16x16x32_bf16 v[86:89], v[146:149], v[198:201], v[86:89]
	v_mfma_f32_16x16x32_bf16 v[82:85], v[158:161], v[198:201], v[82:85]
	v_mfma_f32_16x16x32_bf16 v[78:81], v[146:149], v[206:209], v[78:81]
	v_mfma_f32_16x16x32_bf16 v[74:77], v[158:161], v[206:209], v[74:77]
	s_setprio 0
	s_setprio 1
	v_mfma_f32_16x16x32_bf16 v[98:101], v[162:165], v[178:181], v[98:101]
	v_mfma_f32_16x16x32_bf16 v[102:105], v[170:173], v[178:181], v[102:105]
	v_mfma_f32_16x16x32_bf16 v[90:93], v[162:165], v[186:189], v[90:93]
	v_mfma_f32_16x16x32_bf16 v[94:97], v[170:173], v[186:189], v[94:97]
	v_mfma_f32_16x16x32_bf16 v[66:69], v[162:165], v[194:197], v[66:69]
	v_mfma_f32_16x16x32_bf16 v[70:73], v[170:173], v[194:197], v[70:73]
	v_mfma_f32_16x16x32_bf16 v[50:53], v[162:165], v[202:205], v[50:53]
	v_mfma_f32_16x16x32_bf16 v[54:57], v[170:173], v[202:205], v[54:57]
	v_mfma_f32_16x16x32_bf16 v[98:101], v[166:169], v[182:185], v[98:101]
	v_mfma_f32_16x16x32_bf16 v[102:105], v[174:177], v[182:185], v[102:105]
	v_mfma_f32_16x16x32_bf16 v[90:93], v[166:169], v[190:193], v[90:93]
	v_mfma_f32_16x16x32_bf16 v[94:97], v[174:177], v[190:193], v[94:97]
	v_mfma_f32_16x16x32_bf16 v[66:69], v[166:169], v[198:201], v[66:69]
	v_mfma_f32_16x16x32_bf16 v[70:73], v[174:177], v[198:201], v[70:73]
	v_mfma_f32_16x16x32_bf16 v[50:53], v[166:169], v[206:209], v[50:53]
	v_mfma_f32_16x16x32_bf16 v[54:57], v[174:177], v[206:209], v[54:57]
	s_barrier
; #define PG8_STAGE(bufoff, gbase, voff) do { _Pragma("unroll") for (int _i = 0; _i < 2; ++_i) \
;         __builtin_amdgcn_global_load_lds((const unsigned*)((const char*)(gbase) + (voff)[_i]), (LAS unsigned*)(lds + (bufoff) + ldsw + _i * 8192), 16, 0, 0); } while (0)
; #define PG8_LDA(dst, b, h) do { _Pragma("unroll") for (int m = 0; m < 4; ++m) _Pragma("unroll") for (int k = 0; k < 2; ++k) dst[m][k] = *(const LAS bf16x8*)(lds + PG8_SA(b, h) + aoff + m * 2048 + k * 1024); } while (0)
; #define PG8_MMA(ai, bj, At, Bt) do { __builtin_amdgcn_s_setprio(1); _Pragma("unroll") for (int m = 0; m < 4; ++m) _Pragma("unroll") for (int n = 0; n < 2; ++n) _Pragma("unroll") for (int k = 0; k < 2; ++k) \
;         acc[ai][bj][m][n] = __builtin_amdgcn_mfma_f32_16x16x32_bf16(Bt[n][k], At[m][k], acc[ai][bj][m][n], 0, 0, 0); __builtin_amdgcn_s_setprio(0); } while (0)
; #define PG8_WAIT_V(n) asm volatile("s_waitcnt vmcnt(" #n ")" ::: "memory")
; #define PG8_WAIT_L(n) asm volatile("s_waitcnt lgkmcnt(" #n ")" ::: "memory")
; #define PG8_BAR __builtin_amdgcn_s_barrier()
; #define PG8_SCHED __builtin_amdgcn_sched_barrier(0)
; template <class Epi, class Sched, bool ALIGN_EPI, bool LAST_FUSED = false, bool PERM = false, bool CARRY = false>
; __device__ __forceinline__ void gemm_phase(LAS unsigned char* lds, const int tid, const int K, const int lda, const int ldb, const Sched& S, const Epi& E) {
;     ...
;         for (int t = 0; t < nt; t += 2) {
;     ...
;             PG8_LDA(At, 1, 1); PG8_STAGE(PG8_SB(1, 0), b3, voffB); PG8_STAGE(PG8_SB(1, 1), b3 + hstepB, voffB); PG8_STAGE(PG8_SA(1, 0), a3, voffA);
;             PG8_WAIT_V(8); PG8_WAIT_L(0); PG8_BAR; PG8_MMA(1, 0, At, B0); PG8_MMA(1, 1, At, B1); PG8_BAR; PG8_SCHED;
;         }
	s_setprio 0
	s_add_i32 s16, s92, s95
	v_lshl_add_u64 v[154:155], v[154:155], 0, s[68:69]
	s_mov_b32 m0, s16
	ds_read_b128 v[178:181], v141 offset:49152
	ds_read_b128 v[182:185], v141 offset:50176
	ds_read_b128 v[186:189], v141 offset:51200
	ds_read_b128 v[190:193], v141 offset:52224
	ds_read_b128 v[194:197], v141 offset:53248
	ds_read_b128 v[198:201], v141 offset:54272
	ds_read_b128 v[202:205], v141 offset:55296
	ds_read_b128 v[206:209], v141 offset:56320
	global_load_lds_dwordx4 v[154:155], off
	s_add_i32 m0, s16, 0x2000
	s_add_u32 s16, s52, 0x200080
	v_lshl_add_u64 v[154:155], v[210:211], 0, s[68:69]
	s_addc_u32 s17, s53, 0
	s_add_i32 s52, s93, s95
	global_load_lds_dwordx4 v[154:155], off
	v_lshl_add_u64 v[154:155], s[16:17], 0, v[0:1]
	s_mov_b32 m0, s52
	s_nop 0
	global_load_lds_dwordx4 v[154:155], off
	v_lshl_add_u64 v[154:155], s[16:17], 0, v[122:123]
	s_add_i32 m0, s52, 0x2000
	s_nop 0
	global_load_lds_dwordx4 v[154:155], off
	v_lshl_add_u64 v[154:155], v[212:213], 0, s[68:69]
	s_mov_b32 m0, s96
	s_nop 0
	global_load_lds_dwordx4 v[154:155], off
	v_lshl_add_u64 v[154:155], v[214:215], 0, s[68:69]
	s_mov_b32 m0, s97
	s_nop 0
	global_load_lds_dwordx4 v[154:155], off
	s_waitcnt vmcnt(8) lgkmcnt(0)
	s_barrier
	s_setprio 1
	v_mfma_f32_16x16x32_bf16 v[62:65], v[142:145], v[178:181], v[62:65]
	v_mfma_f32_16x16x32_bf16 v[58:61], v[150:153], v[178:181], v[58:61]
	v_mfma_f32_16x16x32_bf16 v[38:41], v[142:145], v[186:189], v[38:41]
	v_mfma_f32_16x16x32_bf16 v[34:37], v[150:153], v[186:189], v[34:37]
	v_mfma_f32_16x16x32_bf16 v[22:25], v[142:145], v[194:197], v[22:25]
	v_mfma_f32_16x16x32_bf16 v[18:21], v[150:153], v[194:197], v[18:21]
	v_mfma_f32_16x16x32_bf16 v[134:137], v[142:145], v[202:205], v[134:137]
	v_mfma_f32_16x16x32_bf16 v[130:133], v[150:153], v[202:205], v[130:133]
	v_mfma_f32_16x16x32_bf16 v[62:65], v[146:149], v[182:185], v[62:65]
	v_mfma_f32_16x16x32_bf16 v[58:61], v[158:161], v[182:185], v[58:61]
	v_mfma_f32_16x16x32_bf16 v[38:41], v[146:149], v[190:193], v[38:41]
	v_mfma_f32_16x16x32_bf16 v[34:37], v[158:161], v[190:193], v[34:37]
	v_mfma_f32_16x16x32_bf16 v[22:25], v[146:149], v[198:201], v[22:25]
	v_mfma_f32_16x16x32_bf16 v[18:21], v[158:161], v[198:201], v[18:21]
	v_mfma_f32_16x16x32_bf16 v[134:137], v[146:149], v[206:209], v[134:137]
	v_mfma_f32_16x16x32_bf16 v[130:133], v[158:161], v[206:209], v[130:133]
	s_setprio 0
	s_setprio 1
	v_mfma_f32_16x16x32_bf16 v[42:45], v[162:165], v[178:181], v[42:45]
	v_mfma_f32_16x16x32_bf16 v[46:49], v[170:173], v[178:181], v[46:49]
	v_mfma_f32_16x16x32_bf16 v[26:29], v[162:165], v[186:189], v[26:29]
	v_mfma_f32_16x16x32_bf16 v[30:33], v[170:173], v[186:189], v[30:33]
	v_mfma_f32_16x16x32_bf16 v[14:17], v[162:165], v[194:197], v[14:17]
	v_mfma_f32_16x16x32_bf16 v[10:13], v[170:173], v[194:197], v[10:13]
	v_mfma_f32_16x16x32_bf16 v[6:9], v[162:165], v[202:205], v[6:9]
	v_mfma_f32_16x16x32_bf16 v[2:5], v[170:173], v[202:205], v[2:5]
	v_mfma_f32_16x16x32_bf16 v[42:45], v[166:169], v[182:185], v[42:45]
	v_mfma_f32_16x16x32_bf16 v[46:49], v[174:177], v[182:185], v[46:49]
	v_mfma_f32_16x16x32_bf16 v[26:29], v[166:169], v[190:193], v[26:29]
	v_mfma_f32_16x16x32_bf16 v[30:33], v[174:177], v[190:193], v[30:33]
	v_mfma_f32_16x16x32_bf16 v[14:17], v[166:169], v[198:201], v[14:17]
	v_mfma_f32_16x16x32_bf16 v[10:13], v[174:177], v[198:201], v[10:13]
	v_mfma_f32_16x16x32_bf16 v[6:9], v[166:169], v[206:209], v[6:9]
	v_mfma_f32_16x16x32_bf16 v[2:5], v[174:177], v[206:209], v[2:5]
	s_barrier
	s_setprio 0
	s_add_i32 s16, s60, 2
	s_add_u32 vcc_lo, vcc_lo, 0x100
	s_addc_u32 vcc_hi, vcc_hi, 0
	v_lshl_add_u64 v[138:139], v[138:139], 0, s[72:73]
	v_lshl_add_u64 v[128:129], v[128:129], 0, s[72:73]
	s_cmp_ge_i32 s60, s87
	s_mov_b32 s60, s16
	s_cbranch_scc0 .LBB0_1854
	s_and_b64 vcc, exec, s[40:41]
	s_cbranch_vccz .LBB0_1857
	s_barrier
